# att1 list padding C=1, stagger sleep 8, barrier poll sleep 2, xor-1/2/4/8 butterfly steps as DPP adds (whole kernel), sgemm loads de-serialised
# speedup vs baseline: 1.0338x; 1.0143x over previous
.LBB0_92:
	s_waitcnt lgkmcnt(0)
	global_load_dwordx4 v[10:13], v7, s[2:3]
	global_load_dwordx4 v[14:17], v7, s[34:35]
	global_load_dwordx4 v[18:21], v7, s[2:3] offset:1024
	global_load_dwordx4 v[22:25], v7, s[34:35] offset:1024
	global_load_dwordx4 v[26:29], v7, s[2:3] offset:2048
	global_load_dwordx4 v[30:33], v7, s[34:35] offset:2048
	global_load_dwordx4 v[34:37], v7, s[2:3] offset:3072
	global_load_dwordx4 v[38:41], v7, s[34:35] offset:3072
	s_waitcnt vmcnt(7)
	v_cvt_pk_bf16_f32 v42, v10, v11
	v_mul_f32_e32 v9, v11, v11
	v_mul_f32_e32 v44, v13, v13
	s_waitcnt vmcnt(6)
	v_mul_f32_e32 v45, v15, v15
	v_mul_f32_e32 v46, v17, v17
	s_waitcnt vmcnt(5)
	v_mul_f32_e32 v47, v19, v19
	v_mul_f32_e32 v48, v21, v21
	s_waitcnt vmcnt(4)
	v_mul_f32_e32 v49, v23, v23
	v_mul_f32_e32 v50, v25, v25
	s_waitcnt vmcnt(3)
	v_mul_f32_e32 v51, v27, v27
	v_mul_f32_e32 v52, v29, v29
	s_waitcnt vmcnt(2)
	v_mul_f32_e32 v53, v31, v31
	v_mul_f32_e32 v54, v33, v33
	v_fmac_f32_e32 v9, v10, v10
	v_fmac_f32_e32 v44, v12, v12
	v_fmac_f32_e32 v45, v14, v14
	v_fmac_f32_e32 v46, v16, v16
	v_fmac_f32_e32 v47, v18, v18
	v_fmac_f32_e32 v48, v20, v20
	v_fmac_f32_e32 v49, v22, v22
	v_fmac_f32_e32 v50, v24, v24
	s_waitcnt vmcnt(1)
	v_mul_f32_e32 v55, v35, v35
	v_mul_f32_e32 v56, v37, v37
	s_waitcnt vmcnt(0)
	v_mul_f32_e32 v57, v39, v39
	v_mul_f32_e32 v58, v41, v41
	v_cvt_pk_bf16_f32 v43, v12, v13
	v_fmac_f32_e32 v51, v26, v26
	v_fmac_f32_e32 v52, v28, v28
	v_fmac_f32_e32 v53, v30, v30
	v_fmac_f32_e32 v54, v32, v32
	v_add_f32_e32 v9, v9, v44
	v_add_f32_e32 v11, v45, v46
	v_add_f32_e32 v12, v47, v48
	v_add_f32_e32 v13, v49, v50
	v_fmac_f32_e32 v55, v34, v34
	v_fmac_f32_e32 v56, v36, v36
	v_fmac_f32_e32 v57, v38, v38
	v_fmac_f32_e32 v58, v40, v40
	global_store_dwordx2 v8, v[42:43], s[28:29]
	v_cvt_pk_bf16_f32 v10, v14, v15
	v_add_f32_e32 v14, v51, v52
	v_add_f32_e32 v15, v53, v54
	v_add_f32_e32 v9, v9, v12
	v_add_f32_e32 v11, v11, v13
	v_add_f32_e32 v42, v55, v56
	v_add_f32_e32 v43, v57, v58
	v_add_f32_e32 v9, v9, v14
	v_add_f32_e32 v11, v11, v15
	v_add_f32_e32 v9, v9, v42
	v_add_f32_e32 v12, v11, v43
	v_cvt_pk_bf16_f32 v11, v16, v17
	global_store_dwordx2 v8, v[10:11], s[30:31]
	v_cvt_pk_bf16_f32 v10, v18, v19
	s_waitcnt lgkmcnt(1)
	s_nop 1
	v_add_f32_dpp v9, v9, v9 quad_perm:[1,0,3,2] row_mask:0xf bank_mask:0xf
	s_waitcnt lgkmcnt(0)
	s_nop 1
	v_add_f32_dpp v12, v12, v12 quad_perm:[1,0,3,2] row_mask:0xf bank_mask:0xf
	v_cvt_pk_bf16_f32 v11, v20, v21
	global_store_dwordx2 v8, v[10:11], s[28:29] offset:512
	v_cvt_pk_bf16_f32 v10, v22, v23
	s_waitcnt lgkmcnt(1)
	s_nop 1
	v_add_f32_dpp v9, v9, v9 quad_perm:[2,3,0,1] row_mask:0xf bank_mask:0xf
	s_waitcnt lgkmcnt(0)
	s_nop 1
	v_add_f32_dpp v12, v12, v12 quad_perm:[2,3,0,1] row_mask:0xf bank_mask:0xf
	v_cvt_pk_bf16_f32 v11, v24, v25
	global_store_dwordx2 v8, v[10:11], s[30:31] offset:512
	v_cvt_pk_bf16_f32 v10, v26, v27
	s_waitcnt lgkmcnt(1)
	s_nop 1
	v_add_f32_dpp v9, v9, v9 row_half_mirror row_mask:0xf bank_mask:0xf
	s_waitcnt lgkmcnt(0)
	s_nop 1
	v_add_f32_dpp v12, v12, v12 row_half_mirror row_mask:0xf bank_mask:0xf
	v_cvt_pk_bf16_f32 v11, v28, v29
	global_store_dwordx2 v8, v[10:11], s[28:29] offset:1024
	v_cvt_pk_bf16_f32 v10, v30, v31
	s_waitcnt lgkmcnt(1)
	s_nop 1
	v_add_f32_dpp v9, v9, v9 row_mirror row_mask:0xf bank_mask:0xf
	s_waitcnt lgkmcnt(0)
	s_nop 1
	v_add_f32_dpp v12, v12, v12 row_mirror row_mask:0xf bank_mask:0xf
	ds_bpermute_b32 v13, v5, v9
	ds_bpermute_b32 v15, v5, v12
	v_cvt_pk_bf16_f32 v11, v32, v33
	global_store_dwordx2 v8, v[10:11], s[30:31] offset:1024
	v_cvt_pk_bf16_f32 v14, v34, v35
	s_waitcnt lgkmcnt(1)
	v_add_f32_e32 v9, v9, v13
	s_waitcnt lgkmcnt(0)
	v_add_f32_e32 v11, v12, v15
	ds_bpermute_b32 v10, v6, v9
	ds_bpermute_b32 v12, v6, v11
	v_cvt_pk_bf16_f32 v15, v36, v37
	global_store_dwordx2 v8, v[14:15], s[28:29] offset:1536
	v_cvt_pk_bf16_f32 v14, v38, v39
	v_cvt_pk_bf16_f32 v15, v40, v41
	global_store_dwordx2 v8, v[14:15], s[30:31] offset:1536
	s_and_saveexec_b64 s[2:3], s[0:1]
	s_cbranch_execz .LBB0_83
	s_waitcnt lgkmcnt(1)
	v_add_f32_e32 v9, v9, v10
	s_waitcnt lgkmcnt(0)
	v_add_f32_e32 v11, v11, v12
	v_mul_f32_e32 v9, 0x4b800000, v9
	v_mul_f32_e32 v10, 0x4b800000, v11
	v_trunc_f32_e32 v9, v9
	v_trunc_f32_e32 v10, v10
	v_mul_f32_e32 v12, 0x2f800000, v9
	v_mul_f32_e32 v11, 0x2f800000, v10
	v_floor_f32_e32 v13, v12
	v_floor_f32_e32 v11, v11
	v_fmac_f32_e32 v9, 0xcf800000, v13
	v_fmac_f32_e32 v10, 0xcf800000, v11
	v_cvt_u32_f32_e32 v12, v9
	v_cvt_u32_f32_e32 v13, v13
	v_cvt_u32_f32_e32 v10, v10
	v_cvt_u32_f32_e32 v11, v11
	global_store_dwordx2 v0, v[12:13], s[26:27]
	global_store_dwordx2 v0, v[10:11], s[6:7]
	s_branch .LBB0_83

.LBB0_111:
	s_lshl_b32 s2, s10, 8
	s_add_u32 s6, s4, s2
	s_addc_u32 s7, s5, 0
	v_mov_b32_e32 v0, 0x1000
	v_mov_b32_e32 v3, 1
	global_atomic_add v3, v0, v3, s[6:7] offset:1024 sc0
	v_cvt_f32_u32_e32 v0, v2
	v_sub_u32_e32 v4, 0, v2
	v_rcp_iflag_f32_e32 v0, v0
	s_nop 0
	v_mul_f32_e32 v0, 0x4f7ffffe, v0
	v_cvt_u32_f32_e32 v0, v0
	v_mul_lo_u32 v4, v4, v0
	v_mul_hi_u32 v4, v0, v4
	v_add_u32_e32 v0, v0, v4
	s_waitcnt vmcnt(0)
	v_mul_hi_u32 v0, v3, v0
	v_mul_lo_u32 v4, v0, v2
	v_sub_u32_e32 v4, v3, v4
	v_add_u32_e32 v5, 1, v0
	v_cmp_ge_u32_e32 vcc, v4, v2
	v_add_u32_e32 v3, 1, v3
	s_nop 0
	v_cndmask_b32_e32 v0, v0, v5, vcc
	v_sub_u32_e32 v5, v4, v2
	v_cndmask_b32_e32 v4, v4, v5, vcc
	v_add_u32_e32 v5, 1, v0
	v_cmp_ge_u32_e32 vcc, v4, v2
	s_nop 1
	v_cndmask_b32_e32 v0, v0, v5, vcc
	v_mul_lo_u32 v4, v2, v0
	v_add_u32_e32 v2, v4, v2
	v_cmp_ne_u32_e32 vcc, v3, v2
	s_and_saveexec_b64 s[2:3], vcc
	s_xor_b64 s[8:9], exec, s[2:3]
	s_cbranch_execz .LBB0_131
	v_mov_b32_e32 v3, 0x2000
	global_load_dword v4, v3, s[6:7] offset:1024 sc1
	s_sleep 2
	s_waitcnt lgkmcnt(0)
	global_load_dword v1, v3, s[6:7] offset:1024 sc1
	s_sleep 2
	global_load_dword v2, v3, s[6:7] offset:1024 sc1
	s_sleep 2
	global_load_dword v3, v3, s[6:7] offset:1024 sc1
	s_add_u32 s28, s6, 0x2400
	s_addc_u32 s29, s7, 0
	s_waitcnt vmcnt(3)
	v_cmp_eq_u32_e32 vcc, v4, v0
	s_and_saveexec_b64 s[24:25], vcc
	s_cbranch_execz .LBB0_130
	s_add_u32 s26, s72, 0x4200
	s_addc_u32 s27, s73, 0
	s_mov_b32 s11, 1
	s_mov_b64 s[2:3], 0
	v_mov_b32_e32 v4, 0
	s_branch .LBB0_118

.LBB0_118:
	global_load_dword v5, v4, s[28:29] sc1
	s_waitcnt vmcnt(1)
	v_cmp_eq_u32_e32 vcc, v1, v0
	s_or_b64 s[36:37], s[36:37], exec
	s_or_b64 s[34:35], s[34:35], exec
	s_sleep 2
	s_and_saveexec_b64 s[38:39], vcc
	s_cbranch_execz .LBB0_117
	global_load_dword v1, v4, s[28:29] sc1
	s_waitcnt vmcnt(3)
	v_cmp_eq_u32_e32 vcc, v2, v0
	s_mov_b64 s[42:43], -1
	s_mov_b64 s[44:45], -1
	s_sleep 2
	s_and_saveexec_b64 s[40:41], vcc
	s_cbranch_execz .LBB0_116
	global_load_dword v2, v4, s[28:29] sc1
	s_waitcnt vmcnt(3)
	v_cmp_eq_u32_e32 vcc, v3, v0
	s_mov_b64 s[46:47], -1
	s_mov_b64 s[48:49], -1
	s_sleep 2
	s_and_saveexec_b64 s[42:43], vcc
	s_cbranch_execz .LBB0_115
	global_load_dword v3, v4, s[28:29] sc1
	s_and_b32 s12, s11, 63
	s_cmp_eq_u32 s12, 0
	s_sleep 2
	s_cbranch_scc0 .LBB0_124
	global_load_dword v6, v4, s[26:27] sc1
	s_waitcnt vmcnt(0)
	v_cmp_eq_u32_e32 vcc, 0, v6
	s_cbranch_vccnz .LBB0_126
	s_mov_b64 s[48:49], 0

.LBB0_126:
	s_cmp_lt_u32 s11, 0x40001
	s_mov_b64 s[46:47], 0
	s_cselect_b64 s[48:49], -1, 0
	s_and_b64 vcc, exec, s[48:49]
	s_cbranch_vccnz .LBB0_125
	s_branch .LBB0_114

.LBB0_134:
	s_or_b64 exec, exec, s[8:9]
	v_cvt_f32_u32_e32 v3, v1
	s_waitcnt vmcnt(0)
	v_readfirstlane_b32 s2, v2
	s_add_u32 s24, s72, 0x7500
	s_addc_u32 s25, s73, 0
	v_rcp_iflag_f32_e32 v3, v3
	v_add_u32_e32 v0, s2, v0
	v_add_u32_e32 v4, 1, v0
	s_mov_b64 s[2:3], -1
	v_mul_f32_e32 v2, 0x4f7ffffe, v3
	v_cvt_u32_f32_e32 v2, v2
	v_sub_u32_e32 v3, 0, v1
	v_mul_lo_u32 v3, v3, v2
	v_mul_hi_u32 v3, v2, v3
	v_add_u32_e32 v2, v2, v3
	v_mul_hi_u32 v2, v0, v2
	v_mul_lo_u32 v3, v2, v1
	v_sub_u32_e32 v0, v0, v3
	v_add_u32_e32 v5, 1, v2
	v_cmp_ge_u32_e32 vcc, v0, v1
	v_sub_u32_e32 v3, v0, v1
	s_nop 0
	v_cndmask_b32_e32 v2, v2, v5, vcc
	v_cndmask_b32_e32 v0, v0, v3, vcc
	v_add_u32_e32 v3, 1, v2
	v_cmp_ge_u32_e32 vcc, v0, v1
	s_nop 1
	v_cndmask_b32_e32 v2, v2, v3, vcc
	v_mul_lo_u32 v0, v1, v2
	v_add_u32_e32 v0, v0, v1
	v_cmp_ne_u32_e32 vcc, v4, v0
	v_mov_b64_e32 v[0:1], s[24:25]
	s_and_saveexec_b64 s[8:9], vcc
	s_cbranch_execz .LBB0_152
	v_mov_b32_e32 v0, 0
	global_load_dword v5, v0, s[24:25] sc1
	s_sleep 2
	global_load_dword v1, v0, s[24:25] sc1
	s_sleep 2
	global_load_dword v3, v0, s[24:25] sc1
	s_sleep 2
	global_load_dword v4, v0, s[24:25] sc1
	s_mov_b64 s[2:3], 0
	s_waitcnt vmcnt(3)
	v_cmp_eq_u32_e32 vcc, v5, v2
	s_and_saveexec_b64 s[28:29], vcc
	s_cbranch_execz .LBB0_151
	s_add_u32 s26, s72, 0x4200
	s_addc_u32 s27, s73, 0
	s_mov_b32 s11, 1
	s_branch .LBB0_141

.LBB0_141:
	global_load_dword v5, v0, s[24:25] sc1
	s_waitcnt vmcnt(1)
	v_cmp_eq_u32_e32 vcc, v1, v2
	s_or_b64 s[36:37], s[36:37], exec
	s_or_b64 s[34:35], s[34:35], exec
	s_sleep 2
	s_and_saveexec_b64 s[38:39], vcc
	s_cbranch_execz .LBB0_140
	global_load_dword v1, v0, s[24:25] sc1
	s_waitcnt vmcnt(3)
	v_cmp_eq_u32_e32 vcc, v3, v2
	s_mov_b64 s[42:43], -1
	s_mov_b64 s[44:45], -1
	s_sleep 2
	s_and_saveexec_b64 s[40:41], vcc
	s_cbranch_execz .LBB0_139
	global_load_dword v3, v0, s[24:25] sc1
	s_waitcnt vmcnt(3)
	v_cmp_eq_u32_e32 vcc, v4, v2
	s_mov_b64 s[46:47], -1
	s_mov_b64 s[48:49], -1
	s_sleep 2
	s_and_saveexec_b64 s[42:43], vcc
	s_cbranch_execz .LBB0_138
	global_load_dword v4, v0, s[24:25] sc1
	s_and_b32 s12, s11, 63
	s_cmp_eq_u32 s12, 0
	s_sleep 2
	s_cbranch_scc0 .LBB0_148
	global_load_dword v6, v0, s[26:27] sc1
	s_waitcnt vmcnt(0)
	v_cmp_eq_u32_e32 vcc, 0, v6
	s_cbranch_vccnz .LBB0_147
	s_mov_b64 s[48:49], 0
	s_branch .LBB0_148
.LBB0_147:
	s_cmp_lt_u32 s11, 0x40001
	s_mov_b64 s[46:47], 0
	s_cselect_b64 s[48:49], -1, 0

.LBB0_559:
	v_and_b32_e32 v17, 64, v216
	v_xor_b32_e32 v16, 1, v216
	v_add_u32_e32 v19, 64, v17
	v_cmp_lt_i32_e32 vcc, v16, v19
	v_xor_b32_e32 v17, 2, v216
	v_xor_b32_e32 v21, 8, v216
	v_cndmask_b32_e32 v16, v216, v16, vcc
	v_lshlrev_b32_e32 v16, 2, v16
	v_cmp_lt_i32_e32 vcc, v17, v19
	s_ashr_i32 s5, s4, 31
	s_lshl_b64 s[4:5], s[4:5], 11
	v_cndmask_b32_e32 v17, v216, v17, vcc
	v_lshlrev_b32_e32 v17, 2, v17
	s_waitcnt lgkmcnt(0)
	s_nop 1
	v_add_f32_dpp v12, v12, v12 quad_perm:[1,0,3,2] row_mask:0xf bank_mask:0xf
	v_xor_b32_e32 v18, 4, v216
	v_cmp_lt_i32_e32 vcc, v18, v19
	s_lshl_b32 s8, s66, 7
	s_waitcnt lgkmcnt(0)
	s_nop 1
	v_add_f32_dpp v12, v12, v12 quad_perm:[2,3,0,1] row_mask:0xf bank_mask:0xf
	v_cndmask_b32_e32 v18, v216, v18, vcc
	v_lshlrev_b32_e32 v18, 2, v18
	v_cmp_lt_i32_e32 vcc, v21, v19
	s_waitcnt lgkmcnt(0)
	s_nop 1
	v_add_f32_dpp v20, v12, v12 row_half_mirror row_mask:0xf bank_mask:0xf
	v_cndmask_b32_e32 v19, v216, v21, vcc
	v_lshlrev_b32_e32 v19, 2, v19
	ds_bpermute_b32 v21, v19, v20
	v_lshlrev_b32_e32 v12, 2, v144
	s_and_saveexec_b64 s[2:3], s[34:35]
	s_cbranch_execz .LBB0_561
	s_add_u32 s6, s30, s4
	s_addc_u32 s11, s31, s5
	s_lshl_b64 s[20:21], s[8:9], 2
	s_add_u32 s6, s6, s20
	s_addc_u32 s11, s11, s21
	s_lshl_b32 s12, s29, 2
	s_waitcnt lgkmcnt(0)
	v_add_f32_e32 v20, v20, v21
	s_add_u32 s20, s6, s12
	v_mul_f32_e32 v20, 0x3b800000, v20
	s_addc_u32 s21, s11, 0
	global_atomic_add_f32 v12, v20, s[20:21]
.LBB0_561:
	s_or_b64 exec, exec, s[2:3]
	s_waitcnt lgkmcnt(0)
	s_nop 1
	v_add_f32_dpp v13, v13, v13 quad_perm:[1,0,3,2] row_mask:0xf bank_mask:0xf
	s_waitcnt lgkmcnt(0)
	s_nop 1
	v_add_f32_dpp v13, v13, v13 quad_perm:[2,3,0,1] row_mask:0xf bank_mask:0xf
	s_waitcnt lgkmcnt(0)
	s_nop 1
	v_add_f32_dpp v13, v13, v13 row_half_mirror row_mask:0xf bank_mask:0xf
	ds_bpermute_b32 v20, v19, v13
	s_and_saveexec_b64 s[2:3], s[34:35]
	s_cbranch_execz .LBB0_563
	s_add_u32 s6, s30, s4
	s_addc_u32 s11, s31, s5
	s_lshl_b64 s[20:21], s[8:9], 2
	s_add_u32 s6, s6, s20
	s_addc_u32 s11, s11, s21
	s_lshl_b32 s12, s29, 2
	s_waitcnt lgkmcnt(0)
	v_add_f32_e32 v13, v13, v20
	s_add_u32 s20, s6, s12
	v_mul_f32_e32 v13, 0x3b800000, v13
	s_addc_u32 s21, s11, 0
	global_atomic_add_f32 v12, v13, s[20:21] offset:4
.LBB0_563:
	s_or_b64 exec, exec, s[2:3]
	s_waitcnt lgkmcnt(0)
	s_nop 1
	v_add_f32_dpp v13, v14, v14 quad_perm:[1,0,3,2] row_mask:0xf bank_mask:0xf
	s_waitcnt lgkmcnt(0)
	s_nop 1
	v_add_f32_dpp v13, v13, v13 quad_perm:[2,3,0,1] row_mask:0xf bank_mask:0xf
	s_waitcnt lgkmcnt(0)
	s_nop 1
	v_add_f32_dpp v13, v13, v13 row_half_mirror row_mask:0xf bank_mask:0xf
	ds_bpermute_b32 v14, v19, v13
	s_and_saveexec_b64 s[2:3], s[34:35]
	s_cbranch_execz .LBB0_565
	s_add_u32 s6, s30, s4
	s_addc_u32 s11, s31, s5
	s_lshl_b64 s[20:21], s[8:9], 2
	s_add_u32 s6, s6, s20
	s_addc_u32 s11, s11, s21
	s_lshl_b32 s12, s29, 2
	s_waitcnt lgkmcnt(0)
	v_add_f32_e32 v13, v13, v14
	s_add_u32 s20, s6, s12
	v_mul_f32_e32 v13, 0x3b800000, v13
	s_addc_u32 s21, s11, 0
	global_atomic_add_f32 v12, v13, s[20:21] offset:8
.LBB0_565:
	s_or_b64 exec, exec, s[2:3]
	s_waitcnt lgkmcnt(0)
	s_nop 1
	v_add_f32_dpp v13, v15, v15 quad_perm:[1,0,3,2] row_mask:0xf bank_mask:0xf
	s_waitcnt lgkmcnt(0)
	s_nop 1
	v_add_f32_dpp v13, v13, v13 quad_perm:[2,3,0,1] row_mask:0xf bank_mask:0xf
	s_waitcnt lgkmcnt(0)
	s_nop 1
	v_add_f32_dpp v13, v13, v13 row_half_mirror row_mask:0xf bank_mask:0xf
	ds_bpermute_b32 v14, v19, v13
	s_and_saveexec_b64 s[2:3], s[34:35]
	s_cbranch_execz .LBB0_567
	s_add_u32 s6, s30, s4
	s_addc_u32 s11, s31, s5
	s_lshl_b64 s[20:21], s[8:9], 2
	s_add_u32 s6, s6, s20
	s_addc_u32 s11, s11, s21
	s_lshl_b32 s12, s29, 2
	s_waitcnt lgkmcnt(0)
	v_add_f32_e32 v13, v13, v14
	s_add_u32 s20, s6, s12
	v_mul_f32_e32 v13, 0x3b800000, v13
	s_addc_u32 s21, s11, 0
	global_atomic_add_f32 v12, v13, s[20:21] offset:12
.LBB0_567:
	s_or_b64 exec, exec, s[2:3]
	s_waitcnt lgkmcnt(0)
	s_nop 1
	v_add_f32_dpp v8, v8, v8 quad_perm:[1,0,3,2] row_mask:0xf bank_mask:0xf
	s_waitcnt lgkmcnt(0)
	s_nop 1
	v_add_f32_dpp v8, v8, v8 quad_perm:[2,3,0,1] row_mask:0xf bank_mask:0xf
	s_waitcnt lgkmcnt(0)
	s_nop 1
	v_add_f32_dpp v8, v8, v8 row_half_mirror row_mask:0xf bank_mask:0xf
	ds_bpermute_b32 v13, v19, v8
	s_and_saveexec_b64 s[2:3], s[34:35]
	s_cbranch_execz .LBB0_569
	s_add_u32 s6, s30, s4
	s_addc_u32 s11, s31, s5
	s_lshl_b64 s[20:21], s[8:9], 2
	s_add_u32 s6, s6, s20
	s_addc_u32 s11, s11, s21
	s_lshl_b32 s12, s29, 2
	s_waitcnt lgkmcnt(0)
	v_add_f32_e32 v8, v8, v13
	s_add_u32 s20, s6, s12
	v_mul_f32_e32 v8, 0x3b800000, v8
	s_addc_u32 s21, s11, 0
	global_atomic_add_f32 v12, v8, s[20:21] offset:64
.LBB0_569:
	s_or_b64 exec, exec, s[2:3]
	s_waitcnt lgkmcnt(0)
	s_nop 1
	v_add_f32_dpp v8, v9, v9 quad_perm:[1,0,3,2] row_mask:0xf bank_mask:0xf
	s_waitcnt lgkmcnt(0)
	s_nop 1
	v_add_f32_dpp v8, v8, v8 quad_perm:[2,3,0,1] row_mask:0xf bank_mask:0xf
	s_waitcnt lgkmcnt(0)
	s_nop 1
	v_add_f32_dpp v8, v8, v8 row_half_mirror row_mask:0xf bank_mask:0xf
	ds_bpermute_b32 v9, v19, v8
	s_and_saveexec_b64 s[2:3], s[34:35]
	s_cbranch_execz .LBB0_571
	s_add_u32 s6, s30, s4
	s_addc_u32 s11, s31, s5
	s_lshl_b64 s[20:21], s[8:9], 2
	s_add_u32 s6, s6, s20
	s_addc_u32 s11, s11, s21
	s_lshl_b32 s12, s29, 2
	s_waitcnt lgkmcnt(0)
	v_add_f32_e32 v8, v8, v9
	s_add_u32 s20, s6, s12
	v_mul_f32_e32 v8, 0x3b800000, v8
	s_addc_u32 s21, s11, 0
	global_atomic_add_f32 v12, v8, s[20:21] offset:68
.LBB0_571:
	s_or_b64 exec, exec, s[2:3]
	s_waitcnt lgkmcnt(0)
	s_nop 1
	v_add_f32_dpp v8, v10, v10 quad_perm:[1,0,3,2] row_mask:0xf bank_mask:0xf
	s_waitcnt lgkmcnt(0)
	s_nop 1
	v_add_f32_dpp v8, v8, v8 quad_perm:[2,3,0,1] row_mask:0xf bank_mask:0xf
	s_waitcnt lgkmcnt(0)
	s_nop 1
	v_add_f32_dpp v8, v8, v8 row_half_mirror row_mask:0xf bank_mask:0xf
	ds_bpermute_b32 v9, v19, v8
	s_and_saveexec_b64 s[2:3], s[34:35]
	s_cbranch_execz .LBB0_573
	s_add_u32 s6, s30, s4
	s_addc_u32 s11, s31, s5
	s_lshl_b64 s[20:21], s[8:9], 2
	s_add_u32 s6, s6, s20
	s_addc_u32 s11, s11, s21
	s_lshl_b32 s12, s29, 2
	s_waitcnt lgkmcnt(0)
	v_add_f32_e32 v8, v8, v9
	s_add_u32 s20, s6, s12
	v_mul_f32_e32 v8, 0x3b800000, v8
	s_addc_u32 s21, s11, 0
	global_atomic_add_f32 v12, v8, s[20:21] offset:72
.LBB0_573:
	s_or_b64 exec, exec, s[2:3]
	s_waitcnt lgkmcnt(0)
	s_nop 1
	v_add_f32_dpp v8, v11, v11 quad_perm:[1,0,3,2] row_mask:0xf bank_mask:0xf
	s_waitcnt lgkmcnt(0)
	s_nop 1
	v_add_f32_dpp v8, v8, v8 quad_perm:[2,3,0,1] row_mask:0xf bank_mask:0xf
	s_waitcnt lgkmcnt(0)
	s_nop 1
	v_add_f32_dpp v8, v8, v8 row_half_mirror row_mask:0xf bank_mask:0xf
	ds_bpermute_b32 v9, v19, v8
	s_and_saveexec_b64 s[2:3], s[34:35]
	s_cbranch_execz .LBB0_575
	s_add_u32 s6, s30, s4
	s_addc_u32 s11, s31, s5
	s_lshl_b64 s[20:21], s[8:9], 2
	s_add_u32 s6, s6, s20
	s_addc_u32 s8, s11, s21
	s_lshl_b32 s11, s29, 2
	s_waitcnt lgkmcnt(0)
	v_add_f32_e32 v8, v8, v9
	s_add_u32 s20, s6, s11
	v_mul_f32_e32 v8, 0x3b800000, v8
	s_addc_u32 s21, s8, 0
	global_atomic_add_f32 v12, v8, s[20:21] offset:76
.LBB0_575:
	s_or_b64 exec, exec, s[2:3]
	s_add_i32 s8, s64, 0xfffffc80
	s_waitcnt lgkmcnt(0)
	s_nop 1
	v_add_f32_dpp v4, v4, v4 quad_perm:[1,0,3,2] row_mask:0xf bank_mask:0xf
	s_waitcnt lgkmcnt(0)
	s_nop 1
	v_add_f32_dpp v4, v4, v4 quad_perm:[2,3,0,1] row_mask:0xf bank_mask:0xf
	s_waitcnt lgkmcnt(0)
	s_nop 1
	v_add_f32_dpp v4, v4, v4 row_half_mirror row_mask:0xf bank_mask:0xf
	ds_bpermute_b32 v8, v19, v4
	s_and_saveexec_b64 s[2:3], s[34:35]
	s_cbranch_execz .LBB0_577
	s_add_u32 s6, s30, s4
	s_addc_u32 s11, s31, s5
	s_lshl_b64 s[20:21], s[8:9], 2
	s_add_u32 s6, s6, s20
	s_addc_u32 s11, s11, s21
	s_lshl_b32 s12, s29, 2
	s_waitcnt lgkmcnt(0)
	v_add_f32_e32 v4, v4, v8
	s_add_u32 s20, s6, s12
	v_mul_f32_e32 v4, 0x3b800000, v4
	s_addc_u32 s21, s11, 0
	global_atomic_add_f32 v12, v4, s[20:21]
.LBB0_577:
	s_or_b64 exec, exec, s[2:3]
	s_waitcnt lgkmcnt(0)
	s_nop 1
	v_add_f32_dpp v4, v5, v5 quad_perm:[1,0,3,2] row_mask:0xf bank_mask:0xf
	s_waitcnt lgkmcnt(0)
	s_nop 1
	v_add_f32_dpp v4, v4, v4 quad_perm:[2,3,0,1] row_mask:0xf bank_mask:0xf
	s_waitcnt lgkmcnt(0)
	s_nop 1
	v_add_f32_dpp v4, v4, v4 row_half_mirror row_mask:0xf bank_mask:0xf
	ds_bpermute_b32 v5, v19, v4
	s_and_saveexec_b64 s[2:3], s[34:35]
	s_cbranch_execz .LBB0_579
	s_add_u32 s6, s30, s4
	s_addc_u32 s11, s31, s5
	s_lshl_b64 s[20:21], s[8:9], 2
	s_add_u32 s6, s6, s20
	s_addc_u32 s11, s11, s21
	s_lshl_b32 s12, s29, 2
	s_waitcnt lgkmcnt(0)
	v_add_f32_e32 v4, v4, v5
	s_add_u32 s20, s6, s12
	v_mul_f32_e32 v4, 0x3b800000, v4
	s_addc_u32 s21, s11, 0
	global_atomic_add_f32 v12, v4, s[20:21] offset:4
.LBB0_579:
	s_or_b64 exec, exec, s[2:3]
	s_waitcnt lgkmcnt(0)
	s_nop 1
	v_add_f32_dpp v4, v6, v6 quad_perm:[1,0,3,2] row_mask:0xf bank_mask:0xf
	s_waitcnt lgkmcnt(0)
	s_nop 1
	v_add_f32_dpp v4, v4, v4 quad_perm:[2,3,0,1] row_mask:0xf bank_mask:0xf
	s_waitcnt lgkmcnt(0)
	s_nop 1
	v_add_f32_dpp v4, v4, v4 row_half_mirror row_mask:0xf bank_mask:0xf
	ds_bpermute_b32 v5, v19, v4
	s_and_saveexec_b64 s[2:3], s[34:35]
	s_cbranch_execz .LBB0_581
	s_add_u32 s6, s30, s4
	s_addc_u32 s11, s31, s5
	s_lshl_b64 s[20:21], s[8:9], 2
	s_add_u32 s6, s6, s20
	s_addc_u32 s11, s11, s21
	s_lshl_b32 s12, s29, 2
	s_waitcnt lgkmcnt(0)
	v_add_f32_e32 v4, v4, v5
	s_add_u32 s20, s6, s12
	v_mul_f32_e32 v4, 0x3b800000, v4
	s_addc_u32 s21, s11, 0
	global_atomic_add_f32 v12, v4, s[20:21] offset:8
.LBB0_581:
	s_or_b64 exec, exec, s[2:3]
	s_waitcnt lgkmcnt(0)
	s_nop 1
	v_add_f32_dpp v4, v7, v7 quad_perm:[1,0,3,2] row_mask:0xf bank_mask:0xf
	s_waitcnt lgkmcnt(0)
	s_nop 1
	v_add_f32_dpp v4, v4, v4 quad_perm:[2,3,0,1] row_mask:0xf bank_mask:0xf
	s_waitcnt lgkmcnt(0)
	s_nop 1
	v_add_f32_dpp v4, v4, v4 row_half_mirror row_mask:0xf bank_mask:0xf
	ds_bpermute_b32 v5, v19, v4
	s_and_saveexec_b64 s[2:3], s[34:35]
	s_cbranch_execz .LBB0_583
	s_add_u32 s6, s30, s4
	s_addc_u32 s11, s31, s5
	s_lshl_b64 s[20:21], s[8:9], 2
	s_add_u32 s6, s6, s20
	s_addc_u32 s11, s11, s21
	s_lshl_b32 s12, s29, 2
	s_waitcnt lgkmcnt(0)
	v_add_f32_e32 v4, v4, v5
	s_add_u32 s20, s6, s12
	v_mul_f32_e32 v4, 0x3b800000, v4
	s_addc_u32 s21, s11, 0
	global_atomic_add_f32 v12, v4, s[20:21] offset:12
.LBB0_583:
	s_or_b64 exec, exec, s[2:3]
	s_waitcnt lgkmcnt(0)
	s_nop 1
	v_add_f32_dpp v0, v0, v0 quad_perm:[1,0,3,2] row_mask:0xf bank_mask:0xf
	s_waitcnt lgkmcnt(0)
	s_nop 1
	v_add_f32_dpp v0, v0, v0 quad_perm:[2,3,0,1] row_mask:0xf bank_mask:0xf
	s_waitcnt lgkmcnt(0)
	s_nop 1
	v_add_f32_dpp v0, v0, v0 row_half_mirror row_mask:0xf bank_mask:0xf
	ds_bpermute_b32 v4, v19, v0
	s_and_saveexec_b64 s[2:3], s[34:35]
	s_cbranch_execz .LBB0_585
	s_add_u32 s6, s30, s4
	s_addc_u32 s11, s31, s5
	s_lshl_b64 s[20:21], s[8:9], 2
	s_add_u32 s6, s6, s20
	s_addc_u32 s11, s11, s21
	s_lshl_b32 s12, s29, 2
	s_waitcnt lgkmcnt(0)
	v_add_f32_e32 v0, v0, v4
	s_add_u32 s20, s6, s12
	v_mul_f32_e32 v0, 0x3b800000, v0
	s_addc_u32 s21, s11, 0
	global_atomic_add_f32 v12, v0, s[20:21] offset:64
.LBB0_585:
	s_or_b64 exec, exec, s[2:3]
	s_waitcnt lgkmcnt(0)
	s_nop 1
	v_add_f32_dpp v0, v1, v1 quad_perm:[1,0,3,2] row_mask:0xf bank_mask:0xf
	s_waitcnt lgkmcnt(0)
	s_nop 1
	v_add_f32_dpp v0, v0, v0 quad_perm:[2,3,0,1] row_mask:0xf bank_mask:0xf
	s_waitcnt lgkmcnt(0)
	s_nop 1
	v_add_f32_dpp v0, v0, v0 row_half_mirror row_mask:0xf bank_mask:0xf
	ds_bpermute_b32 v1, v19, v0
	s_and_saveexec_b64 s[2:3], s[34:35]
	s_cbranch_execz .LBB0_587
	s_add_u32 s6, s30, s4
	s_addc_u32 s11, s31, s5
	s_lshl_b64 s[20:21], s[8:9], 2
	s_add_u32 s6, s6, s20
	s_addc_u32 s11, s11, s21
	s_lshl_b32 s12, s29, 2
	s_waitcnt lgkmcnt(0)
	v_add_f32_e32 v0, v0, v1
	s_add_u32 s20, s6, s12
	v_mul_f32_e32 v0, 0x3b800000, v0
	s_addc_u32 s21, s11, 0
	global_atomic_add_f32 v12, v0, s[20:21] offset:68
.LBB0_587:
	s_or_b64 exec, exec, s[2:3]
	s_waitcnt lgkmcnt(0)
	s_nop 1
	v_add_f32_dpp v0, v2, v2 quad_perm:[1,0,3,2] row_mask:0xf bank_mask:0xf
	s_waitcnt lgkmcnt(0)
	s_nop 1
	v_add_f32_dpp v0, v0, v0 quad_perm:[2,3,0,1] row_mask:0xf bank_mask:0xf
	s_waitcnt lgkmcnt(0)
	s_nop 1
	v_add_f32_dpp v0, v0, v0 row_half_mirror row_mask:0xf bank_mask:0xf
	ds_bpermute_b32 v1, v19, v0
	s_and_saveexec_b64 s[2:3], s[34:35]
	s_cbranch_execz .LBB0_589
	s_add_u32 s6, s30, s4
	s_addc_u32 s11, s31, s5
	s_lshl_b64 s[20:21], s[8:9], 2
	s_add_u32 s6, s6, s20
	s_addc_u32 s11, s11, s21
	s_lshl_b32 s12, s29, 2
	s_waitcnt lgkmcnt(0)
	v_add_f32_e32 v0, v0, v1
	s_add_u32 s20, s6, s12
	v_mul_f32_e32 v0, 0x3b800000, v0
	s_addc_u32 s21, s11, 0
	global_atomic_add_f32 v12, v0, s[20:21] offset:72
.LBB0_589:
	s_or_b64 exec, exec, s[2:3]
	s_waitcnt lgkmcnt(0)
	s_nop 1
	v_add_f32_dpp v0, v3, v3 quad_perm:[1,0,3,2] row_mask:0xf bank_mask:0xf
	s_waitcnt lgkmcnt(0)
	s_nop 1
	v_add_f32_dpp v0, v0, v0 quad_perm:[2,3,0,1] row_mask:0xf bank_mask:0xf
	s_waitcnt lgkmcnt(0)
	s_nop 1
	v_add_f32_dpp v0, v0, v0 row_half_mirror row_mask:0xf bank_mask:0xf
	ds_bpermute_b32 v1, v19, v0
	s_and_saveexec_b64 s[2:3], s[34:35]
	s_cbranch_execz .LBB0_591
	s_add_u32 s6, s30, s4
	s_addc_u32 s11, s31, s5
	s_lshl_b64 s[4:5], s[8:9], 2
	s_add_u32 s4, s6, s4
	s_addc_u32 s5, s11, s5
	s_lshl_b32 s6, s29, 2
	s_waitcnt lgkmcnt(0)
	v_add_f32_e32 v0, v0, v1
	s_add_u32 s4, s4, s6
	v_mul_f32_e32 v0, 0x3b800000, v0
	s_addc_u32 s5, s5, 0
	global_atomic_add_f32 v12, v0, s[4:5] offset:76

.LBB0_621:
	v_readlane_b32 s2, v253, 2
	v_readlane_b32 s3, v253, 3
	v_cvt_f32_u32_e32 v0, v2
	v_sub_u32_e32 v4, 0, v2
	v_rcp_iflag_f32_e32 v0, v0
	s_nop 1
	global_atomic_add v3, v33, v215, s[2:3] sc0
	v_mul_f32_e32 v0, 0x4f7ffffe, v0
	v_cvt_u32_f32_e32 v0, v0
	v_mul_lo_u32 v4, v4, v0
	v_mul_hi_u32 v4, v0, v4
	v_add_u32_e32 v0, v0, v4
	s_waitcnt vmcnt(0)
	v_mul_hi_u32 v0, v3, v0
	v_mul_lo_u32 v4, v0, v2
	v_sub_u32_e32 v4, v3, v4
	v_add_u32_e32 v5, 1, v0
	v_cmp_ge_u32_e32 vcc, v4, v2
	v_add_u32_e32 v3, 1, v3
	s_nop 0
	v_cndmask_b32_e32 v0, v0, v5, vcc
	v_sub_u32_e32 v5, v4, v2
	v_cndmask_b32_e32 v4, v4, v5, vcc
	v_add_u32_e32 v5, 1, v0
	v_cmp_ge_u32_e32 vcc, v4, v2
	s_nop 1
	v_cndmask_b32_e32 v0, v0, v5, vcc
	v_mul_lo_u32 v4, v2, v0
	v_add_u32_e32 v2, v4, v2
	v_cmp_ne_u32_e32 vcc, v3, v2
	s_and_saveexec_b64 s[2:3], vcc
	s_xor_b64 s[4:5], exec, s[2:3]
	s_cbranch_execz .LBB0_641
	v_readlane_b32 s2, v253, 4
	v_readlane_b32 s3, v253, 5
	s_nop 4
	global_load_dword v4, v33, s[2:3] sc1
	s_sleep 2
	s_waitcnt lgkmcnt(0)
	global_load_dword v1, v33, s[2:3] sc1
	s_sleep 2
	global_load_dword v2, v33, s[2:3] sc1
	s_sleep 2
	global_load_dword v3, v33, s[2:3] sc1
	s_waitcnt vmcnt(3)
	v_cmp_eq_u32_e32 vcc, v4, v0
	s_and_saveexec_b64 s[6:7], vcc
	s_cbranch_execz .LBB0_640
	s_mov_b32 s11, 1
	s_mov_b64 s[2:3], 0
	s_branch .LBB0_628

.LBB0_628:
	v_readlane_b32 s12, v253, 4
	v_readlane_b32 s13, v253, 5
	s_waitcnt vmcnt(0)
	v_cmp_eq_u32_e32 vcc, v1, v0
	s_or_b64 s[38:39], s[38:39], exec
	s_or_b64 s[36:37], s[36:37], exec
	s_nop 0
	global_load_dword v4, v33, s[12:13] sc1
	s_sleep 2
	s_and_saveexec_b64 s[40:41], vcc
	s_cbranch_execz .LBB0_627
	v_readlane_b32 s12, v253, 4
	v_readlane_b32 s13, v253, 5
	s_waitcnt vmcnt(2)
	v_cmp_eq_u32_e32 vcc, v2, v0
	s_mov_b64 s[28:29], -1
	s_mov_b64 s[30:31], -1
	s_nop 0
	global_load_dword v1, v33, s[12:13] sc1
	s_sleep 2
	s_and_saveexec_b64 s[42:43], vcc
	s_cbranch_execz .LBB0_626
	v_readlane_b32 s12, v253, 4
	v_readlane_b32 s13, v253, 5
	s_waitcnt vmcnt(2)
	v_cmp_eq_u32_e32 vcc, v3, v0
	s_mov_b64 s[46:47], -1
	s_nop 1
	global_load_dword v2, v33, s[12:13] sc1
	s_sleep 2
	s_and_saveexec_b64 s[30:31], vcc
	s_cbranch_execz .LBB0_625
	v_readlane_b32 s12, v253, 4
	v_readlane_b32 s13, v253, 5
	s_mov_b64 s[44:45], -1
	s_nop 3
	global_load_dword v3, v33, s[12:13] sc1
	s_and_b32 s12, s11, 63
	s_cmp_eq_u32 s12, 0
	s_sleep 2
	s_cbranch_scc1 .LBB0_634
	s_and_b64 vcc, exec, s[28:29]
	s_cbranch_vccz .LBB0_624

.LBB0_636:
	s_cmp_lt_u32 s11, 0x40001
	s_mov_b64 s[46:47], 0
	s_cselect_b64 s[28:29], -1, 0
	s_and_b64 vcc, exec, s[28:29]
	s_cbranch_vccnz .LBB0_633
	s_branch .LBB0_624

.LBB0_644:
	s_or_b64 exec, exec, s[4:5]
	s_waitcnt vmcnt(0)
	v_readfirstlane_b32 s2, v2
	v_cvt_f32_u32_e32 v2, v1
	v_sub_u32_e32 v3, 0, v1
	v_add_u32_e32 v0, s2, v0
	v_readlane_b32 s4, v253, 8
	v_rcp_iflag_f32_e32 v2, v2
	v_readlane_b32 s5, v253, 9
	s_mov_b64 s[2:3], -1
	v_mul_f32_e32 v2, 0x4f7ffffe, v2
	v_cvt_u32_f32_e32 v2, v2
	v_mul_lo_u32 v3, v3, v2
	v_mul_hi_u32 v3, v2, v3
	v_add_u32_e32 v2, v2, v3
	v_mul_hi_u32 v2, v0, v2
	v_mul_lo_u32 v3, v2, v1
	v_sub_u32_e32 v3, v0, v3
	v_cmp_ge_u32_e32 vcc, v3, v1
	v_add_u32_e32 v4, 1, v2
	v_add_u32_e32 v0, 1, v0
	v_cndmask_b32_e32 v2, v2, v4, vcc
	v_sub_u32_e32 v4, v3, v1
	v_cndmask_b32_e32 v3, v3, v4, vcc
	v_cmp_ge_u32_e32 vcc, v3, v1
	v_add_u32_e32 v3, 1, v2
	s_nop 0
	v_cndmask_b32_e32 v2, v2, v3, vcc
	v_mul_lo_u32 v3, v1, v2
	v_add_u32_e32 v1, v3, v1
	v_cmp_ne_u32_e32 vcc, v0, v1
	v_mov_b64_e32 v[0:1], s[4:5]
	s_and_saveexec_b64 s[4:5], vcc
	s_cbranch_execz .LBB0_662
	v_readlane_b32 s2, v253, 8
	v_readlane_b32 s3, v253, 9
	s_nop 4
	global_load_dword v4, v33, s[2:3] sc1
	s_sleep 2
	global_load_dword v0, v33, s[2:3] sc1
	s_sleep 2
	global_load_dword v1, v33, s[2:3] sc1
	s_sleep 2
	global_load_dword v3, v33, s[2:3] sc1
	s_mov_b64 s[2:3], 0
	s_waitcnt vmcnt(3)
	v_cmp_eq_u32_e32 vcc, v4, v2
	s_and_saveexec_b64 s[6:7], vcc
	s_cbranch_execz .LBB0_661
	s_mov_b32 s11, 1
	s_branch .LBB0_651

.LBB0_651:
	v_readlane_b32 s12, v253, 8
	v_readlane_b32 s13, v253, 9
	s_waitcnt vmcnt(0)
	v_cmp_eq_u32_e32 vcc, v0, v2
	s_or_b64 s[38:39], s[38:39], exec
	s_or_b64 s[36:37], s[36:37], exec
	s_nop 0
	global_load_dword v4, v33, s[12:13] sc1
	s_sleep 2
	s_and_saveexec_b64 s[40:41], vcc
	s_cbranch_execz .LBB0_650
	v_readlane_b32 s12, v253, 8
	v_readlane_b32 s13, v253, 9
	s_waitcnt vmcnt(2)
	v_cmp_eq_u32_e32 vcc, v1, v2
	s_mov_b64 s[28:29], -1
	s_mov_b64 s[30:31], -1
	s_nop 0
	global_load_dword v0, v33, s[12:13] sc1
	s_sleep 2
	s_and_saveexec_b64 s[42:43], vcc
	s_cbranch_execz .LBB0_649
	v_readlane_b32 s12, v253, 8
	v_readlane_b32 s13, v253, 9
	s_waitcnt vmcnt(2)
	v_cmp_eq_u32_e32 vcc, v3, v2
	s_mov_b64 s[46:47], -1
	s_nop 1
	global_load_dword v1, v33, s[12:13] sc1
	s_sleep 2
	s_and_saveexec_b64 s[30:31], vcc
	s_cbranch_execz .LBB0_648
	v_readlane_b32 s12, v253, 8
	v_readlane_b32 s13, v253, 9
	s_mov_b64 s[44:45], -1
	s_nop 3
	global_load_dword v3, v33, s[12:13] sc1
	s_and_b32 s12, s11, 63
	s_cmp_eq_u32 s12, 0
	s_sleep 2
	s_cbranch_scc1 .LBB0_657
	s_and_b64 vcc, exec, s[28:29]
	s_cbranch_vccz .LBB0_647

.LBB0_734:
	s_or_b64 exec, exec, s[2:3]
	v_lshl_add_u32 v0, s68, 5, v97
	v_ashrrev_i32_e32 v1, 31, v0
	s_lshr_b32 s69, s67, 1
	v_lshlrev_b64 v[0:1], 11, v[0:1]
	v_lshl_add_u64 v[0:1], s[6:7], 0, v[0:1]
	s_lshl_b32 s8, s69, 9
	v_lshl_add_u64 v[0:1], v[0:1], 0, s[8:9]
	v_lshl_add_u64 v[4:5], v[0:1], 0, v[32:33]
	s_waitcnt lgkmcnt(0)
	s_barrier
	global_load_dwordx4 v[0:3], v[4:5], off
	s_nop 0
	global_load_dwordx4 v[4:7], v[4:5], off offset:16
	ds_read_b128 v[8:11], v98
	ds_read_b128 v[12:15], v98 offset:16
	s_waitcnt vmcnt(1) lgkmcnt(1)
	v_fma_f32 v0, v8, v0, 0
	v_fmac_f32_e32 v0, v9, v1
	v_fmac_f32_e32 v0, v10, v2
	v_fmac_f32_e32 v0, v11, v3
	s_waitcnt vmcnt(0) lgkmcnt(0)
	v_fmac_f32_e32 v0, v12, v4
	v_fmac_f32_e32 v0, v13, v5
	v_fmac_f32_e32 v0, v14, v6
	v_fmac_f32_e32 v0, v15, v7
	s_waitcnt lgkmcnt(0)
	s_nop 1
	v_add_f32_dpp v0, v0, v0 quad_perm:[1,0,3,2] row_mask:0xf bank_mask:0xf
	s_waitcnt lgkmcnt(0)
	s_nop 1
	v_add_f32_dpp v0, v0, v0 quad_perm:[2,3,0,1] row_mask:0xf bank_mask:0xf
	s_waitcnt lgkmcnt(0)
	s_nop 1
	v_add_f32_dpp v0, v0, v0 row_half_mirror row_mask:0xf bank_mask:0xf
	ds_bpermute_b32 v1, v107, v0
	s_and_saveexec_b64 s[2:3], s[38:39]
	s_cbranch_execz .LBB0_736
	s_waitcnt lgkmcnt(0)
	v_add_f32_e32 v0, v0, v1
	ds_write_b32 v99, v0 offset:512

.LBB0_740:
	s_or_b64 exec, exec, s[2:3]
	s_waitcnt lgkmcnt(0)
	s_barrier
	ds_read_b64 v[0:1], v33 offset:672
	v_readlane_b32 s72, v251, 1
	v_readlane_b32 s76, v251, 5
	v_readlane_b32 s77, v251, 6
	v_mov_b32_e32 v85, v33
	s_waitcnt lgkmcnt(0)
	v_lshl_add_u32 v2, v0, 7, v82
	v_ashrrev_i32_e32 v3, 31, v2
	v_lshlrev_b64 v[94:95], 11, v[2:3]
	v_lshl_add_u64 v[2:3], s[76:77], 0, v[94:95]
	v_lshl_add_u64 v[2:3], v[2:3], 0, s[8:9]
	v_lshl_add_u64 v[2:3], v[2:3], 0, v[84:85]
	s_mov_b32 s2, 0x8000
	v_add_co_u32_e32 v4, vcc, s2, v2
	s_mov_b32 s3, 0x10000
	s_nop 0
	v_addc_co_u32_e32 v5, vcc, 0, v3, vcc
	global_load_dwordx4 v[62:65], v[2:3], off
	global_load_dwordx4 v[54:57], v[4:5], off
	v_add_co_u32_e32 v4, vcc, s3, v2
	s_mov_b32 s11, 0x18000
	s_nop 0
	v_addc_co_u32_e32 v5, vcc, 0, v3, vcc
	v_add_co_u32_e32 v6, vcc, s11, v2
	s_mov_b32 s16, 0x28000
	s_nop 0
	v_addc_co_u32_e32 v7, vcc, 0, v3, vcc
	global_load_dwordx4 v[46:49], v[4:5], off
	global_load_dwordx4 v[38:41], v[6:7], off
	v_add_co_u32_e32 v4, vcc, s12, v2
	s_mov_b32 s18, 0x30000
	s_nop 0
	v_addc_co_u32_e32 v5, vcc, 0, v3, vcc
	v_add_co_u32_e32 v6, vcc, s16, v2
	v_lshl_add_u32 v0, v1, 7, v82
	s_nop 0
	v_addc_co_u32_e32 v7, vcc, 0, v3, vcc
	global_load_dwordx4 v[34:37], v[4:5], off
	global_load_dwordx4 v[24:27], v[6:7], off
	v_add_co_u32_e32 v4, vcc, s18, v2
	s_mov_b32 s19, 0x38000
	s_nop 0
	v_addc_co_u32_e32 v5, vcc, 0, v3, vcc
	v_ashrrev_i32_e32 v1, 31, v0
	v_add_co_u32_e32 v2, vcc, s19, v2
	v_lshl_add_u64 v[74:75], v[86:87], 0, s[8:9]
	v_lshlrev_b64 v[0:1], 11, v[0:1]
	v_addc_co_u32_e32 v3, vcc, 0, v3, vcc
	v_lshl_add_u64 v[0:1], v[74:75], 0, v[0:1]
	global_load_dwordx4 v[16:19], v[4:5], off
	global_load_dwordx4 v[8:11], v[2:3], off
	v_add_co_u32_e32 v2, vcc, s2, v0
	v_readlane_b32 s73, v251, 2
	s_nop 0
	v_addc_co_u32_e32 v3, vcc, 0, v1, vcc
	global_load_dwordx4 v[66:69], v[0:1], off
	global_load_dwordx4 v[58:61], v[2:3], off
	v_add_co_u32_e32 v2, vcc, s3, v0
	v_readlane_b32 s74, v251, 3
	s_nop 0
	v_addc_co_u32_e32 v3, vcc, 0, v1, vcc
	v_add_co_u32_e32 v4, vcc, s11, v0
	v_readlane_b32 s75, v251, 4
	s_nop 0
	v_addc_co_u32_e32 v5, vcc, 0, v1, vcc
	global_load_dwordx4 v[50:53], v[2:3], off
	global_load_dwordx4 v[42:45], v[4:5], off
	v_add_co_u32_e32 v2, vcc, s12, v0
	v_readlane_b32 s78, v251, 7
	s_nop 0
	v_addc_co_u32_e32 v3, vcc, 0, v1, vcc
	v_add_co_u32_e32 v4, vcc, s16, v0
	v_readlane_b32 s79, v251, 8
	s_nop 0
	v_addc_co_u32_e32 v5, vcc, 0, v1, vcc
	global_load_dwordx4 v[28:31], v[2:3], off
	global_load_dwordx4 v[20:23], v[4:5], off
	v_add_co_u32_e32 v2, vcc, s18, v0
	v_readlane_b32 s80, v251, 9
	s_nop 0
	v_addc_co_u32_e32 v3, vcc, 0, v1, vcc
	v_add_co_u32_e32 v0, vcc, s19, v0
	v_readlane_b32 s81, v251, 10
	s_nop 0
	v_addc_co_u32_e32 v1, vcc, 0, v1, vcc
	global_load_dwordx4 v[12:15], v[2:3], off
	global_load_dwordx4 v[4:7], v[0:1], off
	v_add_u32_e32 v0, 0, v84
	ds_read_b128 v[0:3], v0
	v_readlane_b32 s82, v251, 11
	v_readlane_b32 s83, v251, 12
	v_readlane_b32 s84, v251, 13
	v_readlane_b32 s85, v251, 14
	s_waitcnt vmcnt(15) lgkmcnt(0)
	v_mul_f32_e32 v63, v1, v63
	v_fmac_f32_e32 v63, v0, v62
	v_fmac_f32_e32 v63, v2, v64
	v_fmac_f32_e32 v63, v3, v65
	v_readlane_b32 s86, v251, 15
	v_readlane_b32 s87, v251, 16
	s_waitcnt lgkmcnt(0)
	s_nop 1
	v_add_f32_dpp v62, v63, v63 quad_perm:[1,0,3,2] row_mask:0xf bank_mask:0xf
	s_waitcnt lgkmcnt(0)
	s_nop 1
	v_add_f32_dpp v62, v62, v62 quad_perm:[2,3,0,1] row_mask:0xf bank_mask:0xf
	s_waitcnt lgkmcnt(0)
	s_nop 1
	v_add_f32_dpp v62, v62, v62 row_half_mirror row_mask:0xf bank_mask:0xf
	s_waitcnt lgkmcnt(0)
	s_nop 1
	v_add_f32_dpp v62, v62, v62 row_mirror row_mask:0xf bank_mask:0xf
	ds_bpermute_b32 v63, v108, v62
	s_and_saveexec_b64 s[2:3], s[44:45]
	s_cbranch_execz .LBB0_742
	s_waitcnt lgkmcnt(0)
	v_add_f32_e32 v62, v62, v63
	ds_write_b32 v102, v62 offset:1024
.LBB0_742:
	s_or_b64 exec, exec, s[2:3]
	s_waitcnt vmcnt(14)
	v_mul_f32_e32 v55, v1, v55
	v_fmac_f32_e32 v55, v0, v54
	v_fmac_f32_e32 v55, v2, v56
	v_fmac_f32_e32 v55, v3, v57
	s_waitcnt lgkmcnt(0)
	s_nop 1
	v_add_f32_dpp v54, v55, v55 quad_perm:[1,0,3,2] row_mask:0xf bank_mask:0xf
	s_waitcnt lgkmcnt(0)
	s_nop 1
	v_add_f32_dpp v54, v54, v54 quad_perm:[2,3,0,1] row_mask:0xf bank_mask:0xf
	s_waitcnt lgkmcnt(0)
	s_nop 1
	v_add_f32_dpp v54, v54, v54 row_half_mirror row_mask:0xf bank_mask:0xf
	s_waitcnt lgkmcnt(0)
	s_nop 1
	v_add_f32_dpp v54, v54, v54 row_mirror row_mask:0xf bank_mask:0xf
	ds_bpermute_b32 v55, v108, v54
	s_and_saveexec_b64 s[2:3], s[44:45]
	s_cbranch_execz .LBB0_744
	s_waitcnt lgkmcnt(0)
	v_add_f32_e32 v54, v54, v55
	ds_write_b32 v102, v54 offset:1088
.LBB0_744:
	s_or_b64 exec, exec, s[2:3]
	s_waitcnt vmcnt(13)
	v_mul_f32_e32 v47, v1, v47
	v_fmac_f32_e32 v47, v0, v46
	v_fmac_f32_e32 v47, v2, v48
	v_fmac_f32_e32 v47, v3, v49
	s_waitcnt lgkmcnt(0)
	s_nop 1
	v_add_f32_dpp v46, v47, v47 quad_perm:[1,0,3,2] row_mask:0xf bank_mask:0xf
	s_waitcnt lgkmcnt(0)
	s_nop 1
	v_add_f32_dpp v46, v46, v46 quad_perm:[2,3,0,1] row_mask:0xf bank_mask:0xf
	s_waitcnt lgkmcnt(0)
	s_nop 1
	v_add_f32_dpp v46, v46, v46 row_half_mirror row_mask:0xf bank_mask:0xf
	s_waitcnt lgkmcnt(0)
	s_nop 1
	v_add_f32_dpp v46, v46, v46 row_mirror row_mask:0xf bank_mask:0xf
	ds_bpermute_b32 v47, v108, v46
	s_and_saveexec_b64 s[2:3], s[44:45]
	s_cbranch_execz .LBB0_746
	s_waitcnt lgkmcnt(0)
	v_add_f32_e32 v46, v46, v47
	ds_write_b32 v102, v46 offset:1152
.LBB0_746:
	s_or_b64 exec, exec, s[2:3]
	s_waitcnt vmcnt(12)
	v_mul_f32_e32 v39, v1, v39
	v_fmac_f32_e32 v39, v0, v38
	v_fmac_f32_e32 v39, v2, v40
	v_fmac_f32_e32 v39, v3, v41
	s_waitcnt lgkmcnt(0)
	s_nop 1
	v_add_f32_dpp v38, v39, v39 quad_perm:[1,0,3,2] row_mask:0xf bank_mask:0xf
	s_waitcnt lgkmcnt(0)
	s_nop 1
	v_add_f32_dpp v38, v38, v38 quad_perm:[2,3,0,1] row_mask:0xf bank_mask:0xf
	s_waitcnt lgkmcnt(0)
	s_nop 1
	v_add_f32_dpp v38, v38, v38 row_half_mirror row_mask:0xf bank_mask:0xf
	s_waitcnt lgkmcnt(0)
	s_nop 1
	v_add_f32_dpp v38, v38, v38 row_mirror row_mask:0xf bank_mask:0xf
	ds_bpermute_b32 v39, v108, v38
	s_and_saveexec_b64 s[2:3], s[44:45]
	s_cbranch_execz .LBB0_748
	s_waitcnt lgkmcnt(0)
	v_add_f32_e32 v38, v38, v39
	ds_write_b32 v102, v38 offset:1216
.LBB0_748:
	s_or_b64 exec, exec, s[2:3]
	s_waitcnt vmcnt(11)
	v_mul_f32_e32 v35, v1, v35
	v_fmac_f32_e32 v35, v0, v34
	v_fmac_f32_e32 v35, v2, v36
	v_fmac_f32_e32 v35, v3, v37
	s_waitcnt lgkmcnt(0)
	s_nop 1
	v_add_f32_dpp v34, v35, v35 quad_perm:[1,0,3,2] row_mask:0xf bank_mask:0xf
	s_waitcnt lgkmcnt(0)
	s_nop 1
	v_add_f32_dpp v34, v34, v34 quad_perm:[2,3,0,1] row_mask:0xf bank_mask:0xf
	s_waitcnt lgkmcnt(0)
	s_nop 1
	v_add_f32_dpp v34, v34, v34 row_half_mirror row_mask:0xf bank_mask:0xf
	s_waitcnt lgkmcnt(0)
	s_nop 1
	v_add_f32_dpp v34, v34, v34 row_mirror row_mask:0xf bank_mask:0xf
	ds_bpermute_b32 v35, v108, v34
	s_and_saveexec_b64 s[2:3], s[44:45]
	s_cbranch_execz .LBB0_750
	s_waitcnt lgkmcnt(0)
	v_add_f32_e32 v34, v34, v35
	ds_write_b32 v102, v34 offset:1280
.LBB0_750:
	s_or_b64 exec, exec, s[2:3]
	s_waitcnt vmcnt(10)
	v_mul_f32_e32 v25, v1, v25
	v_fmac_f32_e32 v25, v0, v24
	v_fmac_f32_e32 v25, v2, v26
	v_fmac_f32_e32 v25, v3, v27
	s_waitcnt lgkmcnt(0)
	s_nop 1
	v_add_f32_dpp v24, v25, v25 quad_perm:[1,0,3,2] row_mask:0xf bank_mask:0xf
	s_waitcnt lgkmcnt(0)
	s_nop 1
	v_add_f32_dpp v24, v24, v24 quad_perm:[2,3,0,1] row_mask:0xf bank_mask:0xf
	s_waitcnt lgkmcnt(0)
	s_nop 1
	v_add_f32_dpp v24, v24, v24 row_half_mirror row_mask:0xf bank_mask:0xf
	s_waitcnt lgkmcnt(0)
	s_nop 1
	v_add_f32_dpp v24, v24, v24 row_mirror row_mask:0xf bank_mask:0xf
	ds_bpermute_b32 v25, v108, v24
	s_and_saveexec_b64 s[2:3], s[44:45]
	s_cbranch_execz .LBB0_752
	s_waitcnt lgkmcnt(0)
	v_add_f32_e32 v24, v24, v25
	ds_write_b32 v102, v24 offset:1344
.LBB0_752:
	s_or_b64 exec, exec, s[2:3]
	s_waitcnt vmcnt(9)
	v_mul_f32_e32 v17, v1, v17
	v_fmac_f32_e32 v17, v0, v16
	v_fmac_f32_e32 v17, v2, v18
	v_fmac_f32_e32 v17, v3, v19
	s_waitcnt lgkmcnt(0)
	s_nop 1
	v_add_f32_dpp v16, v17, v17 quad_perm:[1,0,3,2] row_mask:0xf bank_mask:0xf
	s_waitcnt lgkmcnt(0)
	s_nop 1
	v_add_f32_dpp v16, v16, v16 quad_perm:[2,3,0,1] row_mask:0xf bank_mask:0xf
	s_waitcnt lgkmcnt(0)
	s_nop 1
	v_add_f32_dpp v16, v16, v16 row_half_mirror row_mask:0xf bank_mask:0xf
	s_waitcnt lgkmcnt(0)
	s_nop 1
	v_add_f32_dpp v16, v16, v16 row_mirror row_mask:0xf bank_mask:0xf
	ds_bpermute_b32 v17, v108, v16
	s_and_saveexec_b64 s[2:3], s[44:45]
	s_cbranch_execz .LBB0_754
	s_waitcnt lgkmcnt(0)
	v_add_f32_e32 v16, v16, v17
	ds_write_b32 v102, v16 offset:1408
.LBB0_754:
	s_or_b64 exec, exec, s[2:3]
	s_waitcnt vmcnt(8)
	v_mul_f32_e32 v9, v1, v9
	v_fmac_f32_e32 v9, v0, v8
	v_fmac_f32_e32 v9, v2, v10
	v_fmac_f32_e32 v9, v3, v11
	s_waitcnt lgkmcnt(0)
	s_nop 1
	v_add_f32_dpp v8, v9, v9 quad_perm:[1,0,3,2] row_mask:0xf bank_mask:0xf
	s_waitcnt lgkmcnt(0)
	s_nop 1
	v_add_f32_dpp v8, v8, v8 quad_perm:[2,3,0,1] row_mask:0xf bank_mask:0xf
	s_waitcnt lgkmcnt(0)
	s_nop 1
	v_add_f32_dpp v8, v8, v8 row_half_mirror row_mask:0xf bank_mask:0xf
	s_waitcnt lgkmcnt(0)
	s_nop 1
	v_add_f32_dpp v8, v8, v8 row_mirror row_mask:0xf bank_mask:0xf
	ds_bpermute_b32 v9, v108, v8
	s_and_saveexec_b64 s[2:3], s[44:45]
	s_cbranch_execz .LBB0_756
	s_waitcnt lgkmcnt(0)
	v_add_f32_e32 v8, v8, v9
	ds_write_b32 v102, v8 offset:1472
.LBB0_756:
	s_or_b64 exec, exec, s[2:3]
	ds_read_b32 v8, v33 offset:680
	s_waitcnt vmcnt(7)
	v_mul_f32_e32 v67, v1, v67
	v_fmac_f32_e32 v67, v0, v66
	v_fmac_f32_e32 v67, v2, v68
	v_fmac_f32_e32 v67, v3, v69
	s_waitcnt lgkmcnt(0)
	v_lshl_add_u32 v8, v8, 7, v82
	v_ashrrev_i32_e32 v9, 31, v8
	v_lshlrev_b64 v[8:9], 11, v[8:9]
	v_lshl_add_u64 v[8:9], v[74:75], 0, v[8:9]
	v_add_co_u32_e32 v10, vcc, 0x8000, v8
	s_nop 0
	v_addc_co_u32_e32 v11, vcc, 0, v9, vcc
	global_load_dwordx4 v[62:65], v[8:9], off
	global_load_dwordx4 v[54:57], v[10:11], off
	v_add_co_u32_e32 v10, vcc, 0x10000, v8
	s_waitcnt lgkmcnt(0)
	s_nop 1
	v_add_f32_dpp v66, v67, v67 quad_perm:[1,0,3,2] row_mask:0xf bank_mask:0xf
	v_addc_co_u32_e32 v11, vcc, 0, v9, vcc
	v_add_co_u32_e32 v16, vcc, 0x18000, v8
	s_nop 0
	v_addc_co_u32_e32 v17, vcc, 0, v9, vcc
	global_load_dwordx4 v[46:49], v[10:11], off
	global_load_dwordx4 v[38:41], v[16:17], off
	v_add_co_u32_e32 v10, vcc, s12, v8
	s_waitcnt lgkmcnt(0)
	s_nop 1
	v_add_f32_dpp v66, v66, v66 quad_perm:[2,3,0,1] row_mask:0xf bank_mask:0xf
	v_addc_co_u32_e32 v11, vcc, 0, v9, vcc
	v_add_co_u32_e32 v16, vcc, 0x28000, v8
	s_nop 0
	v_addc_co_u32_e32 v17, vcc, 0, v9, vcc
	global_load_dwordx4 v[34:37], v[10:11], off
	global_load_dwordx4 v[24:27], v[16:17], off
	v_add_co_u32_e32 v10, vcc, 0x30000, v8
	s_waitcnt lgkmcnt(0)
	s_nop 1
	v_add_f32_dpp v66, v66, v66 row_half_mirror row_mask:0xf bank_mask:0xf
	v_addc_co_u32_e32 v11, vcc, 0, v9, vcc
	v_add_co_u32_e32 v8, vcc, 0x38000, v8
	s_nop 0
	v_addc_co_u32_e32 v9, vcc, 0, v9, vcc
	global_load_dwordx4 v[16:19], v[10:11], off
	s_nop 0
	global_load_dwordx4 v[8:11], v[8:9], off
	s_waitcnt lgkmcnt(0)
	s_nop 1
	v_add_f32_dpp v66, v66, v66 row_mirror row_mask:0xf bank_mask:0xf
	ds_bpermute_b32 v67, v108, v66
	s_and_saveexec_b64 s[2:3], s[44:45]
	s_cbranch_execz .LBB0_758
	s_waitcnt lgkmcnt(0)
	v_add_f32_e32 v66, v66, v67
	ds_write_b32 v102, v66 offset:1536
.LBB0_758:
	s_or_b64 exec, exec, s[2:3]
	s_waitcnt vmcnt(14)
	v_mul_f32_e32 v59, v1, v59
	v_fmac_f32_e32 v59, v0, v58
	v_fmac_f32_e32 v59, v2, v60
	v_fmac_f32_e32 v59, v3, v61
	s_waitcnt lgkmcnt(0)
	s_nop 1
	v_add_f32_dpp v58, v59, v59 quad_perm:[1,0,3,2] row_mask:0xf bank_mask:0xf
	s_waitcnt lgkmcnt(0)
	s_nop 1
	v_add_f32_dpp v58, v58, v58 quad_perm:[2,3,0,1] row_mask:0xf bank_mask:0xf
	s_waitcnt lgkmcnt(0)
	s_nop 1
	v_add_f32_dpp v58, v58, v58 row_half_mirror row_mask:0xf bank_mask:0xf
	s_waitcnt lgkmcnt(0)
	s_nop 1
	v_add_f32_dpp v58, v58, v58 row_mirror row_mask:0xf bank_mask:0xf
	ds_bpermute_b32 v59, v108, v58
	s_and_saveexec_b64 s[2:3], s[44:45]
	s_cbranch_execz .LBB0_760
	s_waitcnt lgkmcnt(0)
	v_add_f32_e32 v58, v58, v59
	ds_write_b32 v102, v58 offset:1600
.LBB0_760:
	s_or_b64 exec, exec, s[2:3]
	s_waitcnt vmcnt(13)
	v_mul_f32_e32 v51, v1, v51
	v_fmac_f32_e32 v51, v0, v50
	v_fmac_f32_e32 v51, v2, v52
	v_fmac_f32_e32 v51, v3, v53
	s_waitcnt lgkmcnt(0)
	s_nop 1
	v_add_f32_dpp v50, v51, v51 quad_perm:[1,0,3,2] row_mask:0xf bank_mask:0xf
	s_waitcnt lgkmcnt(0)
	s_nop 1
	v_add_f32_dpp v50, v50, v50 quad_perm:[2,3,0,1] row_mask:0xf bank_mask:0xf
	s_waitcnt lgkmcnt(0)
	s_nop 1
	v_add_f32_dpp v50, v50, v50 row_half_mirror row_mask:0xf bank_mask:0xf
	s_waitcnt lgkmcnt(0)
	s_nop 1
	v_add_f32_dpp v50, v50, v50 row_mirror row_mask:0xf bank_mask:0xf
	ds_bpermute_b32 v51, v108, v50
	s_and_saveexec_b64 s[2:3], s[44:45]
	s_cbranch_execz .LBB0_762
	s_waitcnt lgkmcnt(0)
	v_add_f32_e32 v50, v50, v51
	ds_write_b32 v102, v50 offset:1664
.LBB0_762:
	s_or_b64 exec, exec, s[2:3]
	s_waitcnt vmcnt(12)
	v_mul_f32_e32 v43, v1, v43
	v_fmac_f32_e32 v43, v0, v42
	v_fmac_f32_e32 v43, v2, v44
	v_fmac_f32_e32 v43, v3, v45
	s_waitcnt lgkmcnt(0)
	s_nop 1
	v_add_f32_dpp v42, v43, v43 quad_perm:[1,0,3,2] row_mask:0xf bank_mask:0xf
	s_waitcnt lgkmcnt(0)
	s_nop 1
	v_add_f32_dpp v42, v42, v42 quad_perm:[2,3,0,1] row_mask:0xf bank_mask:0xf
	s_waitcnt lgkmcnt(0)
	s_nop 1
	v_add_f32_dpp v42, v42, v42 row_half_mirror row_mask:0xf bank_mask:0xf
	s_waitcnt lgkmcnt(0)
	s_nop 1
	v_add_f32_dpp v42, v42, v42 row_mirror row_mask:0xf bank_mask:0xf
	ds_bpermute_b32 v43, v108, v42
	s_and_saveexec_b64 s[2:3], s[44:45]
	s_cbranch_execz .LBB0_764
	s_waitcnt lgkmcnt(0)
	v_add_f32_e32 v42, v42, v43
	ds_write_b32 v102, v42 offset:1728
.LBB0_764:
	s_or_b64 exec, exec, s[2:3]
	s_waitcnt vmcnt(11)
	v_mul_f32_e32 v29, v1, v29
	v_fmac_f32_e32 v29, v0, v28
	v_fmac_f32_e32 v29, v2, v30
	v_fmac_f32_e32 v29, v3, v31
	s_waitcnt lgkmcnt(0)
	s_nop 1
	v_add_f32_dpp v28, v29, v29 quad_perm:[1,0,3,2] row_mask:0xf bank_mask:0xf
	s_waitcnt lgkmcnt(0)
	s_nop 1
	v_add_f32_dpp v28, v28, v28 quad_perm:[2,3,0,1] row_mask:0xf bank_mask:0xf
	s_waitcnt lgkmcnt(0)
	s_nop 1
	v_add_f32_dpp v28, v28, v28 row_half_mirror row_mask:0xf bank_mask:0xf
	s_waitcnt lgkmcnt(0)
	s_nop 1
	v_add_f32_dpp v28, v28, v28 row_mirror row_mask:0xf bank_mask:0xf
	ds_bpermute_b32 v29, v108, v28
	s_and_saveexec_b64 s[2:3], s[44:45]
	s_cbranch_execz .LBB0_766
	s_waitcnt lgkmcnt(0)
	v_add_f32_e32 v28, v28, v29
	ds_write_b32 v102, v28 offset:1792
.LBB0_766:
	s_or_b64 exec, exec, s[2:3]
	s_waitcnt vmcnt(10)
	v_mul_f32_e32 v21, v1, v21
	v_fmac_f32_e32 v21, v0, v20
	v_fmac_f32_e32 v21, v2, v22
	v_fmac_f32_e32 v21, v3, v23
	s_waitcnt lgkmcnt(0)
	s_nop 1
	v_add_f32_dpp v20, v21, v21 quad_perm:[1,0,3,2] row_mask:0xf bank_mask:0xf
	s_waitcnt lgkmcnt(0)
	s_nop 1
	v_add_f32_dpp v20, v20, v20 quad_perm:[2,3,0,1] row_mask:0xf bank_mask:0xf
	s_waitcnt lgkmcnt(0)
	s_nop 1
	v_add_f32_dpp v20, v20, v20 row_half_mirror row_mask:0xf bank_mask:0xf
	s_waitcnt lgkmcnt(0)
	s_nop 1
	v_add_f32_dpp v20, v20, v20 row_mirror row_mask:0xf bank_mask:0xf
	ds_bpermute_b32 v21, v108, v20
	s_and_saveexec_b64 s[2:3], s[44:45]
	s_cbranch_execz .LBB0_768
	s_waitcnt lgkmcnt(0)
	v_add_f32_e32 v20, v20, v21
	ds_write_b32 v102, v20 offset:1856
.LBB0_768:
	s_or_b64 exec, exec, s[2:3]
	s_waitcnt vmcnt(9)
	v_mul_f32_e32 v13, v1, v13
	v_fmac_f32_e32 v13, v0, v12
	v_fmac_f32_e32 v13, v2, v14
	v_fmac_f32_e32 v13, v3, v15
	s_waitcnt lgkmcnt(0)
	s_nop 1
	v_add_f32_dpp v12, v13, v13 quad_perm:[1,0,3,2] row_mask:0xf bank_mask:0xf
	s_waitcnt lgkmcnt(0)
	s_nop 1
	v_add_f32_dpp v12, v12, v12 quad_perm:[2,3,0,1] row_mask:0xf bank_mask:0xf
	s_waitcnt lgkmcnt(0)
	s_nop 1
	v_add_f32_dpp v12, v12, v12 row_half_mirror row_mask:0xf bank_mask:0xf
	s_waitcnt lgkmcnt(0)
	s_nop 1
	v_add_f32_dpp v12, v12, v12 row_mirror row_mask:0xf bank_mask:0xf
	ds_bpermute_b32 v13, v108, v12
	s_and_saveexec_b64 s[2:3], s[44:45]
	s_cbranch_execz .LBB0_770
	s_waitcnt lgkmcnt(0)
	v_add_f32_e32 v12, v12, v13
	ds_write_b32 v102, v12 offset:1920
.LBB0_770:
	s_or_b64 exec, exec, s[2:3]
	s_waitcnt vmcnt(8)
	v_mul_f32_e32 v5, v1, v5
	v_fmac_f32_e32 v5, v0, v4
	v_fmac_f32_e32 v5, v2, v6
	v_fmac_f32_e32 v5, v3, v7
	s_waitcnt lgkmcnt(0)
	s_nop 1
	v_add_f32_dpp v4, v5, v5 quad_perm:[1,0,3,2] row_mask:0xf bank_mask:0xf
	s_waitcnt lgkmcnt(0)
	s_nop 1
	v_add_f32_dpp v4, v4, v4 quad_perm:[2,3,0,1] row_mask:0xf bank_mask:0xf
	s_waitcnt lgkmcnt(0)
	s_nop 1
	v_add_f32_dpp v4, v4, v4 row_half_mirror row_mask:0xf bank_mask:0xf
	s_waitcnt lgkmcnt(0)
	s_nop 1
	v_add_f32_dpp v4, v4, v4 row_mirror row_mask:0xf bank_mask:0xf
	ds_bpermute_b32 v5, v108, v4
	s_and_saveexec_b64 s[2:3], s[44:45]
	s_cbranch_execz .LBB0_772
	s_waitcnt lgkmcnt(0)
	v_add_f32_e32 v4, v4, v5
	ds_write_b32 v102, v4 offset:1984
.LBB0_772:
	s_or_b64 exec, exec, s[2:3]
	ds_read_b32 v4, v33 offset:684
	s_waitcnt vmcnt(7)
	v_mul_f32_e32 v63, v1, v63
	v_fmac_f32_e32 v63, v0, v62
	v_fmac_f32_e32 v63, v2, v64
	v_fmac_f32_e32 v63, v3, v65
	s_waitcnt lgkmcnt(0)
	v_lshl_add_u32 v4, v4, 7, v82
	v_ashrrev_i32_e32 v5, 31, v4
	v_lshlrev_b64 v[4:5], 11, v[4:5]
	v_lshl_add_u64 v[4:5], v[74:75], 0, v[4:5]
	v_add_co_u32_e32 v6, vcc, 0x8000, v4
	s_nop 0
	v_addc_co_u32_e32 v7, vcc, 0, v5, vcc
	global_load_dwordx4 v[66:69], v[4:5], off
	global_load_dwordx4 v[58:61], v[6:7], off
	v_add_co_u32_e32 v6, vcc, 0x10000, v4
	s_waitcnt lgkmcnt(0)
	s_nop 1
	v_add_f32_dpp v62, v63, v63 quad_perm:[1,0,3,2] row_mask:0xf bank_mask:0xf
	v_addc_co_u32_e32 v7, vcc, 0, v5, vcc
	v_add_co_u32_e32 v12, vcc, 0x18000, v4
	s_nop 0
	v_addc_co_u32_e32 v13, vcc, 0, v5, vcc
	global_load_dwordx4 v[50:53], v[6:7], off
	global_load_dwordx4 v[42:45], v[12:13], off
	v_add_co_u32_e32 v6, vcc, s12, v4
	s_waitcnt lgkmcnt(0)
	s_nop 1
	v_add_f32_dpp v62, v62, v62 quad_perm:[2,3,0,1] row_mask:0xf bank_mask:0xf
	v_addc_co_u32_e32 v7, vcc, 0, v5, vcc
	v_add_co_u32_e32 v12, vcc, 0x28000, v4
	s_nop 0
	v_addc_co_u32_e32 v13, vcc, 0, v5, vcc
	global_load_dwordx4 v[28:31], v[6:7], off
	global_load_dwordx4 v[20:23], v[12:13], off
	v_add_co_u32_e32 v6, vcc, 0x30000, v4
	s_waitcnt lgkmcnt(0)
	s_nop 1
	v_add_f32_dpp v62, v62, v62 row_half_mirror row_mask:0xf bank_mask:0xf
	v_addc_co_u32_e32 v7, vcc, 0, v5, vcc
	v_add_co_u32_e32 v4, vcc, 0x38000, v4
	s_nop 0
	v_addc_co_u32_e32 v5, vcc, 0, v5, vcc
	global_load_dwordx4 v[12:15], v[6:7], off
	s_nop 0
	global_load_dwordx4 v[4:7], v[4:5], off
	s_waitcnt lgkmcnt(0)
	s_nop 1
	v_add_f32_dpp v62, v62, v62 row_mirror row_mask:0xf bank_mask:0xf
	ds_bpermute_b32 v63, v108, v62
	s_and_saveexec_b64 s[2:3], s[44:45]
	s_cbranch_execz .LBB0_774
	s_waitcnt lgkmcnt(0)
	v_add_f32_e32 v62, v62, v63
	ds_write_b32 v102, v62 offset:2048
.LBB0_774:
	s_or_b64 exec, exec, s[2:3]
	s_waitcnt vmcnt(14)
	v_mul_f32_e32 v55, v1, v55
	v_fmac_f32_e32 v55, v0, v54
	v_fmac_f32_e32 v55, v2, v56
	v_fmac_f32_e32 v55, v3, v57
	s_waitcnt lgkmcnt(0)
	s_nop 1
	v_add_f32_dpp v54, v55, v55 quad_perm:[1,0,3,2] row_mask:0xf bank_mask:0xf
	s_waitcnt lgkmcnt(0)
	s_nop 1
	v_add_f32_dpp v54, v54, v54 quad_perm:[2,3,0,1] row_mask:0xf bank_mask:0xf
	s_waitcnt lgkmcnt(0)
	s_nop 1
	v_add_f32_dpp v54, v54, v54 row_half_mirror row_mask:0xf bank_mask:0xf
	s_waitcnt lgkmcnt(0)
	s_nop 1
	v_add_f32_dpp v54, v54, v54 row_mirror row_mask:0xf bank_mask:0xf
	ds_bpermute_b32 v55, v108, v54
	s_and_saveexec_b64 s[2:3], s[44:45]
	s_cbranch_execz .LBB0_776
	s_waitcnt lgkmcnt(0)
	v_add_f32_e32 v54, v54, v55
	ds_write_b32 v102, v54 offset:2112
.LBB0_776:
	s_or_b64 exec, exec, s[2:3]
	s_waitcnt vmcnt(13)
	v_mul_f32_e32 v47, v1, v47
	v_fmac_f32_e32 v47, v0, v46
	v_fmac_f32_e32 v47, v2, v48
	v_fmac_f32_e32 v47, v3, v49
	s_waitcnt lgkmcnt(0)
	s_nop 1
	v_add_f32_dpp v46, v47, v47 quad_perm:[1,0,3,2] row_mask:0xf bank_mask:0xf
	s_waitcnt lgkmcnt(0)
	s_nop 1
	v_add_f32_dpp v46, v46, v46 quad_perm:[2,3,0,1] row_mask:0xf bank_mask:0xf
	s_waitcnt lgkmcnt(0)
	s_nop 1
	v_add_f32_dpp v46, v46, v46 row_half_mirror row_mask:0xf bank_mask:0xf
	s_waitcnt lgkmcnt(0)
	s_nop 1
	v_add_f32_dpp v46, v46, v46 row_mirror row_mask:0xf bank_mask:0xf
	ds_bpermute_b32 v47, v108, v46
	s_and_saveexec_b64 s[2:3], s[44:45]
	s_cbranch_execz .LBB0_778
	s_waitcnt lgkmcnt(0)
	v_add_f32_e32 v46, v46, v47
	ds_write_b32 v102, v46 offset:2176
.LBB0_778:
	s_or_b64 exec, exec, s[2:3]
	s_waitcnt vmcnt(12)
	v_mul_f32_e32 v39, v1, v39
	v_fmac_f32_e32 v39, v0, v38
	v_fmac_f32_e32 v39, v2, v40
	v_fmac_f32_e32 v39, v3, v41
	s_waitcnt lgkmcnt(0)
	s_nop 1
	v_add_f32_dpp v38, v39, v39 quad_perm:[1,0,3,2] row_mask:0xf bank_mask:0xf
	s_waitcnt lgkmcnt(0)
	s_nop 1
	v_add_f32_dpp v38, v38, v38 quad_perm:[2,3,0,1] row_mask:0xf bank_mask:0xf
	s_waitcnt lgkmcnt(0)
	s_nop 1
	v_add_f32_dpp v38, v38, v38 row_half_mirror row_mask:0xf bank_mask:0xf
	s_waitcnt lgkmcnt(0)
	s_nop 1
	v_add_f32_dpp v38, v38, v38 row_mirror row_mask:0xf bank_mask:0xf
	ds_bpermute_b32 v39, v108, v38
	s_and_saveexec_b64 s[2:3], s[44:45]
	s_cbranch_execz .LBB0_780
	s_waitcnt lgkmcnt(0)
	v_add_f32_e32 v38, v38, v39
	ds_write_b32 v102, v38 offset:2240
.LBB0_780:
	s_or_b64 exec, exec, s[2:3]
	s_waitcnt vmcnt(11)
	v_mul_f32_e32 v35, v1, v35
	v_fmac_f32_e32 v35, v0, v34
	v_fmac_f32_e32 v35, v2, v36
	v_fmac_f32_e32 v35, v3, v37
	s_waitcnt lgkmcnt(0)
	s_nop 1
	v_add_f32_dpp v34, v35, v35 quad_perm:[1,0,3,2] row_mask:0xf bank_mask:0xf
	s_waitcnt lgkmcnt(0)
	s_nop 1
	v_add_f32_dpp v34, v34, v34 quad_perm:[2,3,0,1] row_mask:0xf bank_mask:0xf
	s_waitcnt lgkmcnt(0)
	s_nop 1
	v_add_f32_dpp v34, v34, v34 row_half_mirror row_mask:0xf bank_mask:0xf
	s_waitcnt lgkmcnt(0)
	s_nop 1
	v_add_f32_dpp v34, v34, v34 row_mirror row_mask:0xf bank_mask:0xf
	ds_bpermute_b32 v35, v108, v34
	s_and_saveexec_b64 s[2:3], s[44:45]
	s_cbranch_execz .LBB0_782
	s_waitcnt lgkmcnt(0)
	v_add_f32_e32 v34, v34, v35
	ds_write_b32 v102, v34 offset:2304
.LBB0_782:
	s_or_b64 exec, exec, s[2:3]
	s_waitcnt vmcnt(10)
	v_mul_f32_e32 v25, v1, v25
	v_fmac_f32_e32 v25, v0, v24
	v_fmac_f32_e32 v25, v2, v26
	v_fmac_f32_e32 v25, v3, v27
	s_waitcnt lgkmcnt(0)
	s_nop 1
	v_add_f32_dpp v24, v25, v25 quad_perm:[1,0,3,2] row_mask:0xf bank_mask:0xf
	s_waitcnt lgkmcnt(0)
	s_nop 1
	v_add_f32_dpp v24, v24, v24 quad_perm:[2,3,0,1] row_mask:0xf bank_mask:0xf
	s_waitcnt lgkmcnt(0)
	s_nop 1
	v_add_f32_dpp v24, v24, v24 row_half_mirror row_mask:0xf bank_mask:0xf
	s_waitcnt lgkmcnt(0)
	s_nop 1
	v_add_f32_dpp v24, v24, v24 row_mirror row_mask:0xf bank_mask:0xf
	ds_bpermute_b32 v25, v108, v24
	s_and_saveexec_b64 s[2:3], s[44:45]
	s_cbranch_execz .LBB0_784
	s_waitcnt lgkmcnt(0)
	v_add_f32_e32 v24, v24, v25
	ds_write_b32 v102, v24 offset:2368
.LBB0_784:
	s_or_b64 exec, exec, s[2:3]
	s_waitcnt vmcnt(9)
	v_mul_f32_e32 v17, v1, v17
	v_fmac_f32_e32 v17, v0, v16
	v_fmac_f32_e32 v17, v2, v18
	v_fmac_f32_e32 v17, v3, v19
	s_waitcnt lgkmcnt(0)
	s_nop 1
	v_add_f32_dpp v16, v17, v17 quad_perm:[1,0,3,2] row_mask:0xf bank_mask:0xf
	s_waitcnt lgkmcnt(0)
	s_nop 1
	v_add_f32_dpp v16, v16, v16 quad_perm:[2,3,0,1] row_mask:0xf bank_mask:0xf
	s_waitcnt lgkmcnt(0)
	s_nop 1
	v_add_f32_dpp v16, v16, v16 row_half_mirror row_mask:0xf bank_mask:0xf
	s_waitcnt lgkmcnt(0)
	s_nop 1
	v_add_f32_dpp v16, v16, v16 row_mirror row_mask:0xf bank_mask:0xf
	ds_bpermute_b32 v17, v108, v16
	s_and_saveexec_b64 s[2:3], s[44:45]
	s_cbranch_execz .LBB0_786
	s_waitcnt lgkmcnt(0)
	v_add_f32_e32 v16, v16, v17
	ds_write_b32 v102, v16 offset:2432
.LBB0_786:
	s_or_b64 exec, exec, s[2:3]
	s_waitcnt vmcnt(8)
	v_mul_f32_e32 v9, v1, v9
	v_fmac_f32_e32 v9, v0, v8
	v_fmac_f32_e32 v9, v2, v10
	v_fmac_f32_e32 v9, v3, v11
	s_waitcnt lgkmcnt(0)
	s_nop 1
	v_add_f32_dpp v8, v9, v9 quad_perm:[1,0,3,2] row_mask:0xf bank_mask:0xf
	s_waitcnt lgkmcnt(0)
	s_nop 1
	v_add_f32_dpp v8, v8, v8 quad_perm:[2,3,0,1] row_mask:0xf bank_mask:0xf
	s_waitcnt lgkmcnt(0)
	s_nop 1
	v_add_f32_dpp v8, v8, v8 row_half_mirror row_mask:0xf bank_mask:0xf
	s_waitcnt lgkmcnt(0)
	s_nop 1
	v_add_f32_dpp v8, v8, v8 row_mirror row_mask:0xf bank_mask:0xf
	ds_bpermute_b32 v9, v108, v8
	s_and_saveexec_b64 s[2:3], s[44:45]
	s_cbranch_execz .LBB0_788
	s_waitcnt lgkmcnt(0)
	v_add_f32_e32 v8, v8, v9
	ds_write_b32 v102, v8 offset:2496
.LBB0_788:
	s_or_b64 exec, exec, s[2:3]
	ds_read_b32 v8, v33 offset:688
	s_waitcnt vmcnt(7)
	v_mul_f32_e32 v46, v1, v67
	v_fmac_f32_e32 v46, v0, v66
	v_fmac_f32_e32 v46, v2, v68
	v_fmac_f32_e32 v46, v3, v69
	s_waitcnt lgkmcnt(0)
	v_lshl_add_u32 v8, v8, 7, v82
	v_ashrrev_i32_e32 v9, 31, v8
	v_lshlrev_b64 v[8:9], 11, v[8:9]
	v_lshl_add_u64 v[8:9], v[74:75], 0, v[8:9]
	v_add_co_u32_e32 v10, vcc, 0x8000, v8
	s_nop 0
	v_addc_co_u32_e32 v11, vcc, 0, v9, vcc
	global_load_dwordx4 v[78:81], v[8:9], off
	global_load_dwordx4 v[70:73], v[10:11], off
	v_add_co_u32_e32 v10, vcc, 0x10000, v8
	s_waitcnt lgkmcnt(0)
	s_nop 1
	v_add_f32_dpp v46, v46, v46 quad_perm:[1,0,3,2] row_mask:0xf bank_mask:0xf
	v_addc_co_u32_e32 v11, vcc, 0, v9, vcc
	v_add_co_u32_e32 v16, vcc, 0x18000, v8
	s_nop 0
	v_addc_co_u32_e32 v17, vcc, 0, v9, vcc
	global_load_dwordx4 v[62:65], v[10:11], off
	global_load_dwordx4 v[38:41], v[16:17], off
	v_add_co_u32_e32 v10, vcc, s12, v8
	s_waitcnt lgkmcnt(0)
	s_nop 1
	v_add_f32_dpp v46, v46, v46 quad_perm:[2,3,0,1] row_mask:0xf bank_mask:0xf
	v_addc_co_u32_e32 v11, vcc, 0, v9, vcc
	v_add_co_u32_e32 v16, vcc, 0x28000, v8
	s_nop 0
	v_addc_co_u32_e32 v17, vcc, 0, v9, vcc
	global_load_dwordx4 v[34:37], v[10:11], off
	global_load_dwordx4 v[24:27], v[16:17], off
	v_add_co_u32_e32 v10, vcc, 0x30000, v8
	s_waitcnt lgkmcnt(0)
	s_nop 1
	v_add_f32_dpp v46, v46, v46 row_half_mirror row_mask:0xf bank_mask:0xf
	v_addc_co_u32_e32 v11, vcc, 0, v9, vcc
	v_add_co_u32_e32 v8, vcc, 0x38000, v8
	s_nop 0
	v_addc_co_u32_e32 v9, vcc, 0, v9, vcc
	global_load_dwordx4 v[16:19], v[10:11], off
	s_nop 0
	global_load_dwordx4 v[8:11], v[8:9], off
	s_waitcnt lgkmcnt(0)
	s_nop 1
	v_add_f32_dpp v46, v46, v46 row_mirror row_mask:0xf bank_mask:0xf
	ds_bpermute_b32 v47, v108, v46
	s_and_saveexec_b64 s[2:3], s[44:45]
	s_cbranch_execz .LBB0_790
	s_waitcnt lgkmcnt(0)
	v_add_f32_e32 v46, v46, v47
	ds_write_b32 v102, v46 offset:2560
.LBB0_790:
	s_or_b64 exec, exec, s[2:3]
	s_waitcnt vmcnt(14)
	v_mul_f32_e32 v46, v1, v59
	v_fmac_f32_e32 v46, v0, v58
	v_fmac_f32_e32 v46, v2, v60
	v_fmac_f32_e32 v46, v3, v61
	s_waitcnt lgkmcnt(0)
	s_waitcnt lgkmcnt(0)
	s_nop 1
	v_add_f32_dpp v46, v46, v46 quad_perm:[1,0,3,2] row_mask:0xf bank_mask:0xf
	s_waitcnt lgkmcnt(0)
	s_nop 1
	v_add_f32_dpp v46, v46, v46 quad_perm:[2,3,0,1] row_mask:0xf bank_mask:0xf
	s_waitcnt lgkmcnt(0)
	s_nop 1
	v_add_f32_dpp v46, v46, v46 row_half_mirror row_mask:0xf bank_mask:0xf
	s_waitcnt lgkmcnt(0)
	s_nop 1
	v_add_f32_dpp v46, v46, v46 row_mirror row_mask:0xf bank_mask:0xf
	ds_bpermute_b32 v47, v108, v46
	s_and_saveexec_b64 s[2:3], s[44:45]
	s_cbranch_execz .LBB0_792
	s_waitcnt lgkmcnt(0)
	v_add_f32_e32 v46, v46, v47
	ds_write_b32 v102, v46 offset:2624
.LBB0_792:
	s_or_b64 exec, exec, s[2:3]
	s_waitcnt vmcnt(13)
	v_mul_f32_e32 v46, v1, v51
	v_fmac_f32_e32 v46, v0, v50
	v_fmac_f32_e32 v46, v2, v52
	v_fmac_f32_e32 v46, v3, v53
	s_waitcnt lgkmcnt(0)
	s_waitcnt lgkmcnt(0)
	s_nop 1
	v_add_f32_dpp v46, v46, v46 quad_perm:[1,0,3,2] row_mask:0xf bank_mask:0xf
	s_waitcnt lgkmcnt(0)
	s_nop 1
	v_add_f32_dpp v46, v46, v46 quad_perm:[2,3,0,1] row_mask:0xf bank_mask:0xf
	s_waitcnt lgkmcnt(0)
	s_nop 1
	v_add_f32_dpp v46, v46, v46 row_half_mirror row_mask:0xf bank_mask:0xf
	s_waitcnt lgkmcnt(0)
	s_nop 1
	v_add_f32_dpp v46, v46, v46 row_mirror row_mask:0xf bank_mask:0xf
	ds_bpermute_b32 v47, v108, v46
	s_and_saveexec_b64 s[2:3], s[44:45]
	s_cbranch_execz .LBB0_794
	s_waitcnt lgkmcnt(0)
	v_add_f32_e32 v46, v46, v47
	ds_write_b32 v102, v46 offset:2688
.LBB0_794:
	s_or_b64 exec, exec, s[2:3]
	s_waitcnt vmcnt(12)
	v_mul_f32_e32 v43, v1, v43
	v_fmac_f32_e32 v43, v0, v42
	v_fmac_f32_e32 v43, v2, v44
	v_fmac_f32_e32 v43, v3, v45
	s_waitcnt lgkmcnt(0)
	s_nop 1
	v_add_f32_dpp v42, v43, v43 quad_perm:[1,0,3,2] row_mask:0xf bank_mask:0xf
	s_waitcnt lgkmcnt(0)
	s_nop 1
	v_add_f32_dpp v42, v42, v42 quad_perm:[2,3,0,1] row_mask:0xf bank_mask:0xf
	s_waitcnt lgkmcnt(0)
	s_nop 1
	v_add_f32_dpp v42, v42, v42 row_half_mirror row_mask:0xf bank_mask:0xf
	s_waitcnt lgkmcnt(0)
	s_nop 1
	v_add_f32_dpp v42, v42, v42 row_mirror row_mask:0xf bank_mask:0xf
	ds_bpermute_b32 v43, v108, v42
	s_and_saveexec_b64 s[2:3], s[44:45]
	s_cbranch_execz .LBB0_796
	s_waitcnt lgkmcnt(0)
	v_add_f32_e32 v42, v42, v43
	ds_write_b32 v102, v42 offset:2752
.LBB0_796:
	s_or_b64 exec, exec, s[2:3]
	s_waitcnt vmcnt(11)
	v_mul_f32_e32 v29, v1, v29
	v_fmac_f32_e32 v29, v0, v28
	v_fmac_f32_e32 v29, v2, v30
	v_fmac_f32_e32 v29, v3, v31
	s_waitcnt lgkmcnt(0)
	s_nop 1
	v_add_f32_dpp v28, v29, v29 quad_perm:[1,0,3,2] row_mask:0xf bank_mask:0xf
	s_waitcnt lgkmcnt(0)
	s_nop 1
	v_add_f32_dpp v28, v28, v28 quad_perm:[2,3,0,1] row_mask:0xf bank_mask:0xf
	s_waitcnt lgkmcnt(0)
	s_nop 1
	v_add_f32_dpp v28, v28, v28 row_half_mirror row_mask:0xf bank_mask:0xf
	s_waitcnt lgkmcnt(0)
	s_nop 1
	v_add_f32_dpp v28, v28, v28 row_mirror row_mask:0xf bank_mask:0xf
	ds_bpermute_b32 v29, v108, v28
	s_and_saveexec_b64 s[2:3], s[44:45]
	s_cbranch_execz .LBB0_798
	s_waitcnt lgkmcnt(0)
	v_add_f32_e32 v28, v28, v29
	ds_write_b32 v102, v28 offset:2816
.LBB0_798:
	s_or_b64 exec, exec, s[2:3]
	s_waitcnt vmcnt(10)
	v_mul_f32_e32 v21, v1, v21
	v_fmac_f32_e32 v21, v0, v20
	v_fmac_f32_e32 v21, v2, v22
	v_fmac_f32_e32 v21, v3, v23
	s_waitcnt lgkmcnt(0)
	s_nop 1
	v_add_f32_dpp v20, v21, v21 quad_perm:[1,0,3,2] row_mask:0xf bank_mask:0xf
	s_waitcnt lgkmcnt(0)
	s_nop 1
	v_add_f32_dpp v20, v20, v20 quad_perm:[2,3,0,1] row_mask:0xf bank_mask:0xf
	s_waitcnt lgkmcnt(0)
	s_nop 1
	v_add_f32_dpp v20, v20, v20 row_half_mirror row_mask:0xf bank_mask:0xf
	s_waitcnt lgkmcnt(0)
	s_nop 1
	v_add_f32_dpp v20, v20, v20 row_mirror row_mask:0xf bank_mask:0xf
	ds_bpermute_b32 v21, v108, v20
	s_and_saveexec_b64 s[2:3], s[44:45]
	s_cbranch_execz .LBB0_800
	s_waitcnt lgkmcnt(0)
	v_add_f32_e32 v20, v20, v21
	ds_write_b32 v102, v20 offset:2880
.LBB0_800:
	s_or_b64 exec, exec, s[2:3]
	s_waitcnt vmcnt(9)
	v_mul_f32_e32 v13, v1, v13
	v_fmac_f32_e32 v13, v0, v12
	v_fmac_f32_e32 v13, v2, v14
	v_fmac_f32_e32 v13, v3, v15
	s_waitcnt lgkmcnt(0)
	s_nop 1
	v_add_f32_dpp v12, v13, v13 quad_perm:[1,0,3,2] row_mask:0xf bank_mask:0xf
	s_waitcnt lgkmcnt(0)
	s_nop 1
	v_add_f32_dpp v12, v12, v12 quad_perm:[2,3,0,1] row_mask:0xf bank_mask:0xf
	s_waitcnt lgkmcnt(0)
	s_nop 1
	v_add_f32_dpp v12, v12, v12 row_half_mirror row_mask:0xf bank_mask:0xf
	s_waitcnt lgkmcnt(0)
	s_nop 1
	v_add_f32_dpp v12, v12, v12 row_mirror row_mask:0xf bank_mask:0xf
	ds_bpermute_b32 v13, v108, v12
	s_and_saveexec_b64 s[2:3], s[44:45]
	s_cbranch_execz .LBB0_802
	s_waitcnt lgkmcnt(0)
	v_add_f32_e32 v12, v12, v13
	ds_write_b32 v102, v12 offset:2944
.LBB0_802:
	s_or_b64 exec, exec, s[2:3]
	s_waitcnt vmcnt(8)
	v_mul_f32_e32 v5, v1, v5
	v_fmac_f32_e32 v5, v0, v4
	v_fmac_f32_e32 v5, v2, v6
	v_fmac_f32_e32 v5, v3, v7
	s_waitcnt lgkmcnt(0)
	s_nop 1
	v_add_f32_dpp v4, v5, v5 quad_perm:[1,0,3,2] row_mask:0xf bank_mask:0xf
	s_waitcnt lgkmcnt(0)
	s_nop 1
	v_add_f32_dpp v4, v4, v4 quad_perm:[2,3,0,1] row_mask:0xf bank_mask:0xf
	s_waitcnt lgkmcnt(0)
	s_nop 1
	v_add_f32_dpp v4, v4, v4 row_half_mirror row_mask:0xf bank_mask:0xf
	s_waitcnt lgkmcnt(0)
	s_nop 1
	v_add_f32_dpp v4, v4, v4 row_mirror row_mask:0xf bank_mask:0xf
	ds_bpermute_b32 v5, v108, v4
	s_and_saveexec_b64 s[2:3], s[44:45]
	s_cbranch_execz .LBB0_804
	s_waitcnt lgkmcnt(0)
	v_add_f32_e32 v4, v4, v5
	ds_write_b32 v102, v4 offset:3008
.LBB0_804:
	s_or_b64 exec, exec, s[2:3]
	ds_read_b32 v4, v33 offset:692
	s_waitcnt lgkmcnt(0)
	v_lshl_add_u32 v4, v4, 7, v82
	v_ashrrev_i32_e32 v5, 31, v4
	v_lshlrev_b64 v[4:5], 11, v[4:5]
	v_lshl_add_u64 v[4:5], v[74:75], 0, v[4:5]
	v_add_co_u32_e32 v6, vcc, 0x8000, v4
	s_nop 1
	v_addc_co_u32_e32 v7, vcc, 0, v5, vcc
	global_load_dwordx4 v[74:77], v[4:5], off
	global_load_dwordx4 v[66:69], v[6:7], off
	v_add_co_u32_e32 v6, vcc, 0x10000, v4
	s_nop 1
	v_addc_co_u32_e32 v7, vcc, 0, v5, vcc
	v_add_co_u32_e32 v12, vcc, 0x18000, v4
	s_nop 1
	v_addc_co_u32_e32 v13, vcc, 0, v5, vcc
	global_load_dwordx4 v[58:61], v[6:7], off
	global_load_dwordx4 v[54:57], v[12:13], off
	v_add_co_u32_e32 v6, vcc, s12, v4
	s_nop 1
	v_addc_co_u32_e32 v7, vcc, 0, v5, vcc
	v_add_co_u32_e32 v12, vcc, 0x28000, v4
	s_nop 1
	v_addc_co_u32_e32 v13, vcc, 0, v5, vcc
	global_load_dwordx4 v[50:53], v[6:7], off
	global_load_dwordx4 v[46:49], v[12:13], off
	v_add_co_u32_e32 v6, vcc, 0x30000, v4
	s_waitcnt vmcnt(13)
	v_mul_f32_e32 v12, v1, v79
	v_addc_co_u32_e32 v7, vcc, 0, v5, vcc
	v_add_co_u32_e32 v4, vcc, 0x38000, v4
	v_fmac_f32_e32 v12, v0, v78
	s_nop 0
	v_addc_co_u32_e32 v5, vcc, 0, v5, vcc
	global_load_dwordx4 v[42:45], v[6:7], off
	s_nop 0
	global_load_dwordx4 v[4:7], v[4:5], off
	v_fmac_f32_e32 v12, v2, v80
	v_fmac_f32_e32 v12, v3, v81
	s_waitcnt lgkmcnt(0)
	s_nop 1
	v_add_f32_dpp v12, v12, v12 quad_perm:[1,0,3,2] row_mask:0xf bank_mask:0xf
	s_waitcnt lgkmcnt(0)
	s_nop 1
	v_add_f32_dpp v12, v12, v12 quad_perm:[2,3,0,1] row_mask:0xf bank_mask:0xf
	s_waitcnt lgkmcnt(0)
	s_nop 1
	v_add_f32_dpp v12, v12, v12 row_half_mirror row_mask:0xf bank_mask:0xf
	s_waitcnt lgkmcnt(0)
	s_nop 1
	v_add_f32_dpp v12, v12, v12 row_mirror row_mask:0xf bank_mask:0xf
	ds_bpermute_b32 v13, v108, v12
	s_and_saveexec_b64 s[2:3], s[44:45]
	s_cbranch_execz .LBB0_806
	s_waitcnt lgkmcnt(0)
	v_add_f32_e32 v12, v12, v13
	ds_write_b32 v102, v12 offset:3072
.LBB0_806:
	s_or_b64 exec, exec, s[2:3]
	s_waitcnt vmcnt(14)
	v_mul_f32_e32 v12, v1, v71
	v_fmac_f32_e32 v12, v0, v70
	v_fmac_f32_e32 v12, v2, v72
	v_fmac_f32_e32 v12, v3, v73
	s_waitcnt lgkmcnt(0)
	s_waitcnt lgkmcnt(0)
	s_nop 1
	v_add_f32_dpp v12, v12, v12 quad_perm:[1,0,3,2] row_mask:0xf bank_mask:0xf
	s_waitcnt lgkmcnt(0)
	s_nop 1
	v_add_f32_dpp v12, v12, v12 quad_perm:[2,3,0,1] row_mask:0xf bank_mask:0xf
	s_waitcnt lgkmcnt(0)
	s_nop 1
	v_add_f32_dpp v12, v12, v12 row_half_mirror row_mask:0xf bank_mask:0xf
	s_waitcnt lgkmcnt(0)
	s_nop 1
	v_add_f32_dpp v12, v12, v12 row_mirror row_mask:0xf bank_mask:0xf
	ds_bpermute_b32 v13, v108, v12
	s_and_saveexec_b64 s[2:3], s[44:45]
	s_cbranch_execz .LBB0_808
	s_waitcnt lgkmcnt(0)
	v_add_f32_e32 v12, v12, v13
	ds_write_b32 v102, v12 offset:3136
.LBB0_808:
	s_or_b64 exec, exec, s[2:3]
	s_waitcnt vmcnt(13)
	v_mul_f32_e32 v12, v1, v63
	v_fmac_f32_e32 v12, v0, v62
	v_fmac_f32_e32 v12, v2, v64
	v_fmac_f32_e32 v12, v3, v65
	s_waitcnt lgkmcnt(0)
	s_waitcnt lgkmcnt(0)
	s_nop 1
	v_add_f32_dpp v12, v12, v12 quad_perm:[1,0,3,2] row_mask:0xf bank_mask:0xf
	s_waitcnt lgkmcnt(0)
	s_nop 1
	v_add_f32_dpp v12, v12, v12 quad_perm:[2,3,0,1] row_mask:0xf bank_mask:0xf
	s_waitcnt lgkmcnt(0)
	s_nop 1
	v_add_f32_dpp v12, v12, v12 row_half_mirror row_mask:0xf bank_mask:0xf
	s_waitcnt lgkmcnt(0)
	s_nop 1
	v_add_f32_dpp v12, v12, v12 row_mirror row_mask:0xf bank_mask:0xf
	ds_bpermute_b32 v13, v108, v12
	s_and_saveexec_b64 s[2:3], s[44:45]
	s_cbranch_execz .LBB0_810
	s_waitcnt lgkmcnt(0)
	v_add_f32_e32 v12, v12, v13
	ds_write_b32 v102, v12 offset:3200
.LBB0_810:
	s_or_b64 exec, exec, s[2:3]
	s_waitcnt vmcnt(12)
	v_mul_f32_e32 v12, v1, v39
	v_fmac_f32_e32 v12, v0, v38
	v_fmac_f32_e32 v12, v2, v40
	v_fmac_f32_e32 v12, v3, v41
	s_waitcnt lgkmcnt(0)
	s_waitcnt lgkmcnt(0)
	s_nop 1
	v_add_f32_dpp v12, v12, v12 quad_perm:[1,0,3,2] row_mask:0xf bank_mask:0xf
	s_waitcnt lgkmcnt(0)
	s_nop 1
	v_add_f32_dpp v12, v12, v12 quad_perm:[2,3,0,1] row_mask:0xf bank_mask:0xf
	s_waitcnt lgkmcnt(0)
	s_nop 1
	v_add_f32_dpp v12, v12, v12 row_half_mirror row_mask:0xf bank_mask:0xf
	s_waitcnt lgkmcnt(0)
	s_nop 1
	v_add_f32_dpp v12, v12, v12 row_mirror row_mask:0xf bank_mask:0xf
	ds_bpermute_b32 v13, v108, v12
	s_and_saveexec_b64 s[2:3], s[44:45]
	s_cbranch_execz .LBB0_812
	s_waitcnt lgkmcnt(0)
	v_add_f32_e32 v12, v12, v13
	ds_write_b32 v102, v12 offset:3264
.LBB0_812:
	s_or_b64 exec, exec, s[2:3]
	s_waitcnt vmcnt(11)
	v_mul_f32_e32 v12, v1, v35
	v_fmac_f32_e32 v12, v0, v34
	v_fmac_f32_e32 v12, v2, v36
	v_fmac_f32_e32 v12, v3, v37
	s_waitcnt lgkmcnt(0)
	s_waitcnt lgkmcnt(0)
	s_nop 1
	v_add_f32_dpp v12, v12, v12 quad_perm:[1,0,3,2] row_mask:0xf bank_mask:0xf
	s_waitcnt lgkmcnt(0)
	s_nop 1
	v_add_f32_dpp v12, v12, v12 quad_perm:[2,3,0,1] row_mask:0xf bank_mask:0xf
	s_waitcnt lgkmcnt(0)
	s_nop 1
	v_add_f32_dpp v12, v12, v12 row_half_mirror row_mask:0xf bank_mask:0xf
	s_waitcnt lgkmcnt(0)
	s_nop 1
	v_add_f32_dpp v12, v12, v12 row_mirror row_mask:0xf bank_mask:0xf
	ds_bpermute_b32 v13, v108, v12
	s_and_saveexec_b64 s[2:3], s[44:45]
	s_cbranch_execz .LBB0_814
	s_waitcnt lgkmcnt(0)
	v_add_f32_e32 v12, v12, v13
	ds_write_b32 v102, v12 offset:3328
.LBB0_814:
	s_or_b64 exec, exec, s[2:3]
	s_waitcnt vmcnt(10)
	v_mul_f32_e32 v12, v1, v25
	v_fmac_f32_e32 v12, v0, v24
	v_fmac_f32_e32 v12, v2, v26
	v_fmac_f32_e32 v12, v3, v27
	s_waitcnt lgkmcnt(0)
	s_waitcnt lgkmcnt(0)
	s_nop 1
	v_add_f32_dpp v12, v12, v12 quad_perm:[1,0,3,2] row_mask:0xf bank_mask:0xf
	s_waitcnt lgkmcnt(0)
	s_nop 1
	v_add_f32_dpp v12, v12, v12 quad_perm:[2,3,0,1] row_mask:0xf bank_mask:0xf
	s_waitcnt lgkmcnt(0)
	s_nop 1
	v_add_f32_dpp v12, v12, v12 row_half_mirror row_mask:0xf bank_mask:0xf
	s_waitcnt lgkmcnt(0)
	s_nop 1
	v_add_f32_dpp v12, v12, v12 row_mirror row_mask:0xf bank_mask:0xf
	ds_bpermute_b32 v13, v108, v12
	s_and_saveexec_b64 s[2:3], s[44:45]
	s_cbranch_execz .LBB0_816
	s_waitcnt lgkmcnt(0)
	v_add_f32_e32 v12, v12, v13
	ds_write_b32 v102, v12 offset:3392
.LBB0_816:
	s_or_b64 exec, exec, s[2:3]
	s_waitcnt vmcnt(9)
	v_mul_f32_e32 v12, v1, v17
	v_fmac_f32_e32 v12, v0, v16
	v_fmac_f32_e32 v12, v2, v18
	v_fmac_f32_e32 v12, v3, v19
	s_waitcnt lgkmcnt(0)
	s_waitcnt lgkmcnt(0)
	s_nop 1
	v_add_f32_dpp v12, v12, v12 quad_perm:[1,0,3,2] row_mask:0xf bank_mask:0xf
	s_waitcnt lgkmcnt(0)
	s_nop 1
	v_add_f32_dpp v12, v12, v12 quad_perm:[2,3,0,1] row_mask:0xf bank_mask:0xf
	s_waitcnt lgkmcnt(0)
	s_nop 1
	v_add_f32_dpp v12, v12, v12 row_half_mirror row_mask:0xf bank_mask:0xf
	s_waitcnt lgkmcnt(0)
	s_nop 1
	v_add_f32_dpp v12, v12, v12 row_mirror row_mask:0xf bank_mask:0xf
	ds_bpermute_b32 v13, v108, v12
	s_and_saveexec_b64 s[2:3], s[44:45]
	s_cbranch_execz .LBB0_818
	s_waitcnt lgkmcnt(0)
	v_add_f32_e32 v12, v12, v13
	ds_write_b32 v102, v12 offset:3456
.LBB0_818:
	s_or_b64 exec, exec, s[2:3]
	s_waitcnt vmcnt(8)
	v_mul_f32_e32 v9, v1, v9
	v_fmac_f32_e32 v9, v0, v8
	v_fmac_f32_e32 v9, v2, v10
	v_fmac_f32_e32 v9, v3, v11
	s_waitcnt lgkmcnt(0)
	s_nop 1
	v_add_f32_dpp v8, v9, v9 quad_perm:[1,0,3,2] row_mask:0xf bank_mask:0xf
	s_waitcnt lgkmcnt(0)
	s_nop 1
	v_add_f32_dpp v8, v8, v8 quad_perm:[2,3,0,1] row_mask:0xf bank_mask:0xf
	s_waitcnt lgkmcnt(0)
	s_nop 1
	v_add_f32_dpp v8, v8, v8 row_half_mirror row_mask:0xf bank_mask:0xf
	s_waitcnt lgkmcnt(0)
	s_nop 1
	v_add_f32_dpp v8, v8, v8 row_mirror row_mask:0xf bank_mask:0xf
	ds_bpermute_b32 v9, v108, v8
	s_and_saveexec_b64 s[2:3], s[44:45]
	s_cbranch_execz .LBB0_820
	s_waitcnt lgkmcnt(0)
	v_add_f32_e32 v8, v8, v9
	ds_write_b32 v102, v8 offset:3520
.LBB0_820:
	s_or_b64 exec, exec, s[2:3]
	v_readlane_b32 s72, v251, 1
	v_readlane_b32 s78, v251, 7
	v_readlane_b32 s79, v251, 8
	v_mov_b32_e32 v85, v33
	s_waitcnt vmcnt(7)
	v_mul_f32_e32 v62, v1, v75
	s_waitcnt lgkmcnt(0)
	v_lshl_add_u64 v[8:9], s[78:79], 0, v[94:95]
	v_lshl_add_u64 v[8:9], v[8:9], 0, s[8:9]
	v_lshl_add_u64 v[34:35], v[8:9], 0, v[84:85]
	v_add_co_u32_e32 v12, vcc, 0x8000, v34
	v_fmac_f32_e32 v62, v0, v74
	s_nop 0
	v_addc_co_u32_e32 v13, vcc, 0, v35, vcc
	v_add_co_u32_e32 v16, vcc, 0x10000, v34
	global_load_dwordx4 v[8:11], v[34:35], off
	s_nop 0
	global_load_dwordx4 v[12:15], v[12:13], off
	v_addc_co_u32_e32 v17, vcc, 0, v35, vcc
	v_add_co_u32_e32 v20, vcc, 0x18000, v34
	v_fmac_f32_e32 v62, v2, v76
	s_nop 0
	v_addc_co_u32_e32 v21, vcc, 0, v35, vcc
	v_add_co_u32_e32 v24, vcc, s12, v34
	global_load_dwordx4 v[16:19], v[16:17], off
	s_nop 0
	global_load_dwordx4 v[20:23], v[20:21], off
	v_addc_co_u32_e32 v25, vcc, 0, v35, vcc
	v_add_co_u32_e32 v28, vcc, 0x28000, v34
	v_fmac_f32_e32 v62, v3, v77
	s_nop 0
	v_addc_co_u32_e32 v29, vcc, 0, v35, vcc
	v_add_co_u32_e32 v36, vcc, 0x30000, v34
	global_load_dwordx4 v[24:27], v[24:25], off
	s_nop 0
	global_load_dwordx4 v[28:31], v[28:29], off
	v_addc_co_u32_e32 v37, vcc, 0, v35, vcc
	v_add_co_u32_e32 v38, vcc, 0x38000, v34
	s_nop 0
	v_addc_co_u32_e32 v39, vcc, 0, v35, vcc
	global_load_dwordx4 v[34:37], v[36:37], off
	s_nop 0
	global_load_dwordx4 v[38:41], v[38:39], off
	v_readlane_b32 s73, v251, 2
	s_waitcnt lgkmcnt(0)
	s_nop 1
	v_add_f32_dpp v62, v62, v62 quad_perm:[1,0,3,2] row_mask:0xf bank_mask:0xf
	v_readlane_b32 s74, v251, 3
	v_readlane_b32 s75, v251, 4
	v_readlane_b32 s76, v251, 5
	v_readlane_b32 s77, v251, 6
	s_waitcnt lgkmcnt(0)
	s_nop 1
	v_add_f32_dpp v62, v62, v62 quad_perm:[2,3,0,1] row_mask:0xf bank_mask:0xf
	v_readlane_b32 s80, v251, 9
	v_readlane_b32 s81, v251, 10
	v_readlane_b32 s82, v251, 11
	v_readlane_b32 s83, v251, 12
	s_waitcnt lgkmcnt(0)
	s_nop 1
	v_add_f32_dpp v62, v62, v62 row_half_mirror row_mask:0xf bank_mask:0xf
	v_readlane_b32 s84, v251, 13
	v_readlane_b32 s85, v251, 14
	v_readlane_b32 s86, v251, 15
	v_readlane_b32 s87, v251, 16
	s_waitcnt lgkmcnt(0)
	s_nop 1
	v_add_f32_dpp v62, v62, v62 row_mirror row_mask:0xf bank_mask:0xf
	ds_bpermute_b32 v63, v108, v62
	s_and_saveexec_b64 s[2:3], s[44:45]
	s_cbranch_execz .LBB0_822
	s_waitcnt lgkmcnt(0)
	v_add_f32_e32 v62, v62, v63
	ds_write_b32 v102, v62 offset:3584
.LBB0_822:
	s_or_b64 exec, exec, s[2:3]
	s_waitcnt vmcnt(14)
	v_mul_f32_e32 v62, v1, v67
	v_fmac_f32_e32 v62, v0, v66
	v_fmac_f32_e32 v62, v2, v68
	v_fmac_f32_e32 v62, v3, v69
	s_waitcnt lgkmcnt(0)
	s_waitcnt lgkmcnt(0)
	s_nop 1
	v_add_f32_dpp v62, v62, v62 quad_perm:[1,0,3,2] row_mask:0xf bank_mask:0xf
	s_waitcnt lgkmcnt(0)
	s_nop 1
	v_add_f32_dpp v62, v62, v62 quad_perm:[2,3,0,1] row_mask:0xf bank_mask:0xf
	s_waitcnt lgkmcnt(0)
	s_nop 1
	v_add_f32_dpp v62, v62, v62 row_half_mirror row_mask:0xf bank_mask:0xf
	s_waitcnt lgkmcnt(0)
	s_nop 1
	v_add_f32_dpp v62, v62, v62 row_mirror row_mask:0xf bank_mask:0xf
	ds_bpermute_b32 v63, v108, v62
	s_and_saveexec_b64 s[2:3], s[44:45]
	s_cbranch_execz .LBB0_824
	s_waitcnt lgkmcnt(0)
	v_add_f32_e32 v62, v62, v63
	ds_write_b32 v102, v62 offset:3648
.LBB0_824:
	s_or_b64 exec, exec, s[2:3]
	s_waitcnt vmcnt(13)
	v_mul_f32_e32 v59, v1, v59
	v_fmac_f32_e32 v59, v0, v58
	v_fmac_f32_e32 v59, v2, v60
	v_fmac_f32_e32 v59, v3, v61
	s_waitcnt lgkmcnt(0)
	s_nop 1
	v_add_f32_dpp v58, v59, v59 quad_perm:[1,0,3,2] row_mask:0xf bank_mask:0xf
	s_waitcnt lgkmcnt(0)
	s_nop 1
	v_add_f32_dpp v58, v58, v58 quad_perm:[2,3,0,1] row_mask:0xf bank_mask:0xf
	s_waitcnt lgkmcnt(0)
	s_nop 1
	v_add_f32_dpp v58, v58, v58 row_half_mirror row_mask:0xf bank_mask:0xf
	s_waitcnt lgkmcnt(0)
	s_nop 1
	v_add_f32_dpp v58, v58, v58 row_mirror row_mask:0xf bank_mask:0xf
	ds_bpermute_b32 v59, v108, v58
	s_and_saveexec_b64 s[2:3], s[44:45]
	s_cbranch_execz .LBB0_826
	s_waitcnt lgkmcnt(0)
	v_add_f32_e32 v58, v58, v59
	ds_write_b32 v102, v58 offset:3712
.LBB0_826:
	s_or_b64 exec, exec, s[2:3]
	s_waitcnt vmcnt(12)
	v_mul_f32_e32 v55, v1, v55
	v_fmac_f32_e32 v55, v0, v54
	v_fmac_f32_e32 v55, v2, v56
	v_fmac_f32_e32 v55, v3, v57
	s_waitcnt lgkmcnt(0)
	s_nop 1
	v_add_f32_dpp v54, v55, v55 quad_perm:[1,0,3,2] row_mask:0xf bank_mask:0xf
	s_waitcnt lgkmcnt(0)
	s_nop 1
	v_add_f32_dpp v54, v54, v54 quad_perm:[2,3,0,1] row_mask:0xf bank_mask:0xf
	s_waitcnt lgkmcnt(0)
	s_nop 1
	v_add_f32_dpp v54, v54, v54 row_half_mirror row_mask:0xf bank_mask:0xf
	s_waitcnt lgkmcnt(0)
	s_nop 1
	v_add_f32_dpp v54, v54, v54 row_mirror row_mask:0xf bank_mask:0xf
	ds_bpermute_b32 v55, v108, v54
	s_and_saveexec_b64 s[2:3], s[44:45]
	s_cbranch_execz .LBB0_828
	s_waitcnt lgkmcnt(0)
	v_add_f32_e32 v54, v54, v55
	ds_write_b32 v102, v54 offset:3776
.LBB0_828:
	s_or_b64 exec, exec, s[2:3]
	s_waitcnt vmcnt(11)
	v_mul_f32_e32 v51, v1, v51
	v_fmac_f32_e32 v51, v0, v50
	v_fmac_f32_e32 v51, v2, v52
	v_fmac_f32_e32 v51, v3, v53
	s_waitcnt lgkmcnt(0)
	s_nop 1
	v_add_f32_dpp v50, v51, v51 quad_perm:[1,0,3,2] row_mask:0xf bank_mask:0xf
	s_waitcnt lgkmcnt(0)
	s_nop 1
	v_add_f32_dpp v50, v50, v50 quad_perm:[2,3,0,1] row_mask:0xf bank_mask:0xf
	s_waitcnt lgkmcnt(0)
	s_nop 1
	v_add_f32_dpp v50, v50, v50 row_half_mirror row_mask:0xf bank_mask:0xf
	s_waitcnt lgkmcnt(0)
	s_nop 1
	v_add_f32_dpp v50, v50, v50 row_mirror row_mask:0xf bank_mask:0xf
	ds_bpermute_b32 v51, v108, v50
	s_and_saveexec_b64 s[2:3], s[44:45]
	s_cbranch_execz .LBB0_830
	s_waitcnt lgkmcnt(0)
	v_add_f32_e32 v50, v50, v51
	ds_write_b32 v102, v50 offset:3840
.LBB0_830:
	s_or_b64 exec, exec, s[2:3]
	s_waitcnt vmcnt(10)
	v_mul_f32_e32 v47, v1, v47
	v_fmac_f32_e32 v47, v0, v46
	v_fmac_f32_e32 v47, v2, v48
	v_fmac_f32_e32 v47, v3, v49
	s_waitcnt lgkmcnt(0)
	s_nop 1
	v_add_f32_dpp v46, v47, v47 quad_perm:[1,0,3,2] row_mask:0xf bank_mask:0xf
	s_waitcnt lgkmcnt(0)
	s_nop 1
	v_add_f32_dpp v46, v46, v46 quad_perm:[2,3,0,1] row_mask:0xf bank_mask:0xf
	s_waitcnt lgkmcnt(0)
	s_nop 1
	v_add_f32_dpp v46, v46, v46 row_half_mirror row_mask:0xf bank_mask:0xf
	s_waitcnt lgkmcnt(0)
	s_nop 1
	v_add_f32_dpp v46, v46, v46 row_mirror row_mask:0xf bank_mask:0xf
	ds_bpermute_b32 v47, v108, v46
	s_and_saveexec_b64 s[2:3], s[44:45]
	s_cbranch_execz .LBB0_832
	s_waitcnt lgkmcnt(0)
	v_add_f32_e32 v46, v46, v47
	ds_write_b32 v102, v46 offset:3904
.LBB0_832:
	s_or_b64 exec, exec, s[2:3]
	s_waitcnt vmcnt(9)
	v_mul_f32_e32 v43, v1, v43
	v_fmac_f32_e32 v43, v0, v42
	v_fmac_f32_e32 v43, v2, v44
	v_fmac_f32_e32 v43, v3, v45
	s_waitcnt lgkmcnt(0)
	s_nop 1
	v_add_f32_dpp v42, v43, v43 quad_perm:[1,0,3,2] row_mask:0xf bank_mask:0xf
	s_waitcnt lgkmcnt(0)
	s_nop 1
	v_add_f32_dpp v42, v42, v42 quad_perm:[2,3,0,1] row_mask:0xf bank_mask:0xf
	s_waitcnt lgkmcnt(0)
	s_nop 1
	v_add_f32_dpp v42, v42, v42 row_half_mirror row_mask:0xf bank_mask:0xf
	s_waitcnt lgkmcnt(0)
	s_nop 1
	v_add_f32_dpp v42, v42, v42 row_mirror row_mask:0xf bank_mask:0xf
	ds_bpermute_b32 v43, v108, v42
	s_and_saveexec_b64 s[2:3], s[44:45]
	s_cbranch_execz .LBB0_834
	s_waitcnt lgkmcnt(0)
	v_add_f32_e32 v42, v42, v43
	ds_write_b32 v102, v42 offset:3968
.LBB0_834:
	s_or_b64 exec, exec, s[2:3]
	s_waitcnt vmcnt(8)
	v_mul_f32_e32 v5, v1, v5
	v_fmac_f32_e32 v5, v0, v4
	v_fmac_f32_e32 v5, v2, v6
	v_fmac_f32_e32 v5, v3, v7
	s_waitcnt lgkmcnt(0)
	s_nop 1
	v_add_f32_dpp v4, v5, v5 quad_perm:[1,0,3,2] row_mask:0xf bank_mask:0xf
	s_waitcnt lgkmcnt(0)
	s_nop 1
	v_add_f32_dpp v4, v4, v4 quad_perm:[2,3,0,1] row_mask:0xf bank_mask:0xf
	s_waitcnt lgkmcnt(0)
	s_nop 1
	v_add_f32_dpp v4, v4, v4 row_half_mirror row_mask:0xf bank_mask:0xf
	s_waitcnt lgkmcnt(0)
	s_nop 1
	v_add_f32_dpp v4, v4, v4 row_mirror row_mask:0xf bank_mask:0xf
	ds_bpermute_b32 v5, v108, v4
	s_and_saveexec_b64 s[2:3], s[44:45]
	s_cbranch_execz .LBB0_836
	s_waitcnt lgkmcnt(0)
	v_add_f32_e32 v4, v4, v5
	ds_write_b32 v102, v4 offset:4032
.LBB0_836:
	s_or_b64 exec, exec, s[2:3]
	s_and_saveexec_b64 s[2:3], s[46:47]
	s_cbranch_execz .LBB0_839
	s_lshl_b32 s11, s68, 2
	s_or_b32 s20, s11, s69
	s_ashr_i32 s21, s20, 31
	s_lshl_b64 s[20:21], s[20:21], 9
	s_waitcnt lgkmcnt(0)
	v_lshl_add_u64 v[4:5], v[88:89], 0, s[20:21]
	global_load_dwordx4 v[4:7], v[4:5], off
	s_waitcnt vmcnt(0)
	v_mul_f32_e32 v1, v1, v5
	v_fmac_f32_e32 v1, v0, v4
	v_fmac_f32_e32 v1, v2, v6
	v_fmac_f32_e32 v1, v3, v7
	s_waitcnt lgkmcnt(0)
	s_nop 1
	v_add_f32_dpp v0, v1, v1 quad_perm:[1,0,3,2] row_mask:0xf bank_mask:0xf
	s_waitcnt lgkmcnt(0)
	s_nop 1
	v_add_f32_dpp v0, v0, v0 quad_perm:[2,3,0,1] row_mask:0xf bank_mask:0xf
	s_waitcnt lgkmcnt(0)
	s_nop 1
	v_add_f32_dpp v0, v0, v0 row_half_mirror row_mask:0xf bank_mask:0xf
	s_waitcnt lgkmcnt(0)
	s_nop 1
	v_add_f32_dpp v0, v0, v0 row_mirror row_mask:0xf bank_mask:0xf
	ds_bpermute_b32 v1, v108, v0
	s_and_b64 exec, exec, s[44:45]
	s_cbranch_execz .LBB0_839
	s_waitcnt lgkmcnt(0)
	v_add_f32_e32 v0, v0, v1
	ds_write_b32 v33, v0 offset:4096

.LBB0_857:
	s_or_b64 exec, exec, s[2:3]
	s_waitcnt lgkmcnt(0)
	s_waitcnt lgkmcnt(0)
	s_nop 1
	v_add_f32_dpp v0, v42, v42 quad_perm:[1,0,3,2] row_mask:0xf bank_mask:0xf
	s_waitcnt lgkmcnt(0)
	s_nop 1
	v_add_f32_dpp v0, v0, v0 quad_perm:[2,3,0,1] row_mask:0xf bank_mask:0xf
	s_waitcnt lgkmcnt(0)
	s_nop 1
	v_add_f32_dpp v0, v0, v0 row_half_mirror row_mask:0xf bank_mask:0xf
	s_waitcnt lgkmcnt(0)
	s_nop 1
	v_add_f32_dpp v0, v0, v0 row_mirror row_mask:0xf bank_mask:0xf
	ds_bpermute_b32 v1, v108, v0
	s_waitcnt lgkmcnt(0)
	v_add_f32_e32 v0, v0, v1
	ds_bpermute_b32 v1, v109, v0
	s_and_saveexec_b64 s[2:3], s[50:51]
	s_cbranch_execz .LBB0_859
	s_waitcnt lgkmcnt(0)
	v_add_f32_e32 v0, v0, v1
	v_mov_b32_e32 v1, s64
	ds_write_b32 v1, v0 offset:4352

.LBB0_880:
	v_readlane_b32 s2, v253, 2
	v_readlane_b32 s3, v253, 3
	v_cvt_f32_u32_e32 v0, v2
	v_sub_u32_e32 v4, 0, v2
	v_rcp_iflag_f32_e32 v0, v0
	s_nop 1
	global_atomic_add v3, v33, v215, s[2:3] sc0
	v_mul_f32_e32 v0, 0x4f7ffffe, v0
	v_cvt_u32_f32_e32 v0, v0
	v_mul_lo_u32 v4, v4, v0
	v_mul_hi_u32 v4, v0, v4
	v_add_u32_e32 v0, v0, v4
	s_waitcnt vmcnt(0)
	v_mul_hi_u32 v0, v3, v0
	v_mul_lo_u32 v4, v0, v2
	v_sub_u32_e32 v4, v3, v4
	v_add_u32_e32 v5, 1, v0
	v_cmp_ge_u32_e32 vcc, v4, v2
	v_add_u32_e32 v3, 1, v3
	s_nop 0
	v_cndmask_b32_e32 v0, v0, v5, vcc
	v_sub_u32_e32 v5, v4, v2
	v_cndmask_b32_e32 v4, v4, v5, vcc
	v_add_u32_e32 v5, 1, v0
	v_cmp_ge_u32_e32 vcc, v4, v2
	s_nop 1
	v_cndmask_b32_e32 v0, v0, v5, vcc
	v_mul_lo_u32 v4, v2, v0
	v_add_u32_e32 v2, v4, v2
	v_cmp_ne_u32_e32 vcc, v3, v2
	s_and_saveexec_b64 s[2:3], vcc
	s_xor_b64 s[6:7], exec, s[2:3]
	s_cbranch_execz .LBB0_900
	v_readlane_b32 s2, v253, 4
	v_readlane_b32 s3, v253, 5
	s_nop 4
	global_load_dword v4, v33, s[2:3] sc1
	s_sleep 2
	s_waitcnt lgkmcnt(0)
	global_load_dword v1, v33, s[2:3] sc1
	s_sleep 2
	global_load_dword v2, v33, s[2:3] sc1
	s_sleep 2
	global_load_dword v3, v33, s[2:3] sc1
	s_waitcnt vmcnt(3)
	v_cmp_eq_u32_e32 vcc, v4, v0
	s_and_saveexec_b64 s[34:35], vcc
	s_cbranch_execz .LBB0_899
	s_mov_b32 s8, 1
	s_mov_b64 s[2:3], 0
	s_branch .LBB0_887

.LBB0_887:
	v_readlane_b32 s12, v253, 4
	v_readlane_b32 s13, v253, 5
	s_waitcnt vmcnt(0)
	v_cmp_eq_u32_e32 vcc, v1, v0
	s_or_b64 s[40:41], s[40:41], exec
	s_or_b64 s[38:39], s[38:39], exec
	s_nop 0
	global_load_dword v4, v33, s[12:13] sc1
	s_sleep 2
	s_and_saveexec_b64 s[42:43], vcc
	s_cbranch_execz .LBB0_886
	v_readlane_b32 s12, v253, 4
	v_readlane_b32 s13, v253, 5
	s_waitcnt vmcnt(2)
	v_cmp_eq_u32_e32 vcc, v2, v0
	s_mov_b64 s[28:29], -1
	s_mov_b64 s[30:31], -1
	s_nop 0
	global_load_dword v1, v33, s[12:13] sc1
	s_sleep 2
	s_and_saveexec_b64 s[44:45], vcc
	s_cbranch_execz .LBB0_885
	v_readlane_b32 s12, v253, 4
	v_readlane_b32 s13, v253, 5
	s_waitcnt vmcnt(2)
	v_cmp_eq_u32_e32 vcc, v3, v0
	s_mov_b64 s[48:49], -1
	s_nop 1
	global_load_dword v2, v33, s[12:13] sc1
	s_sleep 2
	s_and_saveexec_b64 s[30:31], vcc
	s_cbranch_execz .LBB0_884
	v_readlane_b32 s12, v253, 4
	v_readlane_b32 s13, v253, 5
	s_and_b32 s11, s8, 63
	s_mov_b64 s[46:47], -1
	s_cmp_eq_u32 s11, 0
	s_nop 1
	global_load_dword v3, v33, s[12:13] sc1
	s_sleep 2
	s_cbranch_scc1 .LBB0_893
	s_and_b64 vcc, exec, s[28:29]
	s_cbranch_vccz .LBB0_883

.LBB0_895:
	s_cmp_lt_u32 s8, 0x40001
	s_mov_b64 s[48:49], 0
	s_cselect_b64 s[28:29], -1, 0
	s_and_b64 vcc, exec, s[28:29]
	s_cbranch_vccnz .LBB0_892
	s_branch .LBB0_883

.LBB0_903:
	s_or_b64 exec, exec, s[6:7]
	s_waitcnt vmcnt(0)
	v_readfirstlane_b32 s2, v2
	v_cvt_f32_u32_e32 v2, v1
	v_sub_u32_e32 v3, 0, v1
	v_add_u32_e32 v0, s2, v0
	v_readlane_b32 s6, v253, 8
	v_rcp_iflag_f32_e32 v2, v2
	v_readlane_b32 s7, v253, 9
	s_mov_b64 s[2:3], -1
	v_mul_f32_e32 v2, 0x4f7ffffe, v2
	v_cvt_u32_f32_e32 v2, v2
	v_mul_lo_u32 v3, v3, v2
	v_mul_hi_u32 v3, v2, v3
	v_add_u32_e32 v2, v2, v3
	v_mul_hi_u32 v2, v0, v2
	v_mul_lo_u32 v3, v2, v1
	v_sub_u32_e32 v3, v0, v3
	v_cmp_ge_u32_e32 vcc, v3, v1
	v_add_u32_e32 v4, 1, v2
	v_add_u32_e32 v0, 1, v0
	v_cndmask_b32_e32 v2, v2, v4, vcc
	v_sub_u32_e32 v4, v3, v1
	v_cndmask_b32_e32 v3, v3, v4, vcc
	v_cmp_ge_u32_e32 vcc, v3, v1
	v_add_u32_e32 v3, 1, v2
	s_nop 0
	v_cndmask_b32_e32 v2, v2, v3, vcc
	v_mul_lo_u32 v3, v1, v2
	v_add_u32_e32 v1, v3, v1
	v_cmp_ne_u32_e32 vcc, v0, v1
	v_mov_b64_e32 v[0:1], s[6:7]
	s_and_saveexec_b64 s[6:7], vcc
	s_cbranch_execz .LBB0_921
	v_readlane_b32 s2, v253, 8
	v_readlane_b32 s3, v253, 9
	s_nop 4
	global_load_dword v4, v33, s[2:3] sc1
	s_sleep 2
	global_load_dword v0, v33, s[2:3] sc1
	s_sleep 2
	global_load_dword v1, v33, s[2:3] sc1
	s_sleep 2
	global_load_dword v3, v33, s[2:3] sc1
	s_mov_b64 s[2:3], 0
	s_waitcnt vmcnt(3)
	v_cmp_eq_u32_e32 vcc, v4, v2
	s_and_saveexec_b64 s[34:35], vcc
	s_cbranch_execz .LBB0_920
	s_mov_b32 s8, 1
	s_branch .LBB0_910

.LBB0_910:
	v_readlane_b32 s12, v253, 8
	v_readlane_b32 s13, v253, 9
	s_waitcnt vmcnt(0)
	v_cmp_eq_u32_e32 vcc, v0, v2
	s_or_b64 s[40:41], s[40:41], exec
	s_or_b64 s[38:39], s[38:39], exec
	s_nop 0
	global_load_dword v4, v33, s[12:13] sc1
	s_sleep 2
	s_and_saveexec_b64 s[42:43], vcc
	s_cbranch_execz .LBB0_909
	v_readlane_b32 s12, v253, 8
	v_readlane_b32 s13, v253, 9
	s_waitcnt vmcnt(2)
	v_cmp_eq_u32_e32 vcc, v1, v2
	s_mov_b64 s[28:29], -1
	s_mov_b64 s[30:31], -1
	s_nop 0
	global_load_dword v0, v33, s[12:13] sc1
	s_sleep 2
	s_and_saveexec_b64 s[44:45], vcc
	s_cbranch_execz .LBB0_908
	v_readlane_b32 s12, v253, 8
	v_readlane_b32 s13, v253, 9
	s_waitcnt vmcnt(2)
	v_cmp_eq_u32_e32 vcc, v3, v2
	s_mov_b64 s[48:49], -1
	s_nop 1
	global_load_dword v1, v33, s[12:13] sc1
	s_sleep 2
	s_and_saveexec_b64 s[30:31], vcc
	s_cbranch_execz .LBB0_907
	v_readlane_b32 s12, v253, 8
	v_readlane_b32 s13, v253, 9
	s_and_b32 s11, s8, 63
	s_mov_b64 s[46:47], -1
	s_cmp_eq_u32 s11, 0
	s_nop 1
	global_load_dword v3, v33, s[12:13] sc1
	s_sleep 2
	s_cbranch_scc1 .LBB0_916
	s_and_b64 vcc, exec, s[28:29]
	s_cbranch_vccz .LBB0_906

.LBB0_934:
	v_readlane_b32 s2, v254, 24
	v_cmp_gt_i32_e32 vcc, 8, v138
	s_nop 0
	v_lshl_add_u32 v9, v138, 2, s2
	s_waitcnt vmcnt(0) lgkmcnt(0)
	s_barrier
	s_and_saveexec_b64 s[2:3], vcc
	ds_write_b32 v9, v33
	s_or_b64 exec, exec, s[2:3]
	v_and_b32_e32 v14, 64, v216
	v_add_u32_e32 v16, -1, v216
	v_cmp_lt_i32_e32 vcc, v16, v14
	v_add_u32_e32 v17, -2, v216
	v_add_u32_e32 v10, 0x7f, v12
	v_cndmask_b32_e32 v16, v16, v216, vcc
	v_cmp_lt_i32_e32 vcc, v17, v14
	v_add_u32_e32 v18, -4, v216
	v_ashrrev_i32_e32 v15, 7, v10
	v_min_u32_e32 v10, 1, v12
	v_add_u32_e32 v15, v15, v10
	v_lshlrev_b32_e32 v16, 2, v16
	v_cndmask_b32_e32 v17, v17, v216, vcc
	v_cmp_lt_i32_e32 vcc, v18, v14
	v_add_u32_e32 v19, -8, v216
	v_add_u32_e32 v20, -16, v216
	v_cndmask_b32_e32 v18, v18, v216, vcc
	v_cmp_lt_i32_e32 vcc, v19, v14
	ds_bpermute_b32 v16, v16, v15
	v_subrev_u32_e32 v21, 32, v216
	v_cndmask_b32_e32 v19, v19, v216, vcc
	v_cmp_lt_i32_e32 vcc, v20, v14
	v_and_b32_e32 v10, 63, v138
	v_lshlrev_b32_e32 v17, 2, v17
	v_cndmask_b32_e32 v20, v20, v216, vcc
	v_cmp_lt_i32_e32 vcc, v21, v14
	v_lshlrev_b32_e32 v18, 2, v18
	v_lshlrev_b32_e32 v19, 2, v19
	v_cndmask_b32_e32 v21, v21, v216, vcc
	v_cmp_eq_u32_e32 vcc, 63, v10
	s_and_b64 s[4:5], s[40:41], vcc
	v_cmp_ne_u32_e32 vcc, 0, v10
	v_lshlrev_b32_e32 v20, 2, v20
	v_cmp_gt_u32_e64 s[38:39], 16, v10
	s_waitcnt lgkmcnt(0)
	v_cndmask_b32_e32 v16, 0, v16, vcc
	v_add_u32_e32 v15, v16, v15
	ds_bpermute_b32 v16, v17, v15
	v_cmp_lt_u32_e32 vcc, 1, v10
	v_lshlrev_b32_e32 v21, 2, v21
	s_ashr_i32 s11, s20, 6
	s_waitcnt lgkmcnt(0)
	v_cndmask_b32_e32 v16, 0, v16, vcc
	v_add_u32_e32 v15, v16, v15
	ds_bpermute_b32 v16, v18, v15
	v_cmp_lt_u32_e32 vcc, 3, v10
	s_waitcnt lgkmcnt(0)
	s_nop 0
	v_cndmask_b32_e32 v16, 0, v16, vcc
	v_add_u32_e32 v15, v16, v15
	ds_bpermute_b32 v16, v19, v15
	v_cmp_lt_u32_e32 vcc, 7, v10
	s_waitcnt lgkmcnt(0)
	s_nop 0
	v_cndmask_b32_e32 v16, 0, v16, vcc
	v_add_u32_e32 v15, v16, v15
	ds_bpermute_b32 v16, v20, v15
	v_cmp_lt_u32_e32 vcc, 31, v10
	s_waitcnt lgkmcnt(0)
	v_cndmask_b32_e64 v16, v16, 0, s[38:39]
	v_add_u32_e32 v15, v16, v15
	ds_bpermute_b32 v16, v21, v15
	s_waitcnt lgkmcnt(0)
	v_cndmask_b32_e32 v16, 0, v16, vcc
	v_add_u32_e32 v15, v16, v15
	s_and_saveexec_b64 s[2:3], s[4:5]
	s_cbranch_execz .LBB0_989
	s_lshl_b32 s4, s11, 2
	s_add_i32 s4, s4, 0
	s_add_i32 s4, s4, 0x21410
	v_mov_b32_e32 v16, s4
	ds_write_b32 v16, v15
	s_or_b64 exec, exec, s[2:3]
	s_and_saveexec_b64 s[2:3], s[40:41]
	s_cbranch_execnz .LBB0_990

.LBB0_949:
	s_or_b64 exec, exec, s[0:1]
	v_xor_b32_e32 v13, 1, v216
	v_add_u32_e32 v12, 64, v14
	v_cmp_lt_i32_e32 vcc, v13, v12
	v_and_b32_e32 v132, 15, v138
	s_mov_b32 s17, 48
	v_cndmask_b32_e32 v13, v216, v13, vcc
	v_lshlrev_b32_e32 v191, 2, v13
	v_xor_b32_e32 v13, 2, v216
	v_cmp_lt_i32_e32 vcc, v13, v12
	s_nop 1
	v_cndmask_b32_e32 v13, v216, v13, vcc
	v_lshlrev_b32_e32 v192, 2, v13
	v_xor_b32_e32 v13, 4, v216
	v_cmp_lt_i32_e32 vcc, v13, v12
	s_nop 1
	v_cndmask_b32_e32 v13, v216, v13, vcc
	v_lshlrev_b32_e32 v193, 2, v13
	v_xor_b32_e32 v13, 8, v216
	v_cmp_lt_i32_e32 vcc, v13, v12
	s_nop 1
	v_cndmask_b32_e32 v13, v216, v13, vcc
	v_lshlrev_b32_e32 v194, 2, v13
	s_and_b64 vcc, exec, s[80:81]
	s_cbranch_vccnz .LBB0_958
	v_lshl_add_u32 v13, v132, 5, 0
	v_add_u32_e32 v13, 0x21800, v13
	ds_read_b128 v[14:17], v13
	ds_read_b128 v[18:21], v13 offset:16
	v_cmp_eq_u32_e32 vcc, 0, v132
	s_waitcnt lgkmcnt(1)
	v_fma_f32 v0, v0, v14, 0
	v_fmac_f32_e32 v0, v1, v15
	v_fmac_f32_e32 v0, v2, v16
	v_fmac_f32_e32 v0, v3, v17
	s_waitcnt lgkmcnt(0)
	v_fmac_f32_e32 v0, v4, v18
	v_fmac_f32_e32 v0, v5, v19
	v_fmac_f32_e32 v0, v6, v20
	v_fmac_f32_e32 v0, v7, v21
	s_waitcnt lgkmcnt(0)
	s_nop 1
	v_add_f32_dpp v0, v0, v0 quad_perm:[1,0,3,2] row_mask:0xf bank_mask:0xf
	s_waitcnt lgkmcnt(0)
	s_nop 1
	v_add_f32_dpp v0, v0, v0 quad_perm:[2,3,0,1] row_mask:0xf bank_mask:0xf
	s_waitcnt lgkmcnt(0)
	s_nop 1
	v_add_f32_dpp v0, v0, v0 row_half_mirror row_mask:0xf bank_mask:0xf
	ds_bpermute_b32 v1, v194, v0
	s_and_saveexec_b64 s[0:1], vcc
	s_cbranch_execz .LBB0_952
	v_ashrrev_i32_e32 v2, 2, v138
	s_waitcnt lgkmcnt(0)
	v_add_f32_e32 v0, v0, v1
	v_add_u32_e32 v1, 0, v2
	v_add_u32_e32 v1, 0x21a00, v1
	ds_write_b32 v1, v0

.LBB0_968:
	s_waitcnt vmcnt(5)
	v_mbcnt_lo_u32_b32 v8, -1, 0
	v_mbcnt_hi_u32_b32 v8, -1, v8
	v_lshlrev_b32_e32 v8, 4, v8
	v_add_u32_e32 v8, 0x21004, v8
	ds_read2_b32 v[10:11], v8 offset1:1
	ds_read2_b32 v[8:9], v8 offset0:2 offset1:3
	s_waitcnt lgkmcnt(0)
	v_cmp_ge_i32_e32 vcc, s48, v10
	s_bcnt1_i32_b64 s40, vcc
	v_cmp_ge_i32_e32 vcc, s48, v11
	s_bcnt1_i32_b64 s2, vcc
	s_add_i32 s40, s40, s2
	v_cmp_ge_i32_e32 vcc, s48, v8
	s_bcnt1_i32_b64 s2, vcc
	s_add_i32 s40, s40, s2
	v_cmp_ge_i32_e32 vcc, s48, v9
	s_bcnt1_i32_b64 s2, vcc
	s_add_i32 s40, s40, s2
	s_lshl_b32 s2, s40, 2
	s_add_i32 s2, s2, 0x21004
	v_mov_b32_e32 v8, s2
	ds_read_b32 v8, v8
	s_waitcnt lgkmcnt(0)
	v_readfirstlane_b32 s20, v8
	s_lshl_b32 s2, s40, 2
	s_add_i32 s2, s2, 0
	s_add_i32 s3, s2, 0x21c00
	v_mov_b32_e32 v8, s3
	s_add_i32 s2, s2, 0x21000
	v_mov_b32_e32 v9, s2
	ds_read_b32 v8, v8
	ds_read_b32 v130, v9
	s_min_i32 s21, s20, s0
	s_ashr_i32 s41, s40, 31
	s_ashr_i32 s31, s40, 7
	s_bfe_u32 s43, s40, 0x20005
	s_waitcnt lgkmcnt(0)
	v_readfirstlane_b32 s2, v130
	s_sub_i32 s3, s48, s2
	s_sub_i32 s2, s21, s2
	s_lshl_b32 s23, s3, 7
	s_lshl_b32 s2, s2, 7
	v_readfirstlane_b32 s3, v8
	s_min_i32 s28, s2, s3
	s_sub_i32 s2, s28, s23
	s_add_i32 s2, s2, 15
	s_ashr_i32 s29, s2, 4
	s_cmp_lt_i32 s29, 1
	s_cbranch_scc1 .LBB0_987
	s_lshl_b64 s[2:3], s[40:41], 16
	s_add_u32 s46, s1, s2
	s_addc_u32 s47, s12, s3
	s_cmp_lt_i32 s11, s29
	s_cselect_b64 s[50:51], -1, 0
	s_and_b64 s[2:3], s[50:51], exec
	s_cselect_b32 s2, s11, 0
	s_cmp_lt_i32 s19, s29
	s_cselect_b32 s3, s19, s2
	s_lshl_b32 s2, s2, 4
	s_add_i32 s2, s2, s23
	v_or_b32_e32 v8, s2, v132
	v_mov_b32_e32 v9, s2
	s_lshl_b32 s2, s3, 4
	s_add_i32 s2, s2, s23
	v_cmp_gt_i32_e32 vcc, s28, v8
	v_or_b32_e32 v10, s2, v132
	v_mov_b32_e32 v11, s2
	v_cndmask_b32_e32 v8, v9, v8, vcc
	v_cmp_gt_i32_e32 vcc, s28, v10
	v_ashrrev_i32_e32 v9, 31, v8
	v_lshl_add_u64 v[8:9], v[8:9], 2, s[46:47]
	v_cndmask_b32_e32 v10, v11, v10, vcc
	v_ashrrev_i32_e32 v11, 31, v10
	v_lshl_add_u64 v[10:11], v[10:11], 2, s[46:47]
	global_load_dword v220, v[8:9], off
	global_load_dword v230, v[10:11], off
	s_lshl_b32 s2, s40, 8
	s_lshl_b32 s30, s31, 13
	s_and_b32 s41, s2, 0x1f00
	s_or_b32 s2, s41, s30
	s_ashr_i32 s3, s2, 31
	s_lshl_b64 s[2:3], s[2:3], 10
	s_add_u32 s2, s8, s2
	s_addc_u32 s3, s13, s3
	s_lshl_b32 s49, s43, 8
	s_add_u32 s2, s2, s49
	s_addc_u32 s3, s3, 0
	v_lshl_add_u64 v[8:9], s[2:3], 0, v[142:143]
	v_lshlrev_b32_e32 v32, 1, v190
	v_lshl_add_u64 v[10:11], s[2:3], 0, v[144:145]
	v_lshl_add_u64 v[8:9], v[8:9], 0, v[32:33]
	v_lshl_add_u64 v[10:11], v[10:11], 0, v[32:33]
	s_lshl_b32 s31, s31, 2
	global_load_dwordx4 v[50:53], v[8:9], off
	global_load_dwordx4 v[46:49], v[10:11], off
	v_lshl_add_u64 v[8:9], s[2:3], 0, v[146:147]
	v_lshl_add_u64 v[10:11], s[2:3], 0, v[148:149]
	s_or_b32 s52, s31, s43
	v_lshl_add_u64 v[8:9], v[8:9], 0, v[32:33]
	v_lshl_add_u64 v[10:11], v[10:11], 0, v[32:33]
	s_ashr_i32 s53, s52, 31
	global_load_dwordx4 v[58:61], v[8:9], off
	global_load_dwordx4 v[54:57], v[10:11], off
	v_lshl_add_u64 v[8:9], s[2:3], 0, v[150:151]
	v_lshl_add_u64 v[10:11], s[2:3], 0, v[152:153]
	s_lshl_b64 s[52:53], s[52:53], 21
	v_lshl_add_u64 v[8:9], v[8:9], 0, v[32:33]
	v_lshl_add_u64 v[10:11], v[10:11], 0, v[32:33]
	global_load_dwordx4 v[70:73], v[8:9], off
	global_load_dwordx4 v[66:69], v[10:11], off
	v_lshl_add_u64 v[8:9], s[2:3], 0, v[164:165]
	v_lshl_add_u64 v[10:11], s[2:3], 0, v[168:169]
	s_add_u32 s2, s14, s52
	s_addc_u32 s3, s15, s53
	s_lshl_b32 s31, s41, 1
	s_add_u32 s2, s2, s31
	v_lshl_add_u64 v[8:9], v[8:9], 0, v[32:33]
	s_addc_u32 s3, s3, 0
	v_lshl_add_u64 v[10:11], v[10:11], 0, v[32:33]
	global_load_dwordx4 v[78:81], v[8:9], off
	global_load_dwordx4 v[74:77], v[10:11], off
	v_lshl_add_u64 v[8:9], s[2:3], 0, v[162:163]
	v_mov_b32_e32 v183, v33
	v_lshl_add_u64 v[8:9], v[8:9], 0, v[182:183]
	v_lshl_add_u64 v[10:11], s[2:3], 0, v[166:167]
	v_lshl_add_u64 v[10:11], v[10:11], 0, v[182:183]
	global_load_dwordx4 v[86:89], v[8:9], off
	global_load_dwordx4 v[82:85], v[10:11], off
	v_lshl_add_u64 v[8:9], s[2:3], 0, v[170:171]
	v_lshl_add_u64 v[8:9], v[8:9], 0, v[182:183]
	v_lshl_add_u64 v[10:11], s[2:3], 0, v[172:173]
	v_lshl_add_u64 v[10:11], v[10:11], 0, v[182:183]
	global_load_dwordx4 v[94:97], v[8:9], off
	global_load_dwordx4 v[90:93], v[10:11], off
	v_lshl_add_u64 v[8:9], s[2:3], 0, v[174:175]
	v_lshl_add_u64 v[8:9], v[8:9], 0, v[182:183]
	v_lshl_add_u64 v[10:11], s[2:3], 0, v[176:177]
	v_lshl_add_u64 v[10:11], v[10:11], 0, v[182:183]
	global_load_dwordx4 v[102:105], v[8:9], off
	global_load_dwordx4 v[98:101], v[10:11], off
	v_lshl_add_u64 v[8:9], s[2:3], 0, v[178:179]
	v_lshl_add_u64 v[8:9], v[8:9], 0, v[182:183]
	v_lshl_add_u64 v[10:11], s[2:3], 0, v[180:181]
	v_lshl_add_u64 v[10:11], v[10:11], 0, v[182:183]
	global_load_dwordx4 v[110:113], v[8:9], off
	global_load_dwordx4 v[106:109], v[10:11], off
	s_waitcnt vmcnt(17)
	v_and_b32_e32 v8, 0x1fff, v220
	v_or_b32_e32 v8, s30, v8
	v_ashrrev_i32_e32 v9, 31, v8
	s_lshl_b32 s31, s43, 1
	v_lshrrev_b32_e32 v10, 13, v220
	s_min_i32 s2, s17, 47
	v_lshlrev_b64 v[8:9], 11, v[8:9]
	v_and_or_b32 v10, v10, 1, s31
	s_ashr_i32 s3, s2, 3
	v_lshl_add_u64 v[8:9], s[4:5], 0, v[8:9]
	v_lshlrev_b32_e32 v32, 8, v10
	s_lshl_b32 s3, s3, 2
	v_readlane_b32 s18, v254, 24
	v_lshl_add_u64 v[8:9], v[8:9], 0, v[32:33]
	v_mov_b32_e32 v129, v33
	s_add_i32 s3, s18, s3
	v_lshl_add_u64 v[20:21], v[8:9], 0, v[128:129]
	v_mov_b32_e32 v24, s3
	global_load_dwordx4 v[8:11], v[20:21], off
	global_load_dwordx4 v[12:15], v[20:21], off offset:64
	global_load_dwordx4 v[16:19], v[20:21], off offset:128
	s_nop 0
	global_load_dwordx4 v[20:23], v[20:21], off offset:192
	ds_read_b32 v24, v24
	s_lshl_b32 s2, s2, 4
	s_and_b32 s2, s2, 0x70
	v_readlane_b32 s52, v251, 1
	v_readlane_b32 s56, v251, 5
	s_waitcnt lgkmcnt(0)
	v_lshlrev_b32_e32 v24, 7, v24
	v_or_b32_e32 v24, s2, v24
	s_min_i32 s2, s17, 46
	s_add_i32 s2, s2, 1
	s_ashr_i32 s3, s2, 3
	s_lshl_b32 s3, s3, 2
	v_add_u32_e32 v24, v24, v186
	s_add_i32 s3, s18, s3
	v_ashrrev_i32_e32 v25, 31, v24
	v_mov_b32_e32 v28, s3
	v_lshlrev_b64 v[24:25], 11, v[24:25]
	ds_read_b32 v28, v28
	v_or_b32_e32 v24, v24, v227
	v_readlane_b32 s57, v251, 6
	s_lshl_b32 s2, s2, 4
	s_and_b32 s2, s2, 0x70
	v_lshl_add_u64 v[26:27], s[56:57], 0, v[24:25]
	global_load_dwordx4 v[62:65], v[26:27], off
	s_waitcnt lgkmcnt(0)
	v_lshlrev_b32_e32 v28, 7, v28
	v_or_b32_e32 v28, s2, v28
	s_min_i32 s2, s17, 45
	s_add_i32 s2, s2, 2
	s_ashr_i32 s3, s2, 3
	s_lshl_b32 s3, s3, 2
	s_add_i32 s3, s18, s3
	v_mov_b32_e32 v32, s3
	ds_read_b32 v32, v32
	s_lshl_b32 s2, s2, 4
	s_and_b32 s2, s2, 0x70
	v_add_u32_e32 v28, v28, v186
	v_ashrrev_i32_e32 v29, 31, v28
	s_waitcnt lgkmcnt(0)
	v_lshlrev_b32_e32 v32, 7, v32
	v_or_b32_e32 v32, s2, v32
	s_min_i32 s2, s17, 44
	s_add_i32 s2, s2, 3
	s_ashr_i32 s3, s2, 3
	s_lshl_b32 s3, s3, 2
	s_add_i32 s3, s18, s3
	v_add_u32_e32 v34, v32, v186
	v_mov_b32_e32 v32, s3
	ds_read_b32 v32, v32
	s_lshl_b32 s2, s2, 4
	s_and_b32 s2, s2, 0x70
	v_ashrrev_i32_e32 v35, 31, v34
	v_lshlrev_b64 v[28:29], 11, v[28:29]
	s_waitcnt lgkmcnt(0)
	v_lshlrev_b32_e32 v32, 7, v32
	v_or_b32_e32 v32, s2, v32
	v_add_u32_e32 v114, v32, v186
	v_ashrrev_i32_e32 v115, 31, v114
	v_lshlrev_b64 v[34:35], 11, v[34:35]
	v_lshlrev_b64 v[114:115], 11, v[114:115]
	v_readlane_b32 s58, v251, 7
	v_readlane_b32 s59, v251, 8
	v_or_b32_e32 v28, v28, v227
	v_or_b32_e32 v34, v34, v227
	v_or_b32_e32 v114, v114, v227
	v_lshl_add_u64 v[24:25], s[58:59], 0, v[24:25]
	v_lshl_add_u64 v[30:31], s[56:57], 0, v[28:29]
	v_lshl_add_u64 v[28:29], s[58:59], 0, v[28:29]
	v_lshl_add_u64 v[36:37], s[56:57], 0, v[34:35]
	v_lshl_add_u64 v[34:35], s[58:59], 0, v[34:35]
	v_lshl_add_u64 v[116:117], s[56:57], 0, v[114:115]
	v_lshl_add_u64 v[114:115], s[58:59], 0, v[114:115]
	global_load_dwordx4 v[38:41], v[30:31], off
	global_load_dwordx4 v[42:45], v[36:37], off
	global_load_dwordx4 v[118:121], v[116:117], off
	v_add_u32_e32 v32, v187, v196
	global_load_dwordx4 v[24:27], v[24:25], off
	s_cmp_gt_i32 s17, 47
	global_load_dwordx4 v[28:31], v[28:29], off
	v_readlane_b32 s53, v251, 2
	global_load_dwordx4 v[34:37], v[34:35], off
	v_readlane_b32 s54, v251, 3
	global_load_dwordx4 v[114:117], v[114:115], off
	s_barrier
	s_waitcnt vmcnt(27)
	ds_write_b128 v32, v[50:53]
	v_add_u32_e32 v32, v195, v198
	s_waitcnt vmcnt(26)
	ds_write_b128 v32, v[46:49]
	v_add_u32_e32 v32, v197, v200
	s_waitcnt vmcnt(25)
	ds_write_b128 v32, v[58:61]
	v_add_u32_e32 v32, v199, v203
	s_waitcnt vmcnt(24)
	ds_write_b128 v32, v[54:57]
	v_add_u32_e32 v32, v202, v205
	s_waitcnt vmcnt(23)
	ds_write_b128 v32, v[70:73]
	v_add_u32_e32 v32, v204, v207
	s_waitcnt vmcnt(22)
	ds_write_b128 v32, v[66:69]
	v_add_u32_e32 v32, v206, v209
	s_waitcnt vmcnt(21)
	ds_write_b128 v32, v[78:81]
	v_add_u32_e32 v32, v208, v210
	s_waitcnt vmcnt(20)
	ds_write_b128 v32, v[74:77]
	v_add_u32_e32 v32, v211, v201
	s_waitcnt vmcnt(19)
	ds_write_b128 v32, v[86:89]
	v_add_u32_e32 v32, v212, v201
	s_waitcnt vmcnt(18)
	ds_write_b128 v32, v[82:85]
	v_add_u32_e32 v32, v213, v201
	s_waitcnt vmcnt(17)
	ds_write_b128 v32, v[94:97]
	v_add_u32_e32 v32, v221, v201
	s_waitcnt vmcnt(16)
	ds_write_b128 v32, v[90:93]
	v_add_u32_e32 v32, v222, v201
	s_waitcnt vmcnt(15)
	ds_write_b128 v32, v[102:105]
	v_add_u32_e32 v32, v223, v201
	s_waitcnt vmcnt(14)
	ds_write_b128 v32, v[98:101]
	v_add_u32_e32 v32, v224, v201
	s_waitcnt vmcnt(13)
	ds_write_b128 v32, v[110:113]
	v_add_u32_e32 v32, v225, v201
	s_waitcnt vmcnt(12)
	ds_write_b128 v32, v[106:109]
	s_waitcnt vmcnt(7)
	v_mul_f32_e32 v32, v1, v63
	v_fmac_f32_e32 v32, v0, v62
	v_fmac_f32_e32 v32, v2, v64
	v_fmac_f32_e32 v32, v3, v65
	v_readlane_b32 s55, v251, 4
	v_readlane_b32 s60, v251, 9
	v_readlane_b32 s61, v251, 10
	v_readlane_b32 s62, v251, 11
	s_waitcnt lgkmcnt(0)
	s_nop 1
	v_add_f32_dpp v32, v32, v32 quad_perm:[1,0,3,2] row_mask:0xf bank_mask:0xf
	v_readlane_b32 s63, v251, 12
	v_readlane_b32 s64, v251, 13
	v_readlane_b32 s65, v251, 14
	v_readlane_b32 s66, v251, 15
	s_waitcnt lgkmcnt(0)
	s_nop 1
	v_add_f32_dpp v32, v32, v32 quad_perm:[2,3,0,1] row_mask:0xf bank_mask:0xf
	v_readlane_b32 s67, v251, 16
	s_waitcnt lgkmcnt(0)
	s_barrier
	s_nop 1
	v_add_f32_dpp v32, v32, v32 row_half_mirror row_mask:0xf bank_mask:0xf
	s_waitcnt lgkmcnt(0)
	s_nop 1
	v_add_f32_dpp v32, v32, v32 row_mirror row_mask:0xf bank_mask:0xf
	ds_bpermute_b32 v46, v226, v32
	s_cbranch_scc1 .LBB0_972
	s_waitcnt lgkmcnt(0)
	v_add_f32_e32 v32, v32, v46
	v_max_f32_e32 v46, v188, v188
	v_max_f32_e32 v47, v46, v32
	v_sub_f32_e32 v32, v32, v47
	v_sub_f32_e32 v46, v188, v47
	v_exp_f32_e32 v32, v32
	v_exp_f32_e32 v46, v46
	v_mov_b32_e32 v188, v47
	v_mov_b32_e32 v48, v32
	v_fmac_f32_e32 v48, v189, v46
	s_waitcnt vmcnt(3)
	v_pk_mul_f32 v[24:25], v[24:25], v[32:33] op_sel_hi:[1,0]
	v_pk_mul_f32 v[26:27], v[26:27], v[32:33] op_sel_hi:[1,0]
	v_pk_fma_f32 v[4:5], v[4:5], v[46:47], v[24:25] op_sel_hi:[1,0,1]
	v_pk_fma_f32 v[6:7], v[6:7], v[46:47], v[26:27] op_sel_hi:[1,0,1]
	v_mov_b32_e32 v189, v48
.LBB0_972:
	s_waitcnt vmcnt(3)
	v_mul_f32_e32 v24, v1, v39
	v_fmac_f32_e32 v24, v0, v38
	v_fmac_f32_e32 v24, v2, v40
	v_fmac_f32_e32 v24, v3, v41
	s_cmp_gt_i32 s17, 46
	s_waitcnt lgkmcnt(0)
	s_nop 1
	v_add_f32_dpp v24, v24, v24 quad_perm:[1,0,3,2] row_mask:0xf bank_mask:0xf
	s_waitcnt lgkmcnt(0)
	s_nop 1
	v_add_f32_dpp v24, v24, v24 quad_perm:[2,3,0,1] row_mask:0xf bank_mask:0xf
	s_waitcnt lgkmcnt(0)
	s_nop 1
	v_add_f32_dpp v24, v24, v24 row_half_mirror row_mask:0xf bank_mask:0xf
	s_waitcnt lgkmcnt(0)
	s_nop 1
	v_add_f32_dpp v24, v24, v24 row_mirror row_mask:0xf bank_mask:0xf
	ds_bpermute_b32 v25, v226, v24
	s_cbranch_scc1 .LBB0_974
	s_waitcnt lgkmcnt(0)
	v_add_f32_e32 v24, v24, v25
	v_max_f32_e32 v25, v188, v188
	v_max_f32_e32 v27, v25, v24
	v_sub_f32_e32 v24, v24, v27
	v_sub_f32_e32 v25, v188, v27
	v_exp_f32_e32 v24, v24
	v_exp_f32_e32 v26, v25
	v_mov_b32_e32 v188, v27
	v_mov_b32_e32 v32, v24
	v_fmac_f32_e32 v32, v189, v26
	s_waitcnt vmcnt(2)
	v_pk_mul_f32 v[28:29], v[28:29], v[24:25] op_sel_hi:[1,0]
	v_pk_mul_f32 v[24:25], v[30:31], v[24:25] op_sel_hi:[1,0]
	v_pk_fma_f32 v[4:5], v[4:5], v[26:27], v[28:29] op_sel_hi:[1,0,1]
	v_pk_fma_f32 v[6:7], v[6:7], v[26:27], v[24:25] op_sel_hi:[1,0,1]
	v_mov_b32_e32 v189, v32
.LBB0_974:
	v_mul_f32_e32 v24, v1, v43
	v_fmac_f32_e32 v24, v0, v42
	v_fmac_f32_e32 v24, v2, v44
	v_fmac_f32_e32 v24, v3, v45
	s_waitcnt lgkmcnt(0)
	s_cmp_gt_i32 s17, 45
	s_waitcnt lgkmcnt(0)
	s_nop 1
	v_add_f32_dpp v24, v24, v24 quad_perm:[1,0,3,2] row_mask:0xf bank_mask:0xf
	s_waitcnt lgkmcnt(0)
	s_nop 1
	v_add_f32_dpp v24, v24, v24 quad_perm:[2,3,0,1] row_mask:0xf bank_mask:0xf
	s_waitcnt lgkmcnt(0)
	s_nop 1
	v_add_f32_dpp v24, v24, v24 row_half_mirror row_mask:0xf bank_mask:0xf
	s_waitcnt lgkmcnt(0)
	s_nop 1
	v_add_f32_dpp v24, v24, v24 row_mirror row_mask:0xf bank_mask:0xf
	ds_bpermute_b32 v25, v226, v24
	s_cbranch_scc1 .LBB0_976
	s_waitcnt lgkmcnt(0)
	v_add_f32_e32 v24, v24, v25
	v_max_f32_e32 v25, v188, v188
	v_max_f32_e32 v27, v25, v24
	v_sub_f32_e32 v24, v24, v27
	v_sub_f32_e32 v25, v188, v27
	v_exp_f32_e32 v24, v24
	v_exp_f32_e32 v26, v25
	v_mov_b32_e32 v188, v27
	s_waitcnt vmcnt(2)
	v_mov_b32_e32 v30, v24
	v_fmac_f32_e32 v30, v189, v26
	s_waitcnt vmcnt(1)
	v_pk_mul_f32 v[28:29], v[34:35], v[24:25] op_sel_hi:[1,0]
	v_pk_mul_f32 v[24:25], v[36:37], v[24:25] op_sel_hi:[1,0]
	v_pk_fma_f32 v[4:5], v[4:5], v[26:27], v[28:29] op_sel_hi:[1,0,1]
	v_pk_fma_f32 v[6:7], v[6:7], v[26:27], v[24:25] op_sel_hi:[1,0,1]
	v_mov_b32_e32 v189, v30
.LBB0_976:
	v_mul_f32_e32 v24, v1, v119
	v_fmac_f32_e32 v24, v0, v118
	v_fmac_f32_e32 v24, v2, v120
	v_fmac_f32_e32 v24, v3, v121
	s_waitcnt lgkmcnt(0)
	s_cmp_gt_i32 s17, 44
	s_waitcnt lgkmcnt(0)
	s_nop 1
	v_add_f32_dpp v24, v24, v24 quad_perm:[1,0,3,2] row_mask:0xf bank_mask:0xf
	s_waitcnt lgkmcnt(0)
	s_nop 1
	v_add_f32_dpp v24, v24, v24 quad_perm:[2,3,0,1] row_mask:0xf bank_mask:0xf
	s_waitcnt lgkmcnt(0)
	s_nop 1
	v_add_f32_dpp v24, v24, v24 row_half_mirror row_mask:0xf bank_mask:0xf
	s_waitcnt lgkmcnt(0)
	s_nop 1
	v_add_f32_dpp v24, v24, v24 row_mirror row_mask:0xf bank_mask:0xf
	ds_bpermute_b32 v25, v226, v24
	s_cbranch_scc1 .LBB0_978
	s_waitcnt lgkmcnt(0)
	v_add_f32_e32 v24, v24, v25
	v_max_f32_e32 v25, v188, v188
	v_max_f32_e32 v231, v25, v24
	v_sub_f32_e32 v24, v24, v231
	v_sub_f32_e32 v25, v188, v231
	v_exp_f32_e32 v24, v24
	v_exp_f32_e32 v26, v25
	v_mov_b32_e32 v183, v24
	s_waitcnt vmcnt(0)
	v_pk_mul_f32 v[28:29], v[114:115], v[24:25] op_sel_hi:[1,0]
	v_pk_mul_f32 v[24:25], v[116:117], v[24:25] op_sel_hi:[1,0]
	v_fmac_f32_e32 v183, v189, v26
	v_pk_fma_f32 v[6:7], v[6:7], v[26:27], v[24:25] op_sel_hi:[1,0,1]
	v_pk_fma_f32 v[4:5], v[4:5], v[26:27], v[28:29] op_sel_hi:[1,0,1]
	s_andn2_b64 vcc, exec, s[36:37]
	s_cbranch_vccz .LBB0_979
	s_branch .LBB0_980

.LBB0_979:
	s_sleep 8

.LBB0_984:
	s_or_b64 exec, exec, s[2:3]
	s_waitcnt vmcnt(9)
	v_pk_mul_f32 v[34:35], v[0:1], v[34:35]
	v_pk_mul_f32 v[36:37], v[2:3], v[36:37]
	v_add_f32_e32 v32, v34, v35
	v_add_f32_e32 v32, v36, v32
	v_add_f32_e32 v32, v37, v32
	s_waitcnt vmcnt(8)
	v_pk_mul_f32 v[36:37], v[0:1], v[38:39]
	v_pk_mul_f32 v[34:35], v[2:3], v[40:41]
	v_add_f32_e32 v36, v36, v37
	v_add_f32_e32 v34, v34, v36
	v_add_f32_e32 v34, v35, v34
	s_cmp_lt_i32 s17, 48
	s_cselect_b64 vcc, -1, 0
	s_cmp_lt_i32 s17, 47
	s_waitcnt lgkmcnt(1)
	s_nop 1
	v_add_f32_dpp v32, v32, v32 quad_perm:[1,0,3,2] row_mask:0xf bank_mask:0xf
	s_waitcnt lgkmcnt(0)
	s_nop 1
	v_add_f32_dpp v34, v34, v34 quad_perm:[1,0,3,2] row_mask:0xf bank_mask:0xf
	v_add_u32_e32 v232, 0x80, v232
	s_waitcnt lgkmcnt(1)
	s_nop 1
	v_add_f32_dpp v32, v32, v32 quad_perm:[2,3,0,1] row_mask:0xf bank_mask:0xf
	s_waitcnt lgkmcnt(0)
	s_nop 1
	v_add_f32_dpp v34, v34, v34 quad_perm:[2,3,0,1] row_mask:0xf bank_mask:0xf
	s_waitcnt lgkmcnt(1)
	s_nop 1
	v_add_f32_dpp v32, v32, v32 row_half_mirror row_mask:0xf bank_mask:0xf
	s_waitcnt lgkmcnt(0)
	s_nop 1
	v_add_f32_dpp v34, v34, v34 row_half_mirror row_mask:0xf bank_mask:0xf
	s_waitcnt lgkmcnt(1)
	s_nop 1
	v_add_f32_dpp v32, v32, v32 row_mirror row_mask:0xf bank_mask:0xf
	s_waitcnt lgkmcnt(0)
	s_nop 1
	v_add_f32_dpp v34, v34, v34 row_mirror row_mask:0xf bank_mask:0xf
	ds_bpermute_b32 v35, v226, v32
	ds_bpermute_b32 v36, v226, v34
	s_waitcnt lgkmcnt(1)
	v_add_f32_e32 v32, v32, v35
	s_waitcnt lgkmcnt(0)
	v_add_f32_e32 v34, v34, v36
	v_cndmask_b32_e32 v32, v218, v32, vcc
	s_cselect_b64 vcc, -1, 0
	v_cndmask_b32_e32 v34, v218, v34, vcc
	v_max3_f32 v188, v231, v32, v34
	s_add_i32 s17, s17, 2
	v_sub_f32_e32 v34, v34, v188
	v_sub_f32_e32 v32, v32, v188
	v_exp_f32_e32 v34, v34
	v_sub_f32_e32 v35, v231, v188
	v_exp_f32_e32 v32, v32
	v_exp_f32_e32 v36, v35
	s_waitcnt vmcnt(6)
	v_pk_mul_f32 v[30:31], v[30:31], v[34:35] op_sel_hi:[1,0]
	v_pk_mul_f32 v[28:29], v[28:29], v[34:35] op_sel_hi:[1,0]
	v_add_f32_e32 v189, v32, v34
	v_pk_fma_f32 v[24:25], v[24:25], v[32:33], v[28:29] op_sel_hi:[1,0,1]
	v_pk_fma_f32 v[26:27], v[26:27], v[32:33], v[30:31] op_sel_hi:[1,0,1]
	s_add_i32 s41, s41, 8
	v_fmac_f32_e32 v189, v183, v36
	v_pk_fma_f32 v[6:7], v[6:7], v[36:37], v[26:27] op_sel_hi:[1,0,1]
	v_pk_fma_f32 v[4:5], v[4:5], v[36:37], v[24:25] op_sel_hi:[1,0,1]
	s_cmp_lt_i32 s41, s29
	s_cbranch_scc0 .LBB0_987
	v_mov_b32_e32 v231, v188
	v_mov_b32_e32 v183, v189
	v_mov_b32_e32 v220, v230
	v_mov_b32_e32 v230, v233
	s_branch .LBB0_982

.LBB0_996:
	s_min_i32 s0, s17, 39
	s_add_i32 s1, s0, 8
	s_ashr_i32 s1, s1, 3
	s_lshl_b32 s1, s1, 2
	v_readlane_b32 s2, v254, 24
	s_add_i32 s1, s2, s1
	s_waitcnt vmcnt(6)
	v_mov_b32_e32 v66, s1
	ds_read_b32 v66, v66
	s_lshl_b32 s0, s0, 4
	s_and_b32 s0, s0, 0x70
	v_readlane_b32 s48, v251, 1
	v_readlane_b32 s49, v251, 2
	s_waitcnt lgkmcnt(0)
	v_lshlrev_b32_e32 v66, 7, v66
	v_or_b32_e32 v66, s0, v66
	v_add_u32_e32 v66, v66, v186
	s_min_i32 s0, s17, 38
	v_ashrrev_i32_e32 v67, 31, v66
	v_readlane_b32 s50, v251, 3
	v_readlane_b32 s51, v251, 4
	v_readlane_b32 s52, v251, 5
	v_readlane_b32 s53, v251, 6
	v_readlane_b32 s54, v251, 7
	v_readlane_b32 s55, v251, 8
	v_readlane_b32 s56, v251, 9
	v_readlane_b32 s57, v251, 10
	v_readlane_b32 s58, v251, 11
	v_readlane_b32 s59, v251, 12
	s_add_i32 s0, s0, 9
	v_lshlrev_b64 v[66:67], 11, v[66:67]
	v_readlane_b32 s60, v251, 13
	v_readlane_b32 s61, v251, 14
	v_readlane_b32 s62, v251, 15
	v_readlane_b32 s63, v251, 16
	s_mov_b64 s[48:49], s[52:53]
	s_ashr_i32 s1, s0, 3
	v_or_b32_e32 v66, v66, v227
	s_mov_b64 s[50:51], s[54:55]
	s_lshl_b32 s1, s1, 2
	v_lshl_add_u64 v[68:69], s[48:49], 0, v[66:67]
	v_lshl_add_u64 v[66:67], s[50:51], 0, v[66:67]
	s_add_i32 s1, s2, s1
	global_load_dwordx4 v[106:109], v[66:67], off
	v_mov_b32_e32 v66, s1
	ds_read_b32 v66, v66
	s_lshl_b32 s0, s0, 4
	s_and_b32 s0, s0, 0x70
	global_load_dwordx4 v[118:121], v[68:69], off
	s_waitcnt vmcnt(16)
	v_pk_mul_f32 v[16:17], v[0:1], v[16:17]
	s_waitcnt lgkmcnt(0)
	v_lshlrev_b32_e32 v66, 7, v66
	v_or_b32_e32 v66, s0, v66
	s_min_i32 s0, s17, 37
	s_add_i32 s0, s0, 10
	s_ashr_i32 s1, s0, 3
	s_lshl_b32 s1, s1, 2
	s_add_i32 s1, s2, s1
	s_waitcnt vmcnt(7)
	v_mov_b32_e32 v70, s1
	ds_read_b32 v70, v70
	s_lshl_b32 s0, s0, 4
	s_and_b32 s0, s0, 0x70
	v_add_u32_e32 v66, v66, v186
	v_ashrrev_i32_e32 v67, 31, v66
	s_waitcnt lgkmcnt(0)
	v_lshlrev_b32_e32 v70, 7, v70
	v_or_b32_e32 v70, s0, v70
	s_min_i32 s0, s17, 36
	s_add_i32 s0, s0, 11
	s_ashr_i32 s1, s0, 3
	s_lshl_b32 s1, s1, 2
	s_add_i32 s1, s2, s1
	s_waitcnt vmcnt(6)
	v_mov_b32_e32 v74, s1
	ds_read_b32 v74, v74
	s_lshl_b32 s0, s0, 4
	s_and_b32 s0, s0, 0x70
	v_add_u32_e32 v70, v70, v186
	v_ashrrev_i32_e32 v71, 31, v70
	s_waitcnt lgkmcnt(0)
	v_lshlrev_b32_e32 v74, 7, v74
	v_or_b32_e32 v74, s0, v74
	s_min_i32 s0, s17, 35
	s_add_i32 s0, s0, 12
	s_ashr_i32 s1, s0, 3
	s_lshl_b32 s1, s1, 2
	s_add_i32 s1, s2, s1
	s_waitcnt vmcnt(5)
	v_mov_b32_e32 v82, s1
	ds_read_b32 v82, v82
	s_lshl_b32 s0, s0, 4
	s_and_b32 s0, s0, 0x70
	v_add_u32_e32 v74, v74, v186
	v_lshlrev_b64 v[70:71], 11, v[70:71]
	s_waitcnt lgkmcnt(0)
	v_lshlrev_b32_e32 v82, 7, v82
	v_or_b32_e32 v82, s0, v82
	s_min_i32 s0, s17, 34
	s_add_i32 s0, s0, 13
	s_ashr_i32 s1, s0, 3
	s_lshl_b32 s1, s1, 2
	s_add_i32 s1, s2, s1
	s_waitcnt vmcnt(4)
	v_mov_b32_e32 v90, s1
	ds_read_b32 v90, v90
	s_lshl_b32 s0, s0, 4
	s_and_b32 s0, s0, 0x70
	v_add_u32_e32 v82, v82, v186
	v_ashrrev_i32_e32 v75, 31, v74
	s_waitcnt lgkmcnt(0)
	v_lshlrev_b32_e32 v90, 7, v90
	v_or_b32_e32 v90, s0, v90
	s_min_i32 s0, s17, 33
	s_add_i32 s0, s0, 14
	s_ashr_i32 s1, s0, 3
	s_lshl_b32 s1, s1, 2
	s_add_i32 s1, s2, s1
	s_waitcnt vmcnt(3)
	v_mov_b32_e32 v98, s1
	ds_read_b32 v98, v98
	s_lshl_b32 s0, s0, 4
	s_and_b32 s0, s0, 0x70
	v_add_u32_e32 v90, v90, v186
	v_ashrrev_i32_e32 v83, 31, v82
	s_waitcnt lgkmcnt(0)
	v_lshlrev_b32_e32 v98, 7, v98
	v_or_b32_e32 v98, s0, v98
	s_min_i32 s0, s17, 32
	s_add_i32 s0, s0, 15
	s_ashr_i32 s1, s0, 3
	s_lshl_b32 s1, s1, 2
	s_add_i32 s1, s2, s1
	s_waitcnt vmcnt(2)
	v_mov_b32_e32 v130, s1
	ds_read_b32 v130, v130
	s_lshl_b32 s0, s0, 4
	s_and_b32 s0, s0, 0x70
	v_add_u32_e32 v98, v98, v186
	v_ashrrev_i32_e32 v91, 31, v90
	s_waitcnt lgkmcnt(0)
	v_lshlrev_b32_e32 v130, 7, v130
	v_or_b32_e32 v130, s0, v130
	v_add_u32_e32 v130, v130, v186
	v_ashrrev_i32_e32 v99, 31, v98
	v_ashrrev_i32_e32 v131, 31, v130
	v_lshlrev_b64 v[66:67], 11, v[66:67]
	v_or_b32_e32 v70, v70, v227
	v_lshlrev_b64 v[74:75], 11, v[74:75]
	v_lshlrev_b64 v[82:83], 11, v[82:83]
	v_lshlrev_b64 v[90:91], 11, v[90:91]
	v_lshlrev_b64 v[98:99], 11, v[98:99]
	v_lshlrev_b64 v[130:131], 11, v[130:131]
	v_or_b32_e32 v66, v66, v227
	v_lshl_add_u64 v[72:73], s[48:49], 0, v[70:71]
	v_or_b32_e32 v74, v74, v227
	v_or_b32_e32 v82, v82, v227
	v_or_b32_e32 v90, v90, v227
	v_or_b32_e32 v98, v98, v227
	v_or_b32_e32 v130, v130, v227
	global_load_dwordx4 v[78:81], v[72:73], off
	v_lshl_add_u64 v[68:69], s[48:49], 0, v[66:67]
	v_lshl_add_u64 v[66:67], s[50:51], 0, v[66:67]
	v_lshl_add_u64 v[70:71], s[50:51], 0, v[70:71]
	v_lshl_add_u64 v[76:77], s[48:49], 0, v[74:75]
	v_lshl_add_u64 v[74:75], s[50:51], 0, v[74:75]
	v_lshl_add_u64 v[84:85], s[48:49], 0, v[82:83]
	v_lshl_add_u64 v[82:83], s[50:51], 0, v[82:83]
	v_lshl_add_u64 v[92:93], s[48:49], 0, v[90:91]
	v_lshl_add_u64 v[90:91], s[50:51], 0, v[90:91]
	v_lshl_add_u64 v[100:101], s[48:49], 0, v[98:99]
	v_lshl_add_u64 v[98:99], s[50:51], 0, v[98:99]
	v_lshl_add_u64 v[132:133], s[48:49], 0, v[130:131]
	v_lshl_add_u64 v[130:131], s[50:51], 0, v[130:131]
	global_load_dwordx4 v[110:113], v[68:69], off
	global_load_dwordx4 v[86:89], v[76:77], off
	global_load_dwordx4 v[94:97], v[84:85], off
	global_load_dwordx4 v[102:105], v[92:93], off
	global_load_dwordx4 v[114:117], v[100:101], off
	global_load_dwordx4 v[134:137], v[132:133], off
	v_pk_mul_f32 v[18:19], v[2:3], v[18:19]
	global_load_dwordx4 v[66:69], v[66:67], off
	v_add_f32_e32 v16, v16, v17
	global_load_dwordx4 v[70:73], v[70:71], off
	v_add_f32_e32 v16, v18, v16
	global_load_dwordx4 v[74:77], v[74:75], off
	v_add_f32_e32 v16, v19, v16
	global_load_dwordx4 v[82:85], v[82:83], off
	global_load_dwordx4 v[90:93], v[90:91], off
	v_mov_b32_e32 v183, v188
	global_load_dwordx4 v[98:101], v[98:99], off
	v_mov_b32_e32 v32, v189
	global_load_dwordx4 v[130:133], v[130:131], off
	s_waitcnt lgkmcnt(0)
	s_nop 1
	v_add_f32_dpp v16, v16, v16 quad_perm:[1,0,3,2] row_mask:0xf bank_mask:0xf
	s_cmp_lt_i32 s17, 47
	s_mov_b64 s[52:53], s[56:57]
	s_mov_b64 s[54:55], s[58:59]
	s_mov_b64 s[56:57], s[60:61]
	s_waitcnt lgkmcnt(0)
	s_nop 1
	v_add_f32_dpp v16, v16, v16 quad_perm:[2,3,0,1] row_mask:0xf bank_mask:0xf
	s_mov_b64 s[58:59], s[62:63]
	s_waitcnt lgkmcnt(0)
	s_nop 1
	v_add_f32_dpp v16, v16, v16 row_half_mirror row_mask:0xf bank_mask:0xf
	s_waitcnt lgkmcnt(0)
	s_nop 1
	v_add_f32_dpp v16, v16, v16 row_mirror row_mask:0xf bank_mask:0xf
	ds_bpermute_b32 v17, v226, v16
	s_waitcnt lgkmcnt(0)
	v_add_f32_e32 v17, v16, v17
	v_max_f32_e32 v16, v183, v183
	v_max_f32_e32 v188, v16, v17
	v_sub_f32_e32 v17, v17, v188
	v_sub_f32_e32 v16, v183, v188
	v_exp_f32_e32 v18, v17
	v_exp_f32_e32 v16, v16
	v_pk_mul_f32 v[12:13], v[12:13], v[18:19] op_sel_hi:[1,0]
	s_nop 0
	v_pk_fma_f32 v[4:5], v[4:5], v[16:17], v[12:13] op_sel_hi:[1,0,1]
	s_waitcnt vmcnt(28)
	v_mul_f32_e32 v12, v1, v25
	v_fmac_f32_e32 v12, v0, v24
	v_fmac_f32_e32 v12, v2, v26
	v_fmac_f32_e32 v12, v3, v27
	v_mov_b32_e32 v189, v18
	v_pk_mul_f32 v[14:15], v[14:15], v[18:19] op_sel_hi:[1,0]
	v_fmac_f32_e32 v189, v32, v16
	v_pk_fma_f32 v[6:7], v[6:7], v[16:17], v[14:15] op_sel_hi:[1,0,1]
	s_waitcnt lgkmcnt(0)
	s_nop 1
	v_add_f32_dpp v12, v12, v12 quad_perm:[1,0,3,2] row_mask:0xf bank_mask:0xf
	s_waitcnt lgkmcnt(0)
	s_nop 1
	v_add_f32_dpp v12, v12, v12 quad_perm:[2,3,0,1] row_mask:0xf bank_mask:0xf
	s_waitcnt lgkmcnt(0)
	s_nop 1
	v_add_f32_dpp v12, v12, v12 row_half_mirror row_mask:0xf bank_mask:0xf
	s_waitcnt lgkmcnt(0)
	s_nop 1
	v_add_f32_dpp v12, v12, v12 row_mirror row_mask:0xf bank_mask:0xf
	ds_bpermute_b32 v13, v226, v12
	s_cbranch_scc0 .LBB0_998
	s_waitcnt lgkmcnt(0)
	v_add_f32_e32 v12, v12, v13
	v_max_f32_e32 v13, v188, v188
	v_max_f32_e32 v13, v13, v12
	v_sub_f32_e32 v12, v12, v13
	v_sub_f32_e32 v14, v188, v13
	v_exp_f32_e32 v12, v12
	v_exp_f32_e32 v14, v14
	v_mov_b32_e32 v188, v13
	v_mov_b32_e32 v15, v12
	v_fmac_f32_e32 v15, v189, v14
	s_waitcnt vmcnt(21)
	v_pk_mul_f32 v[8:9], v[8:9], v[12:13] op_sel_hi:[1,0]
	v_pk_mul_f32 v[10:11], v[10:11], v[12:13] op_sel_hi:[1,0]
	v_pk_fma_f32 v[4:5], v[4:5], v[14:15], v[8:9] op_sel_hi:[1,0,1]
	v_pk_fma_f32 v[6:7], v[6:7], v[14:15], v[10:11] op_sel_hi:[1,0,1]
	v_mov_b32_e32 v189, v15
.LBB0_998:
	s_waitcnt vmcnt(21)
	v_mul_f32_e32 v8, v1, v29
	v_fmac_f32_e32 v8, v0, v28
	v_fmac_f32_e32 v8, v2, v30
	v_fmac_f32_e32 v8, v3, v31
	s_cmp_gt_i32 s17, 45
	s_waitcnt lgkmcnt(0)
	s_nop 1
	v_add_f32_dpp v8, v8, v8 quad_perm:[1,0,3,2] row_mask:0xf bank_mask:0xf
	s_waitcnt lgkmcnt(0)
	s_nop 1
	v_add_f32_dpp v8, v8, v8 quad_perm:[2,3,0,1] row_mask:0xf bank_mask:0xf
	s_waitcnt lgkmcnt(0)
	s_nop 1
	v_add_f32_dpp v8, v8, v8 row_half_mirror row_mask:0xf bank_mask:0xf
	s_waitcnt lgkmcnt(0)
	s_nop 1
	v_add_f32_dpp v8, v8, v8 row_mirror row_mask:0xf bank_mask:0xf
	ds_bpermute_b32 v9, v226, v8
	s_cbranch_scc1 .LBB0_1000
	s_waitcnt lgkmcnt(0)
	v_add_f32_e32 v8, v8, v9
	v_max_f32_e32 v9, v188, v188
	v_max_f32_e32 v11, v9, v8
	v_sub_f32_e32 v8, v8, v11
	v_sub_f32_e32 v9, v188, v11
	v_exp_f32_e32 v8, v8
	v_exp_f32_e32 v10, v9
	v_mov_b32_e32 v188, v11
	v_mov_b32_e32 v14, v8
	v_fmac_f32_e32 v14, v189, v10
	s_waitcnt vmcnt(20)
	v_pk_mul_f32 v[12:13], v[20:21], v[8:9] op_sel_hi:[1,0]
	v_pk_mul_f32 v[8:9], v[22:23], v[8:9] op_sel_hi:[1,0]
	v_pk_fma_f32 v[4:5], v[4:5], v[10:11], v[12:13] op_sel_hi:[1,0,1]
	v_pk_fma_f32 v[6:7], v[6:7], v[10:11], v[8:9] op_sel_hi:[1,0,1]
	v_mov_b32_e32 v189, v14
.LBB0_1000:
	v_mul_f32_e32 v8, v1, v39
	v_fmac_f32_e32 v8, v0, v38
	v_fmac_f32_e32 v8, v2, v40
	v_fmac_f32_e32 v8, v3, v41
	s_waitcnt lgkmcnt(0)
	s_cmp_gt_i32 s17, 44
	s_waitcnt lgkmcnt(0)
	s_nop 1
	v_add_f32_dpp v8, v8, v8 quad_perm:[1,0,3,2] row_mask:0xf bank_mask:0xf
	s_waitcnt lgkmcnt(0)
	s_nop 1
	v_add_f32_dpp v8, v8, v8 quad_perm:[2,3,0,1] row_mask:0xf bank_mask:0xf
	s_waitcnt lgkmcnt(0)
	s_nop 1
	v_add_f32_dpp v8, v8, v8 row_half_mirror row_mask:0xf bank_mask:0xf
	s_waitcnt lgkmcnt(0)
	s_nop 1
	v_add_f32_dpp v8, v8, v8 row_mirror row_mask:0xf bank_mask:0xf
	ds_bpermute_b32 v9, v226, v8
	s_cbranch_scc1 .LBB0_1002
	s_waitcnt lgkmcnt(0)
	v_add_f32_e32 v8, v8, v9
	v_max_f32_e32 v9, v188, v188
	v_max_f32_e32 v11, v9, v8
	v_sub_f32_e32 v8, v8, v11
	v_sub_f32_e32 v9, v188, v11
	v_exp_f32_e32 v8, v8
	v_exp_f32_e32 v10, v9
	v_mov_b32_e32 v188, v11
	v_mov_b32_e32 v14, v8
	v_fmac_f32_e32 v14, v189, v10
	s_waitcnt vmcnt(19)
	v_pk_mul_f32 v[12:13], v[34:35], v[8:9] op_sel_hi:[1,0]
	v_pk_mul_f32 v[8:9], v[36:37], v[8:9] op_sel_hi:[1,0]
	v_pk_fma_f32 v[4:5], v[4:5], v[10:11], v[12:13] op_sel_hi:[1,0,1]
	v_pk_fma_f32 v[6:7], v[6:7], v[10:11], v[8:9] op_sel_hi:[1,0,1]
	v_mov_b32_e32 v189, v14

.LBB0_1057:
	v_readlane_b32 s2, v253, 2
	v_readlane_b32 s3, v253, 3
	v_cvt_f32_u32_e32 v0, v2
	v_sub_u32_e32 v4, 0, v2
	v_rcp_iflag_f32_e32 v0, v0
	s_nop 1
	global_atomic_add v3, v33, v215, s[2:3] sc0
	v_mul_f32_e32 v0, 0x4f7ffffe, v0
	v_cvt_u32_f32_e32 v0, v0
	v_mul_lo_u32 v4, v4, v0
	v_mul_hi_u32 v4, v0, v4
	v_add_u32_e32 v0, v0, v4
	s_waitcnt vmcnt(0)
	v_mul_hi_u32 v0, v3, v0
	v_mul_lo_u32 v4, v0, v2
	v_sub_u32_e32 v4, v3, v4
	v_add_u32_e32 v5, 1, v0
	v_cmp_ge_u32_e32 vcc, v4, v2
	v_add_u32_e32 v3, 1, v3
	s_nop 0
	v_cndmask_b32_e32 v0, v0, v5, vcc
	v_sub_u32_e32 v5, v4, v2
	v_cndmask_b32_e32 v4, v4, v5, vcc
	v_add_u32_e32 v5, 1, v0
	v_cmp_ge_u32_e32 vcc, v4, v2
	s_nop 1
	v_cndmask_b32_e32 v0, v0, v5, vcc
	v_mul_lo_u32 v4, v2, v0
	v_add_u32_e32 v2, v4, v2
	v_cmp_ne_u32_e32 vcc, v3, v2
	s_and_saveexec_b64 s[2:3], vcc
	s_xor_b64 s[4:5], exec, s[2:3]
	s_cbranch_execz .LBB0_1077
	v_readlane_b32 s2, v253, 4
	v_readlane_b32 s3, v253, 5
	s_nop 4
	global_load_dword v4, v33, s[2:3] sc1
	s_sleep 2
	s_waitcnt lgkmcnt(0)
	global_load_dword v1, v33, s[2:3] sc1
	s_sleep 2
	global_load_dword v2, v33, s[2:3] sc1
	s_sleep 2
	global_load_dword v3, v33, s[2:3] sc1
	s_waitcnt vmcnt(3)
	v_cmp_eq_u32_e32 vcc, v4, v0
	s_and_saveexec_b64 s[6:7], vcc
	s_cbranch_execz .LBB0_1076
	s_mov_b32 s8, 1
	s_mov_b64 s[2:3], 0
	s_branch .LBB0_1064

.LBB0_1064:
	v_readlane_b32 s12, v253, 4
	v_readlane_b32 s13, v253, 5
	s_waitcnt vmcnt(0)
	v_cmp_eq_u32_e32 vcc, v1, v0
	s_or_b64 s[38:39], s[38:39], exec
	s_or_b64 s[36:37], s[36:37], exec
	s_nop 0
	global_load_dword v4, v33, s[12:13] sc1
	s_sleep 2
	s_and_saveexec_b64 s[40:41], vcc
	s_cbranch_execz .LBB0_1063
	v_readlane_b32 s12, v253, 4
	v_readlane_b32 s13, v253, 5
	s_waitcnt vmcnt(2)
	v_cmp_eq_u32_e32 vcc, v2, v0
	s_mov_b64 s[28:29], -1
	s_mov_b64 s[30:31], -1
	s_nop 0
	global_load_dword v1, v33, s[12:13] sc1
	s_sleep 2
	s_and_saveexec_b64 s[42:43], vcc
	s_cbranch_execz .LBB0_1062
	v_readlane_b32 s12, v253, 4
	v_readlane_b32 s13, v253, 5
	s_waitcnt vmcnt(2)
	v_cmp_eq_u32_e32 vcc, v3, v0
	s_mov_b64 s[48:49], -1
	s_nop 1
	global_load_dword v2, v33, s[12:13] sc1
	s_sleep 2
	s_and_saveexec_b64 s[30:31], vcc
	s_cbranch_execz .LBB0_1061
	v_readlane_b32 s12, v253, 4
	v_readlane_b32 s13, v253, 5
	s_mov_b64 s[46:47], -1
	s_nop 3
	global_load_dword v3, v33, s[12:13] sc1
	s_and_b32 s12, s8, 63
	s_cmp_eq_u32 s12, 0
	s_sleep 2
	s_cbranch_scc1 .LBB0_1070
	s_and_b64 vcc, exec, s[28:29]
	s_cbranch_vccz .LBB0_1060

.LBB0_1080:
	s_or_b64 exec, exec, s[4:5]
	s_waitcnt vmcnt(0)
	v_readfirstlane_b32 s2, v2
	v_cvt_f32_u32_e32 v2, v1
	v_sub_u32_e32 v3, 0, v1
	v_add_u32_e32 v0, s2, v0
	v_readlane_b32 s4, v253, 8
	v_rcp_iflag_f32_e32 v2, v2
	v_readlane_b32 s5, v253, 9
	s_mov_b64 s[2:3], -1
	v_mul_f32_e32 v2, 0x4f7ffffe, v2
	v_cvt_u32_f32_e32 v2, v2
	v_mul_lo_u32 v3, v3, v2
	v_mul_hi_u32 v3, v2, v3
	v_add_u32_e32 v2, v2, v3
	v_mul_hi_u32 v2, v0, v2
	v_mul_lo_u32 v3, v2, v1
	v_sub_u32_e32 v3, v0, v3
	v_cmp_ge_u32_e32 vcc, v3, v1
	v_add_u32_e32 v4, 1, v2
	v_add_u32_e32 v0, 1, v0
	v_cndmask_b32_e32 v2, v2, v4, vcc
	v_sub_u32_e32 v4, v3, v1
	v_cndmask_b32_e32 v3, v3, v4, vcc
	v_cmp_ge_u32_e32 vcc, v3, v1
	v_add_u32_e32 v3, 1, v2
	s_nop 0
	v_cndmask_b32_e32 v2, v2, v3, vcc
	v_mul_lo_u32 v3, v1, v2
	v_add_u32_e32 v1, v3, v1
	v_cmp_ne_u32_e32 vcc, v0, v1
	v_mov_b64_e32 v[0:1], s[4:5]
	s_and_saveexec_b64 s[4:5], vcc
	s_cbranch_execz .LBB0_1098
	v_readlane_b32 s2, v253, 8
	v_readlane_b32 s3, v253, 9
	s_nop 4
	global_load_dword v4, v33, s[2:3] sc1
	s_sleep 2
	global_load_dword v0, v33, s[2:3] sc1
	s_sleep 2
	global_load_dword v1, v33, s[2:3] sc1
	s_sleep 2
	global_load_dword v3, v33, s[2:3] sc1
	s_mov_b64 s[2:3], 0
	s_waitcnt vmcnt(3)
	v_cmp_eq_u32_e32 vcc, v4, v2
	s_and_saveexec_b64 s[6:7], vcc
	s_cbranch_execz .LBB0_1097
	s_mov_b32 s8, 1
	s_branch .LBB0_1087

.LBB0_1087:
	v_readlane_b32 s12, v253, 8
	v_readlane_b32 s13, v253, 9
	s_waitcnt vmcnt(0)
	v_cmp_eq_u32_e32 vcc, v0, v2
	s_or_b64 s[38:39], s[38:39], exec
	s_or_b64 s[36:37], s[36:37], exec
	s_nop 0
	global_load_dword v4, v33, s[12:13] sc1
	s_sleep 2
	s_and_saveexec_b64 s[40:41], vcc
	s_cbranch_execz .LBB0_1086
	v_readlane_b32 s12, v253, 8
	v_readlane_b32 s13, v253, 9
	s_waitcnt vmcnt(2)
	v_cmp_eq_u32_e32 vcc, v1, v2
	s_mov_b64 s[28:29], -1
	s_mov_b64 s[30:31], -1
	s_nop 0
	global_load_dword v0, v33, s[12:13] sc1
	s_sleep 2
	s_and_saveexec_b64 s[42:43], vcc
	s_cbranch_execz .LBB0_1085
	v_readlane_b32 s12, v253, 8
	v_readlane_b32 s13, v253, 9
	s_waitcnt vmcnt(2)
	v_cmp_eq_u32_e32 vcc, v3, v2
	s_mov_b64 s[48:49], -1
	s_nop 1
	global_load_dword v1, v33, s[12:13] sc1
	s_sleep 2
	s_and_saveexec_b64 s[30:31], vcc
	s_cbranch_execz .LBB0_1084
	v_readlane_b32 s12, v253, 8
	v_readlane_b32 s13, v253, 9
	s_mov_b64 s[46:47], -1
	s_nop 3
	global_load_dword v3, v33, s[12:13] sc1
	s_and_b32 s12, s8, 63
	s_cmp_eq_u32 s12, 0
	s_sleep 2
	s_cbranch_scc1 .LBB0_1093
	s_and_b64 vcc, exec, s[28:29]
	s_cbranch_vccz .LBB0_1083

.LBB0_1209:
	v_readlane_b32 s12, v253, 4
	v_readlane_b32 s13, v253, 5
	s_waitcnt vmcnt(0)
	v_cmp_eq_u32_e32 vcc, v1, v0
	s_or_b64 s[38:39], s[38:39], exec
	s_or_b64 s[36:37], s[36:37], exec
	s_nop 0
	global_load_dword v4, v33, s[12:13] sc1
	s_sleep 2
	s_and_saveexec_b64 s[40:41], vcc
	s_cbranch_execz .LBB0_1208
	v_readlane_b32 s12, v253, 4
	v_readlane_b32 s13, v253, 5
	s_waitcnt vmcnt(2)
	v_cmp_eq_u32_e32 vcc, v2, v0
	s_mov_b64 s[28:29], -1
	s_mov_b64 s[30:31], -1
	s_nop 0
	global_load_dword v1, v33, s[12:13] sc1
	s_sleep 2
	s_and_saveexec_b64 s[42:43], vcc
	s_cbranch_execz .LBB0_1207
	v_readlane_b32 s12, v253, 4
	v_readlane_b32 s13, v253, 5
	s_waitcnt vmcnt(2)
	v_cmp_eq_u32_e32 vcc, v3, v0
	s_mov_b64 s[46:47], -1
	s_nop 1
	global_load_dword v2, v33, s[12:13] sc1
	s_sleep 2
	s_and_saveexec_b64 s[30:31], vcc
	s_cbranch_execz .LBB0_1206
	v_readlane_b32 s12, v253, 4
	v_readlane_b32 s13, v253, 5
	s_mov_b64 s[44:45], -1
	s_nop 3
	global_load_dword v3, v33, s[12:13] sc1
	s_and_b32 s12, s8, 63
	s_cmp_eq_u32 s12, 0
	s_sleep 2
	s_cbranch_scc1 .LBB0_1215
	s_and_b64 vcc, exec, s[28:29]
	s_cbranch_vccz .LBB0_1205

.LBB0_1217:
	s_cmp_lt_u32 s8, 0x40001
	s_mov_b64 s[46:47], 0
	s_cselect_b64 s[28:29], -1, 0
	s_and_b64 vcc, exec, s[28:29]
	s_cbranch_vccnz .LBB0_1214
	s_branch .LBB0_1205

.LBB0_1232:
	v_readlane_b32 s12, v253, 8
	v_readlane_b32 s13, v253, 9
	s_waitcnt vmcnt(0)
	v_cmp_eq_u32_e32 vcc, v0, v2
	s_or_b64 s[38:39], s[38:39], exec
	s_or_b64 s[36:37], s[36:37], exec
	s_nop 0
	global_load_dword v4, v33, s[12:13] sc1
	s_sleep 2
	s_and_saveexec_b64 s[40:41], vcc
	s_cbranch_execz .LBB0_1231
	v_readlane_b32 s12, v253, 8
	v_readlane_b32 s13, v253, 9
	s_waitcnt vmcnt(2)
	v_cmp_eq_u32_e32 vcc, v1, v2
	s_mov_b64 s[28:29], -1
	s_mov_b64 s[30:31], -1
	s_nop 0
	global_load_dword v0, v33, s[12:13] sc1
	s_sleep 2
	s_and_saveexec_b64 s[42:43], vcc
	s_cbranch_execz .LBB0_1230
	v_readlane_b32 s12, v253, 8
	v_readlane_b32 s13, v253, 9
	s_waitcnt vmcnt(2)
	v_cmp_eq_u32_e32 vcc, v3, v2
	s_mov_b64 s[46:47], -1
	s_nop 1
	global_load_dword v1, v33, s[12:13] sc1
	s_sleep 2
	s_and_saveexec_b64 s[30:31], vcc
	s_cbranch_execz .LBB0_1229
	v_readlane_b32 s12, v253, 8
	v_readlane_b32 s13, v253, 9
	s_mov_b64 s[44:45], -1
	s_nop 3
	global_load_dword v3, v33, s[12:13] sc1
	s_and_b32 s12, s8, 63
	s_cmp_eq_u32 s12, 0
	s_sleep 2
	s_cbranch_scc1 .LBB0_1238
	s_and_b64 vcc, exec, s[28:29]
	s_cbranch_vccz .LBB0_1228

.LBB0_1258:
	s_or_b64 exec, exec, s[38:39]
	s_waitcnt lgkmcnt(0)
	s_barrier
	ds_read_b32 v0, v44
	s_waitcnt vmcnt(1) lgkmcnt(0)
	v_add_f32_e32 v4, v18, v0
	v_add_u32_e32 v0, v16, v45
	v_ashrrev_i32_e32 v1, 31, v0
	v_lshl_add_u64 v[2:3], v[0:1], 2, s[46:47]
	v_lshl_add_u64 v[0:1], v[0:1], 1, s[48:49]
	global_store_dword v[2:3], v4, off
	v_cvt_pk_bf16_f32 v2, v4, v33
	global_store_short v[0:1], v2, off
	v_and_b32_e32 v0, 64, v216
	v_add_u32_e32 v6, 64, v0
	v_xor_b32_e32 v0, 1, v216
	v_cmp_lt_i32_e32 vcc, v0, v6
	v_mul_f32_e32 v1, v4, v4
	s_nop 0
	v_cndmask_b32_e32 v0, v216, v0, vcc
	v_lshlrev_b32_e32 v0, 2, v0
	ds_bpermute_b32 v2, v0, v1
	v_xor_b32_e32 v1, 2, v216
	v_cmp_lt_i32_e32 vcc, v1, v6
	s_waitcnt lgkmcnt(0)
	v_fmac_f32_e32 v2, v4, v4
	v_cndmask_b32_e32 v1, v216, v1, vcc
	v_lshlrev_b32_e32 v1, 2, v1
	s_waitcnt lgkmcnt(0)
	s_nop 1
	v_add_f32_dpp v3, v2, v2 quad_perm:[2,3,0,1] row_mask:0xf bank_mask:0xf
	v_xor_b32_e32 v2, 4, v216
	v_cmp_lt_i32_e32 vcc, v2, v6
	s_nop 1
	v_cndmask_b32_e32 v2, v216, v2, vcc
	v_lshlrev_b32_e32 v2, 2, v2
	s_waitcnt lgkmcnt(0)
	s_nop 1
	v_add_f32_dpp v4, v3, v3 row_half_mirror row_mask:0xf bank_mask:0xf
	v_xor_b32_e32 v3, 8, v216
	v_cmp_lt_i32_e32 vcc, v3, v6
	s_nop 1
	v_cndmask_b32_e32 v3, v216, v3, vcc
	v_lshlrev_b32_e32 v3, 2, v3
	s_waitcnt lgkmcnt(0)
	s_nop 1
	v_add_f32_dpp v5, v4, v4 row_mirror row_mask:0xf bank_mask:0xf
	v_xor_b32_e32 v4, 16, v216
	v_cmp_lt_i32_e32 vcc, v4, v6
	s_nop 1
	v_cndmask_b32_e32 v4, v216, v4, vcc
	v_lshlrev_b32_e32 v4, 2, v4
	ds_bpermute_b32 v6, v4, v5
	s_and_saveexec_b64 s[2:3], s[36:37]
	s_cbranch_execz .LBB0_1260
	s_waitcnt lgkmcnt(0)
	v_add_f32_e32 v5, v5, v6
	v_mul_f32_e32 v5, 0x4b800000, v5
	v_trunc_f32_e32 v5, v5
	v_mul_f32_e32 v6, 0x2f800000, v5
	v_floor_f32_e32 v7, v6
	v_fmac_f32_e32 v5, 0xcf800000, v7
	v_cvt_u32_f32_e32 v6, v5
	v_cvt_u32_f32_e32 v7, v7
	global_atomic_add_x2 v[46:47], v[6:7], off
.LBB0_1260:
	s_or_b64 exec, exec, s[2:3]
	v_add_u32_e32 v5, v42, v85
	ds_read_b32 v5, v5
	s_waitcnt lgkmcnt(1)
	v_add_u32_e32 v6, v16, v86
	v_ashrrev_i32_e32 v7, 31, v6
	v_lshl_add_u64 v[8:9], v[6:7], 2, s[46:47]
	v_lshl_add_u64 v[6:7], v[6:7], 1, s[48:49]
	s_waitcnt vmcnt(2) lgkmcnt(0)
	v_add_f32_e32 v5, v17, v5
	global_store_dword v[8:9], v5, off
	v_cvt_pk_bf16_f32 v8, v5, v33
	global_store_short v[6:7], v8, off
	v_mul_f32_e32 v6, v5, v5
	ds_bpermute_b32 v0, v0, v6
	s_waitcnt lgkmcnt(0)
	v_fmac_f32_e32 v0, v5, v5
	s_waitcnt lgkmcnt(0)
	s_nop 1
	v_add_f32_dpp v0, v0, v0 quad_perm:[2,3,0,1] row_mask:0xf bank_mask:0xf
	s_waitcnt lgkmcnt(0)
	s_nop 1
	v_add_f32_dpp v0, v0, v0 row_half_mirror row_mask:0xf bank_mask:0xf
	s_waitcnt lgkmcnt(0)
	s_nop 1
	v_add_f32_dpp v0, v0, v0 row_mirror row_mask:0xf bank_mask:0xf
	ds_bpermute_b32 v1, v4, v0
	s_and_saveexec_b64 s[2:3], s[36:37]
	s_cbranch_execz .LBB0_1254
	s_waitcnt lgkmcnt(0)
	v_add_f32_e32 v0, v0, v1
	v_mul_f32_e32 v0, 0x4b800000, v0
	v_trunc_f32_e32 v0, v0
	v_mul_f32_e32 v1, 0x2f800000, v0
	v_floor_f32_e32 v1, v1
	v_fmac_f32_e32 v0, 0xcf800000, v1
	v_cvt_u32_f32_e32 v0, v0
	v_cvt_u32_f32_e32 v1, v1
	global_atomic_add_x2 v[48:49], v[0:1], off
	s_branch .LBB0_1254

.LBB0_1341:
	s_or_b64 exec, exec, s[38:39]
	s_waitcnt lgkmcnt(0)
	s_barrier
	ds_read_b32 v0, v44
	s_waitcnt lgkmcnt(0)
	v_add_f32_e32 v4, v18, v0
	v_add_u32_e32 v0, v16, v45
	v_ashrrev_i32_e32 v1, 31, v0
	v_lshl_add_u64 v[2:3], v[0:1], 2, s[46:47]
	v_lshl_add_u64 v[0:1], v[0:1], 1, s[48:49]
	global_store_dword v[2:3], v4, off
	v_cvt_pk_bf16_f32 v2, v4, v33
	global_store_short v[0:1], v2, off
	v_and_b32_e32 v0, 64, v216
	v_add_u32_e32 v6, 64, v0
	v_xor_b32_e32 v0, 1, v216
	v_cmp_lt_i32_e32 vcc, v0, v6
	v_mul_f32_e32 v1, v4, v4
	s_nop 0
	v_cndmask_b32_e32 v0, v216, v0, vcc
	v_lshlrev_b32_e32 v0, 2, v0
	ds_bpermute_b32 v2, v0, v1
	v_xor_b32_e32 v1, 2, v216
	v_cmp_lt_i32_e32 vcc, v1, v6
	s_waitcnt lgkmcnt(0)
	v_fmac_f32_e32 v2, v4, v4
	v_cndmask_b32_e32 v1, v216, v1, vcc
	v_lshlrev_b32_e32 v1, 2, v1
	s_waitcnt lgkmcnt(0)
	s_nop 1
	v_add_f32_dpp v3, v2, v2 quad_perm:[2,3,0,1] row_mask:0xf bank_mask:0xf
	v_xor_b32_e32 v2, 4, v216
	v_cmp_lt_i32_e32 vcc, v2, v6
	s_nop 1
	v_cndmask_b32_e32 v2, v216, v2, vcc
	v_lshlrev_b32_e32 v2, 2, v2
	s_waitcnt lgkmcnt(0)
	s_nop 1
	v_add_f32_dpp v4, v3, v3 row_half_mirror row_mask:0xf bank_mask:0xf
	v_xor_b32_e32 v3, 8, v216
	v_cmp_lt_i32_e32 vcc, v3, v6
	s_nop 1
	v_cndmask_b32_e32 v3, v216, v3, vcc
	v_lshlrev_b32_e32 v3, 2, v3
	s_waitcnt lgkmcnt(0)
	s_nop 1
	v_add_f32_dpp v5, v4, v4 row_mirror row_mask:0xf bank_mask:0xf
	v_xor_b32_e32 v4, 16, v216
	v_cmp_lt_i32_e32 vcc, v4, v6
	s_nop 1
	v_cndmask_b32_e32 v4, v216, v4, vcc
	v_lshlrev_b32_e32 v4, 2, v4
	ds_bpermute_b32 v6, v4, v5
	s_and_saveexec_b64 s[2:3], s[36:37]
	s_cbranch_execz .LBB0_1343
	s_waitcnt lgkmcnt(0)
	v_add_f32_e32 v5, v5, v6
	v_mul_f32_e32 v5, 0x4b800000, v5
	v_trunc_f32_e32 v5, v5
	v_mul_f32_e32 v6, 0x2f800000, v5
	v_floor_f32_e32 v7, v6
	v_fmac_f32_e32 v5, 0xcf800000, v7
	v_cvt_u32_f32_e32 v6, v5
	v_cvt_u32_f32_e32 v7, v7
	global_atomic_add_x2 v[46:47], v[6:7], off
.LBB0_1343:
	s_or_b64 exec, exec, s[2:3]
	v_add_u32_e32 v5, v42, v85
	ds_read_b32 v5, v5
	s_waitcnt lgkmcnt(0)
	v_add_f32_e32 v5, v17, v5
	v_mul_f32_e32 v6, v5, v5
	ds_bpermute_b32 v0, v0, v6
	s_waitcnt lgkmcnt(0)
	v_fmac_f32_e32 v0, v5, v5
	s_waitcnt lgkmcnt(0)
	s_nop 1
	v_add_f32_dpp v0, v0, v0 quad_perm:[2,3,0,1] row_mask:0xf bank_mask:0xf
	v_add_u32_e32 v2, v16, v86
	s_waitcnt lgkmcnt(0)
	s_nop 1
	v_add_f32_dpp v0, v0, v0 row_half_mirror row_mask:0xf bank_mask:0xf
	v_ashrrev_i32_e32 v3, 31, v2
	v_lshl_add_u64 v[6:7], v[2:3], 2, s[46:47]
	v_lshl_add_u64 v[2:3], v[2:3], 1, s[48:49]
	global_store_dword v[6:7], v5, off
	s_waitcnt lgkmcnt(0)
	s_nop 1
	v_add_f32_dpp v0, v0, v0 row_mirror row_mask:0xf bank_mask:0xf
	ds_bpermute_b32 v1, v4, v0
	v_cvt_pk_bf16_f32 v4, v5, v33
	global_store_short v[2:3], v4, off
	s_and_saveexec_b64 s[2:3], s[36:37]
	s_cbranch_execz .LBB0_1337
	s_waitcnt lgkmcnt(0)
	v_add_f32_e32 v0, v0, v1
	v_mul_f32_e32 v0, 0x4b800000, v0
	v_trunc_f32_e32 v0, v0
	v_mul_f32_e32 v1, 0x2f800000, v0
	v_floor_f32_e32 v1, v1
	v_fmac_f32_e32 v0, 0xcf800000, v1
	v_cvt_u32_f32_e32 v0, v0
	v_cvt_u32_f32_e32 v1, v1
	global_atomic_add_x2 v[48:49], v[0:1], off
	s_branch .LBB0_1337

.LBB0_1789:
	v_readlane_b32 s0, v253, 2
	v_readlane_b32 s1, v253, 3
	v_cvt_f32_u32_e32 v0, v2
	v_sub_u32_e32 v4, 0, v2
	v_rcp_iflag_f32_e32 v0, v0
	s_nop 1
	global_atomic_add v3, v33, v215, s[0:1] sc0
	v_mul_f32_e32 v0, 0x4f7ffffe, v0
	v_cvt_u32_f32_e32 v0, v0
	v_mul_lo_u32 v4, v4, v0
	v_mul_hi_u32 v4, v0, v4
	v_add_u32_e32 v0, v0, v4
	s_waitcnt vmcnt(0)
	v_mul_hi_u32 v0, v3, v0
	v_mul_lo_u32 v4, v0, v2
	v_sub_u32_e32 v4, v3, v4
	v_add_u32_e32 v5, 1, v0
	v_cmp_ge_u32_e32 vcc, v4, v2
	v_add_u32_e32 v3, 1, v3
	s_nop 0
	v_cndmask_b32_e32 v0, v0, v5, vcc
	v_sub_u32_e32 v5, v4, v2
	v_cndmask_b32_e32 v4, v4, v5, vcc
	v_add_u32_e32 v5, 1, v0
	v_cmp_ge_u32_e32 vcc, v4, v2
	s_nop 1
	v_cndmask_b32_e32 v0, v0, v5, vcc
	v_mul_lo_u32 v4, v2, v0
	v_add_u32_e32 v2, v4, v2
	v_cmp_ne_u32_e32 vcc, v3, v2
	s_and_saveexec_b64 s[0:1], vcc
	s_xor_b64 s[0:1], exec, s[0:1]
	s_cbranch_execz .LBB0_1809
	v_readlane_b32 s2, v253, 4
	v_readlane_b32 s3, v253, 5
	s_nop 4
	global_load_dword v4, v33, s[2:3] sc1
	s_sleep 2
	s_waitcnt lgkmcnt(0)
	global_load_dword v1, v33, s[2:3] sc1
	s_sleep 2
	global_load_dword v2, v33, s[2:3] sc1
	s_sleep 2
	global_load_dword v3, v33, s[2:3] sc1
	s_waitcnt vmcnt(3)
	v_cmp_eq_u32_e32 vcc, v4, v0
	s_and_saveexec_b64 s[6:7], vcc
	s_cbranch_execz .LBB0_1808
	s_mov_b32 s11, 1
	s_mov_b64 s[2:3], 0
	s_branch .LBB0_1796

.LBB0_1812:
	s_or_b64 exec, exec, s[2:3]
	s_waitcnt vmcnt(0)
	v_readfirstlane_b32 s0, v2
	v_cvt_f32_u32_e32 v2, v1
	v_sub_u32_e32 v3, 0, v1
	v_add_u32_e32 v0, s0, v0
	v_readlane_b32 s0, v253, 8
	v_rcp_iflag_f32_e32 v2, v2
	v_readlane_b32 s1, v253, 9
	s_mov_b64 s[2:3], -1
	v_mul_f32_e32 v2, 0x4f7ffffe, v2
	v_cvt_u32_f32_e32 v2, v2
	v_mul_lo_u32 v3, v3, v2
	v_mul_hi_u32 v3, v2, v3
	v_add_u32_e32 v2, v2, v3
	v_mul_hi_u32 v2, v0, v2
	v_mul_lo_u32 v3, v2, v1
	v_sub_u32_e32 v3, v0, v3
	v_cmp_ge_u32_e32 vcc, v3, v1
	v_add_u32_e32 v4, 1, v2
	v_add_u32_e32 v0, 1, v0
	v_cndmask_b32_e32 v2, v2, v4, vcc
	v_sub_u32_e32 v4, v3, v1
	v_cndmask_b32_e32 v3, v3, v4, vcc
	v_cmp_ge_u32_e32 vcc, v3, v1
	v_add_u32_e32 v3, 1, v2
	s_nop 0
	v_cndmask_b32_e32 v2, v2, v3, vcc
	v_mul_lo_u32 v3, v1, v2
	v_add_u32_e32 v1, v3, v1
	v_cmp_ne_u32_e32 vcc, v0, v1
	v_mov_b64_e32 v[0:1], s[0:1]
	s_and_saveexec_b64 s[0:1], vcc
	s_cbranch_execz .LBB0_1830
	v_readlane_b32 s2, v253, 8
	v_readlane_b32 s3, v253, 9
	s_nop 4
	global_load_dword v4, v33, s[2:3] sc1
	s_sleep 2
	global_load_dword v0, v33, s[2:3] sc1
	s_sleep 2
	global_load_dword v1, v33, s[2:3] sc1
	s_sleep 2
	global_load_dword v3, v33, s[2:3] sc1
	s_mov_b64 s[2:3], 0
	s_waitcnt vmcnt(3)
	v_cmp_eq_u32_e32 vcc, v4, v2
	s_and_saveexec_b64 s[6:7], vcc
	s_cbranch_execz .LBB0_1829
	s_mov_b32 s11, 1
	s_branch .LBB0_1819

.LBB0_2004:
	v_readlane_b32 s0, v253, 2
	v_readlane_b32 s1, v253, 3
	v_cvt_f32_u32_e32 v0, v2
	v_sub_u32_e32 v4, 0, v2
	v_rcp_iflag_f32_e32 v0, v0
	s_nop 1
	global_atomic_add v3, v33, v215, s[0:1] sc0
	v_mul_f32_e32 v0, 0x4f7ffffe, v0
	v_cvt_u32_f32_e32 v0, v0
	v_mul_lo_u32 v4, v4, v0
	v_mul_hi_u32 v4, v0, v4
	v_add_u32_e32 v0, v0, v4
	s_waitcnt vmcnt(0)
	v_mul_hi_u32 v0, v3, v0
	v_mul_lo_u32 v4, v0, v2
	v_sub_u32_e32 v4, v3, v4
	v_add_u32_e32 v5, 1, v0
	v_cmp_ge_u32_e32 vcc, v4, v2
	v_add_u32_e32 v3, 1, v3
	s_nop 0
	v_cndmask_b32_e32 v0, v0, v5, vcc
	v_sub_u32_e32 v5, v4, v2
	v_cndmask_b32_e32 v4, v4, v5, vcc
	v_add_u32_e32 v5, 1, v0
	v_cmp_ge_u32_e32 vcc, v4, v2
	s_nop 1
	v_cndmask_b32_e32 v0, v0, v5, vcc
	v_mul_lo_u32 v4, v2, v0
	v_add_u32_e32 v2, v4, v2
	v_cmp_ne_u32_e32 vcc, v3, v2
	s_and_saveexec_b64 s[0:1], vcc
	s_xor_b64 s[0:1], exec, s[0:1]
	s_cbranch_execz .LBB0_2024
	v_readlane_b32 s2, v253, 4
	v_readlane_b32 s3, v253, 5
	s_nop 4
	global_load_dword v4, v33, s[2:3] sc1
	s_sleep 2
	s_waitcnt lgkmcnt(0)
	global_load_dword v1, v33, s[2:3] sc1
	s_sleep 2
	global_load_dword v2, v33, s[2:3] sc1
	s_sleep 2
	global_load_dword v3, v33, s[2:3] sc1
	s_waitcnt vmcnt(3)
	v_cmp_eq_u32_e32 vcc, v4, v0
	s_and_saveexec_b64 s[6:7], vcc
	s_cbranch_execz .LBB0_2023
	s_mov_b32 s8, 1
	s_mov_b64 s[2:3], 0
	s_branch .LBB0_2011

.LBB0_2011:
	v_readlane_b32 s12, v253, 4
	v_readlane_b32 s13, v253, 5
	s_waitcnt vmcnt(0)
	v_cmp_eq_u32_e32 vcc, v1, v0
	s_or_b64 s[38:39], s[38:39], exec
	s_or_b64 s[36:37], s[36:37], exec
	s_nop 0
	global_load_dword v4, v33, s[12:13] sc1
	s_sleep 2
	s_and_saveexec_b64 s[40:41], vcc
	s_cbranch_execz .LBB0_2010
	v_readlane_b32 s12, v253, 4
	v_readlane_b32 s13, v253, 5
	s_waitcnt vmcnt(2)
	v_cmp_eq_u32_e32 vcc, v2, v0
	s_mov_b64 s[28:29], -1
	s_mov_b64 s[30:31], -1
	s_nop 0
	global_load_dword v1, v33, s[12:13] sc1
	s_sleep 2
	s_and_saveexec_b64 s[42:43], vcc
	s_cbranch_execz .LBB0_2009
	v_readlane_b32 s12, v253, 4
	v_readlane_b32 s13, v253, 5
	s_waitcnt vmcnt(2)
	v_cmp_eq_u32_e32 vcc, v3, v0
	s_mov_b64 s[46:47], -1
	s_nop 1
	global_load_dword v2, v33, s[12:13] sc1
	s_sleep 2
	s_and_saveexec_b64 s[30:31], vcc
	s_cbranch_execz .LBB0_2008
	v_readlane_b32 s12, v253, 4
	v_readlane_b32 s13, v253, 5
	s_and_b32 s11, s8, 63
	s_mov_b64 s[44:45], -1
	s_cmp_eq_u32 s11, 0
	s_nop 1
	global_load_dword v3, v33, s[12:13] sc1
	s_sleep 2
	s_cbranch_scc1 .LBB0_2017
	s_and_b64 vcc, exec, s[28:29]
	s_cbranch_vccz .LBB0_2007

.LBB0_2027:
	s_or_b64 exec, exec, s[2:3]
	s_waitcnt vmcnt(0)
	v_readfirstlane_b32 s0, v2
	v_cvt_f32_u32_e32 v2, v1
	v_sub_u32_e32 v3, 0, v1
	v_add_u32_e32 v0, s0, v0
	v_readlane_b32 s0, v253, 8
	v_rcp_iflag_f32_e32 v2, v2
	v_readlane_b32 s1, v253, 9
	s_mov_b64 s[2:3], -1
	v_mul_f32_e32 v2, 0x4f7ffffe, v2
	v_cvt_u32_f32_e32 v2, v2
	v_mul_lo_u32 v3, v3, v2
	v_mul_hi_u32 v3, v2, v3
	v_add_u32_e32 v2, v2, v3
	v_mul_hi_u32 v2, v0, v2
	v_mul_lo_u32 v3, v2, v1
	v_sub_u32_e32 v3, v0, v3
	v_cmp_ge_u32_e32 vcc, v3, v1
	v_add_u32_e32 v4, 1, v2
	v_add_u32_e32 v0, 1, v0
	v_cndmask_b32_e32 v2, v2, v4, vcc
	v_sub_u32_e32 v4, v3, v1
	v_cndmask_b32_e32 v3, v3, v4, vcc
	v_cmp_ge_u32_e32 vcc, v3, v1
	v_add_u32_e32 v3, 1, v2
	s_nop 0
	v_cndmask_b32_e32 v2, v2, v3, vcc
	v_mul_lo_u32 v3, v1, v2
	v_add_u32_e32 v1, v3, v1
	v_cmp_ne_u32_e32 vcc, v0, v1
	v_mov_b64_e32 v[0:1], s[0:1]
	s_and_saveexec_b64 s[0:1], vcc
	s_cbranch_execz .LBB0_2045
	v_readlane_b32 s2, v253, 8
	v_readlane_b32 s3, v253, 9
	s_nop 4
	global_load_dword v4, v33, s[2:3] sc1
	s_sleep 2
	global_load_dword v0, v33, s[2:3] sc1
	s_sleep 2
	global_load_dword v1, v33, s[2:3] sc1
	s_sleep 2
	global_load_dword v3, v33, s[2:3] sc1
	s_mov_b64 s[2:3], 0
	s_waitcnt vmcnt(3)
	v_cmp_eq_u32_e32 vcc, v4, v2
	s_and_saveexec_b64 s[6:7], vcc
	s_cbranch_execz .LBB0_2044
	s_mov_b32 s8, 1
	s_branch .LBB0_2034

.LBB0_2034:
	v_readlane_b32 s12, v253, 8
	v_readlane_b32 s13, v253, 9
	s_waitcnt vmcnt(0)
	v_cmp_eq_u32_e32 vcc, v0, v2
	s_or_b64 s[38:39], s[38:39], exec
	s_or_b64 s[36:37], s[36:37], exec
	s_nop 0
	global_load_dword v4, v33, s[12:13] sc1
	s_sleep 2
	s_and_saveexec_b64 s[40:41], vcc
	s_cbranch_execz .LBB0_2033
	v_readlane_b32 s12, v253, 8
	v_readlane_b32 s13, v253, 9
	s_waitcnt vmcnt(2)
	v_cmp_eq_u32_e32 vcc, v1, v2
	s_mov_b64 s[28:29], -1
	s_mov_b64 s[30:31], -1
	s_nop 0
	global_load_dword v0, v33, s[12:13] sc1
	s_sleep 2
	s_and_saveexec_b64 s[42:43], vcc
	s_cbranch_execz .LBB0_2032
	v_readlane_b32 s12, v253, 8
	v_readlane_b32 s13, v253, 9
	s_waitcnt vmcnt(2)
	v_cmp_eq_u32_e32 vcc, v3, v2
	s_mov_b64 s[46:47], -1
	s_nop 1
	global_load_dword v1, v33, s[12:13] sc1
	s_sleep 2
	s_and_saveexec_b64 s[30:31], vcc
	s_cbranch_execz .LBB0_2031
	v_readlane_b32 s12, v253, 8
	v_readlane_b32 s13, v253, 9
	s_and_b32 s11, s8, 63
	s_mov_b64 s[44:45], -1
	s_cmp_eq_u32 s11, 0
	s_nop 1
	global_load_dword v3, v33, s[12:13] sc1
	s_sleep 2
	s_cbranch_scc1 .LBB0_2040
	s_and_b64 vcc, exec, s[28:29]
	s_cbranch_vccz .LBB0_2030

.LBB0_2059:
	s_or_b64 exec, exec, s[0:1]
	s_waitcnt lgkmcnt(0)
	s_barrier
	ds_read_b32 v0, v44
	s_waitcnt vmcnt(1) lgkmcnt(0)
	v_add_f32_e32 v4, v18, v0
	v_add_u32_e32 v0, v16, v45
	v_ashrrev_i32_e32 v1, 31, v0
	v_lshl_add_u64 v[2:3], v[0:1], 2, s[90:91]
	v_lshl_add_u64 v[0:1], v[0:1], 1, s[92:93]
	global_store_dword v[2:3], v4, off
	v_cvt_pk_bf16_f32 v2, v4, v33
	global_store_short v[0:1], v2, off
	v_and_b32_e32 v0, 64, v216
	v_add_u32_e32 v6, 64, v0
	v_xor_b32_e32 v0, 1, v216
	v_cmp_lt_i32_e32 vcc, v0, v6
	v_mul_f32_e32 v1, v4, v4
	s_nop 0
	v_cndmask_b32_e32 v0, v216, v0, vcc
	v_lshlrev_b32_e32 v0, 2, v0
	ds_bpermute_b32 v2, v0, v1
	v_xor_b32_e32 v1, 2, v216
	v_cmp_lt_i32_e32 vcc, v1, v6
	s_waitcnt lgkmcnt(0)
	v_fmac_f32_e32 v2, v4, v4
	v_cndmask_b32_e32 v1, v216, v1, vcc
	v_lshlrev_b32_e32 v1, 2, v1
	s_waitcnt lgkmcnt(0)
	s_nop 1
	v_add_f32_dpp v3, v2, v2 quad_perm:[2,3,0,1] row_mask:0xf bank_mask:0xf
	v_xor_b32_e32 v2, 4, v216
	v_cmp_lt_i32_e32 vcc, v2, v6
	s_nop 1
	v_cndmask_b32_e32 v2, v216, v2, vcc
	v_lshlrev_b32_e32 v2, 2, v2
	s_waitcnt lgkmcnt(0)
	s_nop 1
	v_add_f32_dpp v4, v3, v3 row_half_mirror row_mask:0xf bank_mask:0xf
	v_xor_b32_e32 v3, 8, v216
	v_cmp_lt_i32_e32 vcc, v3, v6
	s_nop 1
	v_cndmask_b32_e32 v3, v216, v3, vcc
	v_lshlrev_b32_e32 v3, 2, v3
	s_waitcnt lgkmcnt(0)
	s_nop 1
	v_add_f32_dpp v5, v4, v4 row_mirror row_mask:0xf bank_mask:0xf
	v_xor_b32_e32 v4, 16, v216
	v_cmp_lt_i32_e32 vcc, v4, v6
	s_nop 1
	v_cndmask_b32_e32 v4, v216, v4, vcc
	v_lshlrev_b32_e32 v4, 2, v4
	ds_bpermute_b32 v6, v4, v5
	s_and_saveexec_b64 s[0:1], s[96:97]
	s_cbranch_execz .LBB0_2061
	s_waitcnt lgkmcnt(0)
	v_add_f32_e32 v5, v5, v6
	v_mul_f32_e32 v5, 0x4b800000, v5
	v_trunc_f32_e32 v5, v5
	v_mul_f32_e32 v6, 0x2f800000, v5
	v_floor_f32_e32 v7, v6
	v_fmac_f32_e32 v5, 0xcf800000, v7
	v_cvt_u32_f32_e32 v6, v5
	v_cvt_u32_f32_e32 v7, v7
	global_atomic_add_x2 v[46:47], v[6:7], off
.LBB0_2061:
	s_or_b64 exec, exec, s[0:1]
	v_add_u32_e32 v5, v42, v85
	ds_read_b32 v5, v5
	s_waitcnt lgkmcnt(1)
	v_add_u32_e32 v6, v16, v86
	v_ashrrev_i32_e32 v7, 31, v6
	v_lshl_add_u64 v[8:9], v[6:7], 2, s[90:91]
	v_lshl_add_u64 v[6:7], v[6:7], 1, s[92:93]
	s_waitcnt vmcnt(2) lgkmcnt(0)
	v_add_f32_e32 v5, v17, v5
	global_store_dword v[8:9], v5, off
	v_cvt_pk_bf16_f32 v8, v5, v33
	global_store_short v[6:7], v8, off
	v_mul_f32_e32 v6, v5, v5
	ds_bpermute_b32 v0, v0, v6
	s_waitcnt lgkmcnt(0)
	v_fmac_f32_e32 v0, v5, v5
	s_waitcnt lgkmcnt(0)
	s_nop 1
	v_add_f32_dpp v0, v0, v0 quad_perm:[2,3,0,1] row_mask:0xf bank_mask:0xf
	s_waitcnt lgkmcnt(0)
	s_nop 1
	v_add_f32_dpp v0, v0, v0 row_half_mirror row_mask:0xf bank_mask:0xf
	s_waitcnt lgkmcnt(0)
	s_nop 1
	v_add_f32_dpp v0, v0, v0 row_mirror row_mask:0xf bank_mask:0xf
	ds_bpermute_b32 v1, v4, v0
	s_and_saveexec_b64 s[0:1], s[96:97]
	s_cbranch_execz .LBB0_2055
	s_waitcnt lgkmcnt(0)
	v_add_f32_e32 v0, v0, v1
	v_mul_f32_e32 v0, 0x4b800000, v0
	v_trunc_f32_e32 v0, v0
	v_mul_f32_e32 v1, 0x2f800000, v0
	v_floor_f32_e32 v1, v1
	v_fmac_f32_e32 v0, 0xcf800000, v1
	v_cvt_u32_f32_e32 v0, v0
	v_cvt_u32_f32_e32 v1, v1
	global_atomic_add_x2 v[48:49], v[0:1], off
	s_branch .LBB0_2055

.LBB0_2142:
	s_or_b64 exec, exec, s[0:1]
	s_waitcnt lgkmcnt(0)
	s_barrier
	ds_read_b32 v0, v44
	s_waitcnt lgkmcnt(0)
	v_add_f32_e32 v4, v18, v0
	v_add_u32_e32 v0, v16, v45
	v_ashrrev_i32_e32 v1, 31, v0
	v_lshl_add_u64 v[2:3], v[0:1], 2, s[90:91]
	v_lshl_add_u64 v[0:1], v[0:1], 1, s[92:93]
	global_store_dword v[2:3], v4, off
	v_cvt_pk_bf16_f32 v2, v4, v33
	global_store_short v[0:1], v2, off
	v_and_b32_e32 v0, 64, v216
	v_add_u32_e32 v6, 64, v0
	v_xor_b32_e32 v0, 1, v216
	v_cmp_lt_i32_e32 vcc, v0, v6
	v_mul_f32_e32 v1, v4, v4
	s_nop 0
	v_cndmask_b32_e32 v0, v216, v0, vcc
	v_lshlrev_b32_e32 v0, 2, v0
	ds_bpermute_b32 v2, v0, v1
	v_xor_b32_e32 v1, 2, v216
	v_cmp_lt_i32_e32 vcc, v1, v6
	s_waitcnt lgkmcnt(0)
	v_fmac_f32_e32 v2, v4, v4
	v_cndmask_b32_e32 v1, v216, v1, vcc
	v_lshlrev_b32_e32 v1, 2, v1
	s_waitcnt lgkmcnt(0)
	s_nop 1
	v_add_f32_dpp v3, v2, v2 quad_perm:[2,3,0,1] row_mask:0xf bank_mask:0xf
	v_xor_b32_e32 v2, 4, v216
	v_cmp_lt_i32_e32 vcc, v2, v6
	s_nop 1
	v_cndmask_b32_e32 v2, v216, v2, vcc
	v_lshlrev_b32_e32 v2, 2, v2
	s_waitcnt lgkmcnt(0)
	s_nop 1
	v_add_f32_dpp v4, v3, v3 row_half_mirror row_mask:0xf bank_mask:0xf
	v_xor_b32_e32 v3, 8, v216
	v_cmp_lt_i32_e32 vcc, v3, v6
	s_nop 1
	v_cndmask_b32_e32 v3, v216, v3, vcc
	v_lshlrev_b32_e32 v3, 2, v3
	s_waitcnt lgkmcnt(0)
	s_nop 1
	v_add_f32_dpp v5, v4, v4 row_mirror row_mask:0xf bank_mask:0xf
	v_xor_b32_e32 v4, 16, v216
	v_cmp_lt_i32_e32 vcc, v4, v6
	s_nop 1
	v_cndmask_b32_e32 v4, v216, v4, vcc
	v_lshlrev_b32_e32 v4, 2, v4
	ds_bpermute_b32 v6, v4, v5
	s_and_saveexec_b64 s[0:1], s[96:97]
	s_cbranch_execz .LBB0_2144
	s_waitcnt lgkmcnt(0)
	v_add_f32_e32 v5, v5, v6
	v_mul_f32_e32 v5, 0x4b800000, v5
	v_trunc_f32_e32 v5, v5
	v_mul_f32_e32 v6, 0x2f800000, v5
	v_floor_f32_e32 v7, v6
	v_fmac_f32_e32 v5, 0xcf800000, v7
	v_cvt_u32_f32_e32 v6, v5
	v_cvt_u32_f32_e32 v7, v7
	global_atomic_add_x2 v[46:47], v[6:7], off
.LBB0_2144:
	s_or_b64 exec, exec, s[0:1]
	v_add_u32_e32 v5, v42, v85
	ds_read_b32 v5, v5
	s_waitcnt lgkmcnt(0)
	v_add_f32_e32 v5, v17, v5
	v_mul_f32_e32 v6, v5, v5
	ds_bpermute_b32 v0, v0, v6
	s_waitcnt lgkmcnt(0)
	v_fmac_f32_e32 v0, v5, v5
	s_waitcnt lgkmcnt(0)
	s_nop 1
	v_add_f32_dpp v0, v0, v0 quad_perm:[2,3,0,1] row_mask:0xf bank_mask:0xf
	v_add_u32_e32 v2, v16, v86
	s_waitcnt lgkmcnt(0)
	s_nop 1
	v_add_f32_dpp v0, v0, v0 row_half_mirror row_mask:0xf bank_mask:0xf
	v_ashrrev_i32_e32 v3, 31, v2
	v_lshl_add_u64 v[6:7], v[2:3], 2, s[90:91]
	v_lshl_add_u64 v[2:3], v[2:3], 1, s[92:93]
	global_store_dword v[6:7], v5, off
	s_waitcnt lgkmcnt(0)
	s_nop 1
	v_add_f32_dpp v0, v0, v0 row_mirror row_mask:0xf bank_mask:0xf
	ds_bpermute_b32 v1, v4, v0
	v_cvt_pk_bf16_f32 v4, v5, v33
	global_store_short v[2:3], v4, off
	s_and_saveexec_b64 s[0:1], s[96:97]
	s_cbranch_execz .LBB0_2138
	s_waitcnt lgkmcnt(0)
	v_add_f32_e32 v0, v0, v1
	v_mul_f32_e32 v0, 0x4b800000, v0
	v_trunc_f32_e32 v0, v0
	v_mul_f32_e32 v1, 0x2f800000, v0
	v_floor_f32_e32 v1, v1
	v_fmac_f32_e32 v0, 0xcf800000, v1
	v_cvt_u32_f32_e32 v0, v0
	v_cvt_u32_f32_e32 v1, v1
	global_atomic_add_x2 v[48:49], v[0:1], off
	s_branch .LBB0_2138

.LBB0_2660:
	s_or_b64 exec, exec, s[38:39]
	s_waitcnt lgkmcnt(0)
	s_barrier
	ds_read_b32 v0, v205
	s_waitcnt vmcnt(1) lgkmcnt(0)
	v_add_f32_e32 v4, v26, v0
	v_add_u32_e32 v0, v24, v206
	v_ashrrev_i32_e32 v1, 31, v0
	v_lshl_add_u64 v[2:3], v[0:1], 2, s[92:93]
	v_lshl_add_u64 v[0:1], v[0:1], 1, s[56:57]
	global_store_dword v[2:3], v4, off
	v_cvt_pk_bf16_f32 v2, v4, v33
	global_store_short v[0:1], v2, off
	v_and_b32_e32 v0, 64, v216
	v_add_u32_e32 v6, 64, v0
	v_xor_b32_e32 v0, 1, v216
	v_cmp_lt_i32_e32 vcc, v0, v6
	v_mul_f32_e32 v1, v4, v4
	s_nop 0
	v_cndmask_b32_e32 v0, v216, v0, vcc
	v_lshlrev_b32_e32 v0, 2, v0
	ds_bpermute_b32 v2, v0, v1
	v_xor_b32_e32 v1, 2, v216
	v_cmp_lt_i32_e32 vcc, v1, v6
	s_waitcnt lgkmcnt(0)
	v_fmac_f32_e32 v2, v4, v4
	v_cndmask_b32_e32 v1, v216, v1, vcc
	v_lshlrev_b32_e32 v1, 2, v1
	s_waitcnt lgkmcnt(0)
	s_nop 1
	v_add_f32_dpp v3, v2, v2 quad_perm:[2,3,0,1] row_mask:0xf bank_mask:0xf
	v_xor_b32_e32 v2, 4, v216
	v_cmp_lt_i32_e32 vcc, v2, v6
	s_nop 1
	v_cndmask_b32_e32 v2, v216, v2, vcc
	v_lshlrev_b32_e32 v2, 2, v2
	s_waitcnt lgkmcnt(0)
	s_nop 1
	v_add_f32_dpp v4, v3, v3 row_half_mirror row_mask:0xf bank_mask:0xf
	v_xor_b32_e32 v3, 8, v216
	v_cmp_lt_i32_e32 vcc, v3, v6
	s_nop 1
	v_cndmask_b32_e32 v3, v216, v3, vcc
	v_lshlrev_b32_e32 v3, 2, v3
	s_waitcnt lgkmcnt(0)
	s_nop 1
	v_add_f32_dpp v5, v4, v4 row_mirror row_mask:0xf bank_mask:0xf
	v_xor_b32_e32 v4, 16, v216
	v_cmp_lt_i32_e32 vcc, v4, v6
	s_nop 1
	v_cndmask_b32_e32 v4, v216, v4, vcc
	v_lshlrev_b32_e32 v4, 2, v4
	ds_bpermute_b32 v6, v4, v5
	s_and_saveexec_b64 s[2:3], s[90:91]
	s_cbranch_execz .LBB0_2662
	s_waitcnt lgkmcnt(0)
	v_add_f32_e32 v5, v5, v6
	v_mul_f32_e32 v5, 0x4b800000, v5
	v_trunc_f32_e32 v5, v5
	v_mul_f32_e32 v6, 0x2f800000, v5
	v_floor_f32_e32 v7, v6
	v_fmac_f32_e32 v5, 0xcf800000, v7
	v_cvt_u32_f32_e32 v6, v5
	v_cvt_u32_f32_e32 v7, v7
	global_atomic_add_x2 v[166:167], v[6:7], off
.LBB0_2662:
	s_or_b64 exec, exec, s[2:3]
	v_add_u32_e32 v5, v70, v208
	ds_read_b32 v5, v5
	s_waitcnt lgkmcnt(1)
	v_add_u32_e32 v6, v24, v207
	v_ashrrev_i32_e32 v7, 31, v6
	v_lshl_add_u64 v[8:9], v[6:7], 2, s[92:93]
	v_lshl_add_u64 v[6:7], v[6:7], 1, s[56:57]
	s_waitcnt vmcnt(2) lgkmcnt(0)
	v_add_f32_e32 v5, v25, v5
	global_store_dword v[8:9], v5, off
	v_cvt_pk_bf16_f32 v8, v5, v33
	global_store_short v[6:7], v8, off
	v_mul_f32_e32 v6, v5, v5
	ds_bpermute_b32 v0, v0, v6
	s_waitcnt lgkmcnt(0)
	v_fmac_f32_e32 v0, v5, v5
	s_waitcnt lgkmcnt(0)
	s_nop 1
	v_add_f32_dpp v0, v0, v0 quad_perm:[2,3,0,1] row_mask:0xf bank_mask:0xf
	s_waitcnt lgkmcnt(0)
	s_nop 1
	v_add_f32_dpp v0, v0, v0 row_half_mirror row_mask:0xf bank_mask:0xf
	s_waitcnt lgkmcnt(0)
	s_nop 1
	v_add_f32_dpp v0, v0, v0 row_mirror row_mask:0xf bank_mask:0xf
	ds_bpermute_b32 v1, v4, v0
	s_and_saveexec_b64 s[2:3], s[90:91]
	s_cbranch_execz .LBB0_2656
	s_waitcnt lgkmcnt(0)
	v_add_f32_e32 v0, v0, v1
	v_mul_f32_e32 v0, 0x4b800000, v0
	v_trunc_f32_e32 v0, v0
	v_mul_f32_e32 v1, 0x2f800000, v0
	v_floor_f32_e32 v1, v1
	v_fmac_f32_e32 v0, 0xcf800000, v1
	v_cvt_u32_f32_e32 v0, v0
	v_cvt_u32_f32_e32 v1, v1
	global_atomic_add_x2 v[168:169], v[0:1], off
	s_branch .LBB0_2656

.LBB0_2760:
	s_or_b64 exec, exec, s[2:3]
	v_add_u32_e32 v5, v70, v208
	ds_read_b32 v5, v5
	s_waitcnt vmcnt(2) lgkmcnt(0)
	v_add_f32_e32 v5, v25, v5
	v_mul_f32_e32 v6, v5, v5
	ds_bpermute_b32 v0, v0, v6
	s_waitcnt lgkmcnt(0)
	v_fmac_f32_e32 v0, v5, v5
	s_waitcnt lgkmcnt(0)
	s_nop 1
	v_add_f32_dpp v0, v0, v0 quad_perm:[2,3,0,1] row_mask:0xf bank_mask:0xf
	v_add_u32_e32 v2, v24, v207
	s_waitcnt lgkmcnt(0)
	s_nop 1
	v_add_f32_dpp v0, v0, v0 row_half_mirror row_mask:0xf bank_mask:0xf
	v_ashrrev_i32_e32 v3, 31, v2
	v_lshl_add_u64 v[6:7], v[2:3], 2, s[92:93]
	v_lshl_add_u64 v[2:3], v[2:3], 1, s[56:57]
	global_store_dword v[6:7], v5, off
	s_waitcnt lgkmcnt(0)
	s_nop 1
	v_add_f32_dpp v0, v0, v0 row_mirror row_mask:0xf bank_mask:0xf
	ds_bpermute_b32 v1, v4, v0
	v_cvt_pk_bf16_f32 v4, v5, v33
	global_store_short v[2:3], v4, off
	s_and_saveexec_b64 s[2:3], s[90:91]
	s_cbranch_execz .LBB0_2754
	s_waitcnt lgkmcnt(0)
	v_add_f32_e32 v0, v0, v1
	v_mul_f32_e32 v0, 0x4b800000, v0
	v_trunc_f32_e32 v0, v0
	v_mul_f32_e32 v1, 0x2f800000, v0
	v_floor_f32_e32 v1, v1
	v_fmac_f32_e32 v0, 0xcf800000, v1
	v_cvt_u32_f32_e32 v0, v0
	v_cvt_u32_f32_e32 v1, v1
	global_atomic_add_x2 v[168:169], v[0:1], off
	s_branch .LBB0_2754

.LBB0_2888:
	s_or_b64 exec, exec, s[40:41]
	s_waitcnt lgkmcnt(0)
	s_barrier
	ds_read_b32 v1, v205
	v_and_b32_e32 v0, 64, v216
	v_add_u32_e32 v0, 64, v0
	v_xor_b32_e32 v2, 1, v216
	v_cmp_lt_i32_e32 vcc, v2, v0
	s_waitcnt vmcnt(1) lgkmcnt(0)
	v_add_f32_e32 v1, v28, v1
	v_mul_f32_e32 v3, v1, v1
	v_cndmask_b32_e32 v2, v216, v2, vcc
	v_lshlrev_b32_e32 v2, 2, v2
	ds_bpermute_b32 v5, v2, v3
	v_xor_b32_e32 v3, 2, v216
	v_cmp_lt_i32_e32 vcc, v3, v0
	v_xor_b32_e32 v4, 4, v216
	s_waitcnt lgkmcnt(0)
	v_fmac_f32_e32 v5, v1, v1
	v_cndmask_b32_e32 v3, v216, v3, vcc
	v_lshlrev_b32_e32 v3, 2, v3
	v_cmp_lt_i32_e32 vcc, v4, v0
	s_waitcnt lgkmcnt(0)
	s_nop 1
	v_add_f32_dpp v6, v5, v5 quad_perm:[2,3,0,1] row_mask:0xf bank_mask:0xf
	v_cndmask_b32_e32 v4, v216, v4, vcc
	v_lshlrev_b32_e32 v4, 2, v4
	v_xor_b32_e32 v5, 8, v216
	v_cmp_lt_i32_e32 vcc, v5, v0
	s_waitcnt lgkmcnt(0)
	s_nop 1
	v_add_f32_dpp v7, v6, v6 row_half_mirror row_mask:0xf bank_mask:0xf
	v_cndmask_b32_e32 v5, v216, v5, vcc
	v_lshlrev_b32_e32 v5, 2, v5
	v_xor_b32_e32 v6, 16, v216
	v_cmp_lt_i32_e32 vcc, v6, v0
	s_nop 1
	v_cndmask_b32_e32 v0, v216, v6, vcc
	v_lshlrev_b32_e32 v6, 2, v0
	s_waitcnt lgkmcnt(0)
	s_nop 1
	v_add_f32_dpp v0, v7, v7 row_mirror row_mask:0xf bank_mask:0xf
	ds_bpermute_b32 v7, v6, v0
	s_and_saveexec_b64 s[2:3], s[90:91]
	s_cbranch_execz .LBB0_2890
	s_waitcnt lgkmcnt(0)
	v_add_f32_e32 v0, v0, v7
	v_mul_f32_e32 v0, 0x4b800000, v0
	v_trunc_f32_e32 v0, v0
	v_mul_f32_e32 v7, 0x2f800000, v0
	v_floor_f32_e32 v7, v7
	v_fmac_f32_e32 v0, 0xcf800000, v7
	v_cvt_u32_f32_e32 v8, v0
	v_cvt_u32_f32_e32 v9, v7
	global_atomic_add_x2 v[166:167], v[8:9], off
.LBB0_2890:
	s_or_b64 exec, exec, s[2:3]
	ds_read_b32 v0, v27
	s_waitcnt vmcnt(0) lgkmcnt(0)
	v_add_f32_e32 v0, v25, v0
	v_mul_f32_e32 v7, v0, v0
	ds_bpermute_b32 v2, v2, v7
	s_waitcnt lgkmcnt(0)
	v_fmac_f32_e32 v2, v0, v0
	s_waitcnt lgkmcnt(0)
	s_nop 1
	v_add_f32_dpp v2, v2, v2 quad_perm:[2,3,0,1] row_mask:0xf bank_mask:0xf
	s_waitcnt lgkmcnt(0)
	s_nop 1
	v_add_f32_dpp v2, v2, v2 row_half_mirror row_mask:0xf bank_mask:0xf
	s_waitcnt lgkmcnt(0)
	s_nop 1
	v_add_f32_dpp v2, v2, v2 row_mirror row_mask:0xf bank_mask:0xf
	ds_bpermute_b32 v3, v6, v2
	s_and_saveexec_b64 s[2:3], s[90:91]
	s_cbranch_execz .LBB0_2892
	s_waitcnt lgkmcnt(0)
	v_add_f32_e32 v2, v2, v3
	v_mul_f32_e32 v2, 0x4b800000, v2
	v_trunc_f32_e32 v2, v2
	v_mul_f32_e32 v3, 0x2f800000, v2
	v_floor_f32_e32 v3, v3
	v_fmac_f32_e32 v2, 0xcf800000, v3
	v_cvt_u32_f32_e32 v2, v2
	v_cvt_u32_f32_e32 v3, v3
	global_atomic_add_x2 v[168:169], v[2:3], off

.LBB0_2915:
	s_or_b64 exec, exec, s[54:55]
	s_waitcnt lgkmcnt(0)
	s_barrier
	ds_read_b32 v0, v205
	v_ashrrev_i32_e32 v25, 31, v24
	s_waitcnt vmcnt(1) lgkmcnt(0)
	v_add_f32_e32 v1, v44, v0
	v_mul_f32_e32 v0, v1, v1
	ds_bpermute_b32 v0, v38, v0
	s_waitcnt lgkmcnt(0)
	v_fmac_f32_e32 v0, v1, v1
	s_waitcnt lgkmcnt(0)
	s_nop 1
	v_add_f32_dpp v0, v0, v0 quad_perm:[2,3,0,1] row_mask:0xf bank_mask:0xf
	s_waitcnt lgkmcnt(0)
	s_nop 1
	v_add_f32_dpp v0, v0, v0 row_half_mirror row_mask:0xf bank_mask:0xf
	s_waitcnt lgkmcnt(0)
	s_nop 1
	v_add_f32_dpp v0, v0, v0 row_mirror row_mask:0xf bank_mask:0xf
	ds_bpermute_b32 v2, v42, v0
	s_and_saveexec_b64 s[2:3], s[90:91]
	s_cbranch_execz .LBB0_2917
	s_waitcnt lgkmcnt(0)
	v_add_f32_e32 v0, v0, v2
	v_mul_f32_e32 v0, 0x4b800000, v0
	v_trunc_f32_e32 v0, v0
	v_mul_f32_e32 v2, 0x2f800000, v0
	v_floor_f32_e32 v3, v2
	v_fmac_f32_e32 v0, 0xcf800000, v3
	v_cvt_u32_f32_e32 v2, v0
	v_cvt_u32_f32_e32 v3, v3
	global_atomic_add_x2 v[166:167], v[2:3], off
.LBB0_2917:
	s_or_b64 exec, exec, s[2:3]
	ds_read_b32 v0, v27
	s_waitcnt vmcnt(0) lgkmcnt(0)
	v_add_f32_e32 v0, v43, v0
	v_mul_f32_e32 v2, v0, v0
	ds_bpermute_b32 v2, v38, v2
	s_waitcnt lgkmcnt(0)
	v_fmac_f32_e32 v2, v0, v0
	s_waitcnt lgkmcnt(0)
	s_nop 1
	v_add_f32_dpp v2, v2, v2 quad_perm:[2,3,0,1] row_mask:0xf bank_mask:0xf
	s_waitcnt lgkmcnt(0)
	s_nop 1
	v_add_f32_dpp v2, v2, v2 row_half_mirror row_mask:0xf bank_mask:0xf
	s_waitcnt lgkmcnt(0)
	s_nop 1
	v_add_f32_dpp v2, v2, v2 row_mirror row_mask:0xf bank_mask:0xf
	ds_bpermute_b32 v3, v42, v2
	s_and_saveexec_b64 s[2:3], s[90:91]
	s_cbranch_execz .LBB0_2919
	s_waitcnt lgkmcnt(0)
	v_add_f32_e32 v2, v2, v3
	v_mul_f32_e32 v2, 0x4b800000, v2
	v_trunc_f32_e32 v2, v2
	v_mul_f32_e32 v3, 0x2f800000, v2
	v_floor_f32_e32 v3, v3
	v_fmac_f32_e32 v2, 0xcf800000, v3
	v_cvt_u32_f32_e32 v2, v2
	v_cvt_u32_f32_e32 v3, v3
	global_atomic_add_x2 v[168:169], v[2:3], off

.LBB0_3076:
	v_readlane_b32 s2, v253, 2
	v_mov_b32_e32 v3, 0
	v_mov_b32_e32 v0, 1
	v_readlane_b32 s3, v253, 3
	v_sub_u32_e32 v5, 0, v2
	s_nop 3
	global_atomic_add v4, v3, v0, s[2:3] sc0
	v_cvt_f32_u32_e32 v0, v2
	v_rcp_iflag_f32_e32 v0, v0
	s_nop 0
	v_mul_f32_e32 v0, 0x4f7ffffe, v0
	v_cvt_u32_f32_e32 v0, v0
	v_mul_lo_u32 v5, v5, v0
	v_mul_hi_u32 v5, v0, v5
	v_add_u32_e32 v0, v0, v5
	s_waitcnt vmcnt(0)
	v_mul_hi_u32 v0, v4, v0
	v_mul_lo_u32 v5, v0, v2
	v_sub_u32_e32 v5, v4, v5
	v_add_u32_e32 v6, 1, v0
	v_cmp_ge_u32_e32 vcc, v5, v2
	v_add_u32_e32 v4, 1, v4
	s_nop 0
	v_cndmask_b32_e32 v0, v0, v6, vcc
	v_sub_u32_e32 v6, v5, v2
	v_cndmask_b32_e32 v5, v5, v6, vcc
	v_add_u32_e32 v6, 1, v0
	v_cmp_ge_u32_e32 vcc, v5, v2
	s_nop 1
	v_cndmask_b32_e32 v0, v0, v6, vcc
	v_mul_lo_u32 v5, v2, v0
	v_add_u32_e32 v2, v5, v2
	v_cmp_ne_u32_e32 vcc, v4, v2
	s_and_saveexec_b64 s[2:3], vcc
	s_xor_b64 s[2:3], exec, s[2:3]
	s_cbranch_execz .LBB0_3096
	v_readlane_b32 s4, v253, 4
	v_readlane_b32 s5, v253, 5
	s_nop 4
	global_load_dword v4, v3, s[4:5] sc1
	s_sleep 2
	s_waitcnt lgkmcnt(0)
	global_load_dword v1, v3, s[4:5] sc1
	s_sleep 2
	global_load_dword v2, v3, s[4:5] sc1
	s_sleep 2
	global_load_dword v3, v3, s[4:5] sc1
	s_waitcnt vmcnt(3)
	v_cmp_eq_u32_e32 vcc, v4, v0
	s_and_saveexec_b64 s[4:5], vcc
	s_cbranch_execz .LBB0_3095
	s_mov_b32 s26, 1
	s_mov_b64 s[6:7], 0
	v_mov_b32_e32 v4, 0
	s_branch .LBB0_3083

.LBB0_3083:
	v_readlane_b32 s14, v253, 4
	v_readlane_b32 s15, v253, 5
	s_waitcnt vmcnt(0)
	v_cmp_eq_u32_e32 vcc, v1, v0
	s_or_b64 s[12:13], s[12:13], exec
	s_or_b64 s[10:11], s[10:11], exec
	s_nop 0
	global_load_dword v5, v4, s[14:15] sc1
	s_sleep 2
	s_and_saveexec_b64 s[14:15], vcc
	s_cbranch_execz .LBB0_3082
	v_readlane_b32 s16, v253, 4
	v_readlane_b32 s17, v253, 5
	s_waitcnt vmcnt(2)
	v_cmp_eq_u32_e32 vcc, v2, v0
	s_mov_b64 s[18:19], -1
	s_mov_b64 s[20:21], -1
	s_nop 0
	global_load_dword v1, v4, s[16:17] sc1
	s_sleep 2
	s_and_saveexec_b64 s[16:17], vcc
	s_cbranch_execz .LBB0_3081
	v_readlane_b32 s18, v253, 4
	v_readlane_b32 s19, v253, 5
	s_waitcnt vmcnt(2)
	v_cmp_eq_u32_e32 vcc, v3, v0
	s_mov_b64 s[22:23], -1
	s_mov_b64 s[24:25], -1
	s_nop 0
	global_load_dword v2, v4, s[18:19] sc1
	s_sleep 2
	s_and_saveexec_b64 s[18:19], vcc
	s_cbranch_execz .LBB0_3080
	v_readlane_b32 s20, v253, 4
	v_readlane_b32 s21, v253, 5
	s_and_b32 s22, s26, 63
	s_cmp_eq_u32 s22, 0
	s_mov_b64 s[22:23], -1
	s_nop 1
	global_load_dword v3, v4, s[20:21] sc1
	s_mov_b64 s[20:21], -1
	s_sleep 2
	s_cbranch_scc0 .LBB0_3089
	v_readlane_b32 s22, v252, 0
	v_readlane_b32 s23, v252, 1
	s_nop 4
	global_load_dword v6, v4, s[22:23] sc1
	s_waitcnt vmcnt(0)
	v_cmp_eq_u32_e32 vcc, 0, v6
	s_cbranch_vccnz .LBB0_3091
	s_mov_b64 s[24:25], 0
	s_mov_b64 s[22:23], -1

.LBB0_3091:
	s_cmp_lt_u32 s26, 0x40001
	s_mov_b64 s[22:23], 0
	s_cselect_b64 s[24:25], -1, 0
	s_and_b64 vcc, exec, s[24:25]
	s_cbranch_vccnz .LBB0_3090
	s_branch .LBB0_3079

.LBB0_3099:
	s_or_b64 exec, exec, s[4:5]
	v_cvt_f32_u32_e32 v3, v1
	s_waitcnt vmcnt(0)
	v_readfirstlane_b32 s2, v2
	s_mov_b64 s[4:5], -1
	v_rcp_iflag_f32_e32 v3, v3
	v_add_u32_e32 v0, s2, v0
	v_add_u32_e32 v4, 1, v0
	v_mul_f32_e32 v2, 0x4f7ffffe, v3
	v_cvt_u32_f32_e32 v2, v2
	v_sub_u32_e32 v3, 0, v1
	v_mul_lo_u32 v3, v3, v2
	v_mul_hi_u32 v3, v2, v3
	v_add_u32_e32 v2, v2, v3
	v_mul_hi_u32 v2, v0, v2
	v_mul_lo_u32 v3, v2, v1
	v_sub_u32_e32 v0, v0, v3
	v_add_u32_e32 v5, 1, v2
	v_cmp_ge_u32_e32 vcc, v0, v1
	v_sub_u32_e32 v3, v0, v1
	s_nop 0
	v_cndmask_b32_e32 v2, v2, v5, vcc
	v_cndmask_b32_e32 v0, v0, v3, vcc
	v_add_u32_e32 v3, 1, v2
	v_cmp_ge_u32_e32 vcc, v0, v1
	s_nop 1
	v_cndmask_b32_e32 v2, v2, v3, vcc
	v_mul_lo_u32 v0, v1, v2
	v_add_u32_e32 v0, v0, v1
	v_cmp_ne_u32_e32 vcc, v4, v0
	v_mov_b64_e32 v[0:1], s[10:11]
	s_and_saveexec_b64 s[2:3], vcc
	s_cbranch_execz .LBB0_3117
	v_mov_b32_e32 v0, 0
	global_load_dword v5, v0, s[10:11] sc1
	s_sleep 2
	global_load_dword v1, v0, s[10:11] sc1
	s_sleep 2
	global_load_dword v3, v0, s[10:11] sc1
	s_sleep 2
	global_load_dword v4, v0, s[10:11] sc1
	s_mov_b64 s[6:7], 0
	s_waitcnt vmcnt(3)
	v_cmp_eq_u32_e32 vcc, v5, v2
	s_and_saveexec_b64 s[4:5], vcc
	s_cbranch_execz .LBB0_3116
	s_mov_b32 s26, 1
	s_branch .LBB0_3106

.LBB0_3106:
	v_readlane_b32 s14, v253, 8
	v_readlane_b32 s15, v253, 9
	s_waitcnt vmcnt(0)
	v_cmp_eq_u32_e32 vcc, v1, v2
	s_or_b64 s[12:13], s[12:13], exec
	s_or_b64 s[10:11], s[10:11], exec
	s_nop 0
	global_load_dword v5, v0, s[14:15] sc1
	s_sleep 2
	s_and_saveexec_b64 s[14:15], vcc
	s_cbranch_execz .LBB0_3105
	v_readlane_b32 s16, v253, 8
	v_readlane_b32 s17, v253, 9
	s_waitcnt vmcnt(2)
	v_cmp_eq_u32_e32 vcc, v3, v2
	s_mov_b64 s[18:19], -1
	s_mov_b64 s[20:21], -1
	s_nop 0
	global_load_dword v1, v0, s[16:17] sc1
	s_sleep 2
	s_and_saveexec_b64 s[16:17], vcc
	s_cbranch_execz .LBB0_3104
	v_readlane_b32 s18, v253, 8
	v_readlane_b32 s19, v253, 9
	s_waitcnt vmcnt(2)
	v_cmp_eq_u32_e32 vcc, v4, v2
	s_mov_b64 s[22:23], -1
	s_mov_b64 s[24:25], -1
	s_nop 0
	global_load_dword v3, v0, s[18:19] sc1
	s_sleep 2
	s_and_saveexec_b64 s[18:19], vcc
	s_cbranch_execz .LBB0_3103
	v_readlane_b32 s20, v253, 8
	v_readlane_b32 s21, v253, 9
	s_and_b32 s22, s26, 63
	s_cmp_eq_u32 s22, 0
	s_mov_b64 s[22:23], -1
	s_nop 1
	global_load_dword v4, v0, s[20:21] sc1
	s_mov_b64 s[20:21], -1
	s_sleep 2
	s_cbranch_scc0 .LBB0_3113
	v_readlane_b32 s22, v252, 0
	v_readlane_b32 s23, v252, 1
	s_nop 4
	global_load_dword v6, v0, s[22:23] sc1
	s_waitcnt vmcnt(0)
	v_cmp_eq_u32_e32 vcc, 0, v6
	s_cbranch_vccnz .LBB0_3112
	s_mov_b64 s[24:25], 0
	s_mov_b64 s[22:23], -1
	s_branch .LBB0_3113
.LBB0_3112:
	s_cmp_lt_u32 s26, 0x40001
	s_mov_b64 s[22:23], 0
	s_cselect_b64 s[24:25], -1, 0
